# attention: static s_setprio 1 for waves 4-7 around the tile loop; split-K ctx GEMM loop: setprio in front of barrier
# baseline (speedup 1.0000x reference)
; #define PG8_STAGE(bufoff, gbase, voff) do { _Pragma("unroll") for (int _i = 0; _i < 2; ++_i) \
;         __builtin_amdgcn_global_load_lds((const unsigned*)((const char*)(gbase) + (voff)[_i]), (PG8_LAS unsigned*)(lds + (bufoff) + ldsw + _i * 8192), 16, 0, 0); } while (0)
; #define PG8_LDA(dst, b, h) do { _Pragma("unroll") for (int m = 0; m < 4; ++m) _Pragma("unroll") for (int k = 0; k < 2; ++k) dst[m][k] = *(const PG8_LAS bf16x8*)(lds + PG8_SA(b, h) + aoff + m * 2048 + k * 1024); } while (0)
; #define PG8_LDB(dst, b, h) do { _Pragma("unroll") for (int n = 0; n < 2; ++n) _Pragma("unroll") for (int k = 0; k < 2; ++k) dst[n][k] = *(const PG8_LAS bf16x8*)(lds + PG8_SB(b, h) + boff + n * 2048 + k * 1024); } while (0)
; #define PG8_MMA(ai, bj, At, Bt) do { __builtin_amdgcn_s_setprio(1); _Pragma("unroll") for (int m = 0; m < 4; ++m) _Pragma("unroll") for (int n = 0; n < 2; ++n) _Pragma("unroll") for (int k = 0; k < 2; ++k) \
;         acc[ai][bj][m][n] = __builtin_amdgcn_mfma_f32_16x16x32_bf16(Bt[n][k], At[m][k], acc[ai][bj][m][n], 0, 0, 0); __builtin_amdgcn_s_setprio(0); } while (0)
; #define PG8_WAIT_V(n) asm volatile("s_waitcnt vmcnt(" #n ")" ::: "memory")
; #define PG8_WAIT_L(n) asm volatile("s_waitcnt lgkmcnt(" #n ")" ::: "memory")
; template <class Epi, class Sched, bool ALIGN_EPI = false, bool SP2 = false>
; __device__ __forceinline__ void gemm_phase(PG8_LAS unsigned char* lds, const Gemm g, const Sched& S, const Epi& E) {
;     ...
;             const bool last = (t == nt - 2);
;             const char* a1 = cA + (size_t)(t + 1) * kstep;
;             const char* a2 = last ? nA : cA + (size_t)(t + 2) * kstep; const char* b2 = last ? nB : cB + (size_t)(t + 2) * kstep;
;             const char* a3 = a2 + kstep; const char* b3 = b2 + kstep;
;             if (last && has_next) S.a_ready(nxt);
;             if constexpr (SP2) {
;             PG8_LDB(B0, 0, 0); PG8_LDB(B1, 0, 1); PG8_SCHED; PG8_LDA(At, 0, 0); PG8_STAGE(PG8_SA(1, 1), a1 + hstepA, voffA);
;             PG8_WAIT_V(8); PG8_WAIT_L(0); PG8_BAR; PG8_MMA(0, 0, At, B0); PG8_MMA(0, 1, At, B1); PG8_BAR; PG8_SCHED;
;             PG8_LDA(At, 0, 1); PG8_STAGE(PG8_SB(0, 0), b2, voffB); PG8_STAGE(PG8_SB(0, 1), b2 + hstep, voffB); PG8_STAGE(PG8_SA(0, 0), a2, voffA);
;             PG8_WAIT_V(8); PG8_WAIT_L(0); PG8_BAR; PG8_MMA(1, 0, At, B0); PG8_MMA(1, 1, At, B1); PG8_BAR; PG8_SCHED;
.LBB0_1098:
	ds_read_b128 v[148:151], v138
	ds_read_b128 v[152:155], v138 offset:1024
	ds_read_b128 v[156:159], v138 offset:2048
	ds_read_b128 v[160:163], v138 offset:3072
	ds_read_b128 v[164:167], v139
	ds_read_b128 v[168:171], v139 offset:1024
	ds_read_b128 v[172:175], v139 offset:2048
	ds_read_b128 v[176:179], v139 offset:3072
	s_add_i32 s65, s26, 2
	s_add_u32 s27, s24, 0xfff50080
	s_addc_u32 s28, s25, -1
	s_cmp_eq_u32 s30, s26
	s_cselect_b32 s26, s6, s63
	s_cselect_b32 s29, s23, s28
	s_cselect_b32 s28, s22, s27
	s_cselect_b32 s27, s7, s64
	v_lshl_add_u64 v[144:145], s[24:25], 0, v[136:137]
	s_add_i32 m0, s39, 0xc000
	ds_read_b128 v[180:183], v140
	ds_read_b128 v[184:187], v140 offset:1024
	ds_read_b128 v[190:193], v140 offset:2048
	ds_read_b128 v[194:197], v140 offset:3072
	ds_read_b128 v[198:201], v140 offset:4096
	ds_read_b128 v[202:205], v140 offset:5120
	ds_read_b128 v[206:209], v140 offset:6144
	ds_read_b128 v[210:213], v140 offset:7168
	global_load_lds_dwordx4 v[144:145], off
	v_lshl_add_u64 v[144:145], s[24:25], 0, v[132:133]
	s_add_i32 m0, s39, 0xe000
	s_nop 0
	global_load_lds_dwordx4 v[144:145], off
	s_waitcnt vmcnt(8) lgkmcnt(0)
	s_setprio 1
	s_barrier
	s_waitcnt lgkmcnt(0)
	v_mfma_f32_16x16x32_bf16 v[124:127], v[148:151], v[180:183], v[124:127]
	v_mfma_f32_16x16x32_bf16 v[120:123], v[156:159], v[180:183], v[120:123]
	v_mfma_f32_16x16x32_bf16 v[108:111], v[148:151], v[190:193], v[108:111]
	v_mfma_f32_16x16x32_bf16 v[104:107], v[156:159], v[190:193], v[104:107]
	v_mfma_f32_16x16x32_bf16 v[92:95], v[148:151], v[198:201], v[92:95]
	v_mfma_f32_16x16x32_bf16 v[88:91], v[156:159], v[198:201], v[88:91]
	v_mfma_f32_16x16x32_bf16 v[76:79], v[148:151], v[206:209], v[76:79]
	v_mfma_f32_16x16x32_bf16 v[72:75], v[156:159], v[206:209], v[72:75]
	v_mfma_f32_16x16x32_bf16 v[124:127], v[152:155], v[184:187], v[124:127]
	v_mfma_f32_16x16x32_bf16 v[120:123], v[160:163], v[184:187], v[120:123]
	v_mfma_f32_16x16x32_bf16 v[108:111], v[152:155], v[194:197], v[108:111]
	v_mfma_f32_16x16x32_bf16 v[104:107], v[160:163], v[194:197], v[104:107]
	v_mfma_f32_16x16x32_bf16 v[92:95], v[152:155], v[202:205], v[92:95]
	v_mfma_f32_16x16x32_bf16 v[88:91], v[160:163], v[202:205], v[88:91]
	v_mfma_f32_16x16x32_bf16 v[76:79], v[152:155], v[210:213], v[76:79]
	v_mfma_f32_16x16x32_bf16 v[72:75], v[160:163], v[210:213], v[72:75]
	s_setprio 0
	s_setprio 1
	v_mfma_f32_16x16x32_bf16 v[116:119], v[164:167], v[180:183], v[116:119]
	v_mfma_f32_16x16x32_bf16 v[112:115], v[172:175], v[180:183], v[112:115]
	v_mfma_f32_16x16x32_bf16 v[100:103], v[164:167], v[190:193], v[100:103]
	v_mfma_f32_16x16x32_bf16 v[96:99], v[172:175], v[190:193], v[96:99]
	v_mfma_f32_16x16x32_bf16 v[84:87], v[164:167], v[198:201], v[84:87]
	v_mfma_f32_16x16x32_bf16 v[80:83], v[172:175], v[198:201], v[80:83]
	v_mfma_f32_16x16x32_bf16 v[68:71], v[164:167], v[206:209], v[68:71]
	v_mfma_f32_16x16x32_bf16 v[64:67], v[172:175], v[206:209], v[64:67]
	v_mfma_f32_16x16x32_bf16 v[116:119], v[168:171], v[184:187], v[116:119]
	v_mfma_f32_16x16x32_bf16 v[112:115], v[176:179], v[184:187], v[112:115]
	v_mfma_f32_16x16x32_bf16 v[100:103], v[168:171], v[194:197], v[100:103]
	v_mfma_f32_16x16x32_bf16 v[96:99], v[176:179], v[194:197], v[96:99]
	v_mfma_f32_16x16x32_bf16 v[84:87], v[168:171], v[202:205], v[84:87]
	v_mfma_f32_16x16x32_bf16 v[80:83], v[176:179], v[202:205], v[80:83]
	v_mfma_f32_16x16x32_bf16 v[68:71], v[168:171], v[210:213], v[68:71]
	v_mfma_f32_16x16x32_bf16 v[64:67], v[176:179], v[210:213], v[64:67]
	s_setprio 0
	s_barrier
	s_add_i32 s66, s48, s38
	v_lshl_add_u64 v[144:145], s[26:27], 0, v[128:129]
	s_mov_b32 m0, s66
	ds_read_b128 v[180:183], v140 offset:16384
	ds_read_b128 v[184:187], v140 offset:17408
	ds_read_b128 v[190:193], v140 offset:18432
	ds_read_b128 v[194:197], v140 offset:19456
	ds_read_b128 v[198:201], v140 offset:20480
	ds_read_b128 v[202:205], v140 offset:21504
	ds_read_b128 v[206:209], v140 offset:22528
	ds_read_b128 v[210:213], v140 offset:23552
	global_load_lds_dwordx4 v[144:145], off
	s_add_i32 m0, s66, 0x2000
	s_add_u32 s66, s26, 0xb0000
	v_lshl_add_u64 v[214:215], s[26:27], 0, v[130:131]
	s_addc_u32 s67, s27, 0
	s_add_i32 s68, s49, s38
	global_load_lds_dwordx4 v[214:215], off
	v_lshl_add_u64 v[216:217], s[66:67], 0, v[128:129]
	s_mov_b32 m0, s68
	v_lshl_add_u64 v[218:219], s[28:29], 0, v[130:131]
	global_load_lds_dwordx4 v[216:217], off
	v_lshl_add_u64 v[216:217], s[66:67], 0, v[130:131]
	s_add_i32 m0, s68, 0x2000
	s_nop 0
	global_load_lds_dwordx4 v[216:217], off
	v_lshl_add_u64 v[216:217], s[28:29], 0, v[128:129]
	s_mov_b32 m0, s39
	s_nop 0
	global_load_lds_dwordx4 v[216:217], off
	s_mov_b32 m0, s40
	s_nop 0
	global_load_lds_dwordx4 v[218:219], off
	s_waitcnt vmcnt(8) lgkmcnt(0)
	s_setprio 1
	s_barrier
; #define PG8_STAGE(bufoff, gbase, voff) do { _Pragma("unroll") for (int _i = 0; _i < 2; ++_i) \
;         __builtin_amdgcn_global_load_lds((const unsigned*)((const char*)(gbase) + (voff)[_i]), (PG8_LAS unsigned*)(lds + (bufoff) + ldsw + _i * 8192), 16, 0, 0); } while (0)
; #define PG8_LDA(dst, b, h) do { _Pragma("unroll") for (int m = 0; m < 4; ++m) _Pragma("unroll") for (int k = 0; k < 2; ++k) dst[m][k] = *(const PG8_LAS bf16x8*)(lds + PG8_SA(b, h) + aoff + m * 2048 + k * 1024); } while (0)
; #define PG8_LDB(dst, b, h) do { _Pragma("unroll") for (int n = 0; n < 2; ++n) _Pragma("unroll") for (int k = 0; k < 2; ++k) dst[n][k] = *(const PG8_LAS bf16x8*)(lds + PG8_SB(b, h) + boff + n * 2048 + k * 1024); } while (0)
; #define PG8_MMA(ai, bj, At, Bt) do { __builtin_amdgcn_s_setprio(1); _Pragma("unroll") for (int m = 0; m < 4; ++m) _Pragma("unroll") for (int n = 0; n < 2; ++n) _Pragma("unroll") for (int k = 0; k < 2; ++k) \
;         acc[ai][bj][m][n] = __builtin_amdgcn_mfma_f32_16x16x32_bf16(Bt[n][k], At[m][k], acc[ai][bj][m][n], 0, 0, 0); __builtin_amdgcn_s_setprio(0); } while (0)
; #define PG8_WAIT_V(n) asm volatile("s_waitcnt vmcnt(" #n ")" ::: "memory")
; #define PG8_WAIT_L(n) asm volatile("s_waitcnt lgkmcnt(" #n ")" ::: "memory")
; #define PG8_BAR __builtin_amdgcn_s_barrier()
; #define PG8_SCHED __builtin_amdgcn_sched_barrier(0)
; template <class Epi, class Sched, bool ALIGN_EPI = false, bool SP2 = false>
; __device__ __forceinline__ void gemm_phase(PG8_LAS unsigned char* lds, const Gemm g, const Sched& S, const Epi& E) {
;     ...
;             PG8_WAIT_V(8); PG8_WAIT_L(0); PG8_BAR; PG8_MMA(1, 0, At, B0); PG8_MMA(1, 1, At, B1); PG8_BAR; PG8_SCHED;
;             PG8_LDB(B0, 1, 0); PG8_LDB(B1, 1, 1); PG8_SCHED; PG8_LDA(At, 1, 0); PG8_STAGE(PG8_SA(0, 1), a2 + hstepA, voffA);
;             PG8_WAIT_V(8); PG8_WAIT_L(0); PG8_BAR; PG8_MMA(0, 0, At, B0); PG8_MMA(0, 1, At, B1); PG8_BAR; PG8_SCHED;
	s_waitcnt lgkmcnt(0)
	v_mfma_f32_16x16x32_bf16 v[60:63], v[148:151], v[180:183], v[60:63]
	v_mfma_f32_16x16x32_bf16 v[56:59], v[156:159], v[180:183], v[56:59]
	v_mfma_f32_16x16x32_bf16 v[44:47], v[148:151], v[190:193], v[44:47]
	v_mfma_f32_16x16x32_bf16 v[40:43], v[156:159], v[190:193], v[40:43]
	v_mfma_f32_16x16x32_bf16 v[28:31], v[148:151], v[198:201], v[28:31]
	v_mfma_f32_16x16x32_bf16 v[24:27], v[156:159], v[198:201], v[24:27]
	v_mfma_f32_16x16x32_bf16 v[12:15], v[148:151], v[206:209], v[12:15]
	v_mfma_f32_16x16x32_bf16 v[8:11], v[156:159], v[206:209], v[8:11]
	v_mfma_f32_16x16x32_bf16 v[60:63], v[152:155], v[184:187], v[60:63]
	v_mfma_f32_16x16x32_bf16 v[56:59], v[160:163], v[184:187], v[56:59]
	v_mfma_f32_16x16x32_bf16 v[44:47], v[152:155], v[194:197], v[44:47]
	v_mfma_f32_16x16x32_bf16 v[40:43], v[160:163], v[194:197], v[40:43]
	v_mfma_f32_16x16x32_bf16 v[28:31], v[152:155], v[202:205], v[28:31]
	v_mfma_f32_16x16x32_bf16 v[24:27], v[160:163], v[202:205], v[24:27]
	v_mfma_f32_16x16x32_bf16 v[12:15], v[152:155], v[210:213], v[12:15]
	v_mfma_f32_16x16x32_bf16 v[8:11], v[160:163], v[210:213], v[8:11]
	s_setprio 0
	s_setprio 1
	v_mfma_f32_16x16x32_bf16 v[52:55], v[164:167], v[180:183], v[52:55]
	v_mfma_f32_16x16x32_bf16 v[48:51], v[172:175], v[180:183], v[48:51]
	v_mfma_f32_16x16x32_bf16 v[36:39], v[164:167], v[190:193], v[36:39]
	v_mfma_f32_16x16x32_bf16 v[32:35], v[172:175], v[190:193], v[32:35]
	v_mfma_f32_16x16x32_bf16 v[20:23], v[164:167], v[198:201], v[20:23]
	v_mfma_f32_16x16x32_bf16 v[16:19], v[172:175], v[198:201], v[16:19]
	v_mfma_f32_16x16x32_bf16 v[4:7], v[164:167], v[206:209], v[4:7]
	v_mfma_f32_16x16x32_bf16 v[0:3], v[172:175], v[206:209], v[0:3]
	v_mfma_f32_16x16x32_bf16 v[52:55], v[168:171], v[184:187], v[52:55]
	v_mfma_f32_16x16x32_bf16 v[48:51], v[176:179], v[184:187], v[48:51]
	v_mfma_f32_16x16x32_bf16 v[36:39], v[168:171], v[194:197], v[36:39]
	v_mfma_f32_16x16x32_bf16 v[32:35], v[176:179], v[194:197], v[32:35]
	v_mfma_f32_16x16x32_bf16 v[20:23], v[168:171], v[202:205], v[20:23]
	v_mfma_f32_16x16x32_bf16 v[16:19], v[176:179], v[202:205], v[16:19]
	v_mfma_f32_16x16x32_bf16 v[4:7], v[168:171], v[210:213], v[4:7]
	v_mfma_f32_16x16x32_bf16 v[0:3], v[176:179], v[210:213], v[0:3]
	s_setprio 0
	s_barrier
	s_add_i32 s66, 0, 0x18000
	v_add_u32_e32 v141, s66, v143
	s_add_i32 s67, 0, 0x1c000
	ds_read_b128 v[148:151], v141
	ds_read_b128 v[152:155], v141 offset:1024
	ds_read_b128 v[156:159], v141 offset:2048
	ds_read_b128 v[160:163], v141 offset:3072
	v_add_u32_e32 v141, s67, v143
	ds_read_b128 v[164:167], v141
	ds_read_b128 v[168:171], v141 offset:1024
	ds_read_b128 v[172:175], v141 offset:2048
	ds_read_b128 v[176:179], v141 offset:3072
	s_add_u32 s28, s28, 0xb0000
	s_addc_u32 s29, s29, 0
	s_mov_b32 m0, s41
	v_lshl_add_u64 v[220:221], s[28:29], 0, v[128:129]
	ds_read_b128 v[180:183], v140 offset:32768
	ds_read_b128 v[184:187], v140 offset:33792
	ds_read_b128 v[190:193], v140 offset:34816
	ds_read_b128 v[194:197], v140 offset:35840
	ds_read_b128 v[198:201], v140 offset:36864
	ds_read_b128 v[202:205], v140 offset:37888
	ds_read_b128 v[206:209], v140 offset:38912
	ds_read_b128 v[210:213], v140 offset:39936
	global_load_lds_dwordx4 v[220:221], off
	v_lshl_add_u64 v[220:221], s[28:29], 0, v[130:131]
	s_mov_b32 m0, s42
	s_nop 0
	global_load_lds_dwordx4 v[220:221], off
	s_waitcnt vmcnt(8) lgkmcnt(0)
	s_setprio 1
	s_barrier
	s_waitcnt lgkmcnt(0)
	v_mfma_f32_16x16x32_bf16 v[124:127], v[148:151], v[180:183], v[124:127]
	v_mfma_f32_16x16x32_bf16 v[120:123], v[156:159], v[180:183], v[120:123]
	v_mfma_f32_16x16x32_bf16 v[108:111], v[148:151], v[190:193], v[108:111]
	v_mfma_f32_16x16x32_bf16 v[104:107], v[156:159], v[190:193], v[104:107]
	v_mfma_f32_16x16x32_bf16 v[92:95], v[148:151], v[198:201], v[92:95]
	v_mfma_f32_16x16x32_bf16 v[88:91], v[156:159], v[198:201], v[88:91]
	v_mfma_f32_16x16x32_bf16 v[76:79], v[148:151], v[206:209], v[76:79]
	v_mfma_f32_16x16x32_bf16 v[72:75], v[156:159], v[206:209], v[72:75]
	v_mfma_f32_16x16x32_bf16 v[124:127], v[152:155], v[184:187], v[124:127]
	v_mfma_f32_16x16x32_bf16 v[120:123], v[160:163], v[184:187], v[120:123]
	v_mfma_f32_16x16x32_bf16 v[108:111], v[152:155], v[194:197], v[108:111]
	v_mfma_f32_16x16x32_bf16 v[104:107], v[160:163], v[194:197], v[104:107]
	v_mfma_f32_16x16x32_bf16 v[92:95], v[152:155], v[202:205], v[92:95]
	v_mfma_f32_16x16x32_bf16 v[88:91], v[160:163], v[202:205], v[88:91]
	v_mfma_f32_16x16x32_bf16 v[76:79], v[152:155], v[210:213], v[76:79]
	v_mfma_f32_16x16x32_bf16 v[72:75], v[160:163], v[210:213], v[72:75]
	s_setprio 0
	s_setprio 1
	v_mfma_f32_16x16x32_bf16 v[116:119], v[164:167], v[180:183], v[116:119]
	v_mfma_f32_16x16x32_bf16 v[112:115], v[172:175], v[180:183], v[112:115]
	v_mfma_f32_16x16x32_bf16 v[100:103], v[164:167], v[190:193], v[100:103]
	v_mfma_f32_16x16x32_bf16 v[96:99], v[172:175], v[190:193], v[96:99]
	v_mfma_f32_16x16x32_bf16 v[84:87], v[164:167], v[198:201], v[84:87]
	v_mfma_f32_16x16x32_bf16 v[80:83], v[172:175], v[198:201], v[80:83]
	v_mfma_f32_16x16x32_bf16 v[68:71], v[164:167], v[206:209], v[68:71]
	v_mfma_f32_16x16x32_bf16 v[64:67], v[172:175], v[206:209], v[64:67]
	v_mfma_f32_16x16x32_bf16 v[116:119], v[168:171], v[184:187], v[116:119]
	v_mfma_f32_16x16x32_bf16 v[112:115], v[176:179], v[184:187], v[112:115]
	v_mfma_f32_16x16x32_bf16 v[100:103], v[168:171], v[194:197], v[100:103]
	v_mfma_f32_16x16x32_bf16 v[96:99], v[176:179], v[194:197], v[96:99]
	v_mfma_f32_16x16x32_bf16 v[84:87], v[168:171], v[202:205], v[84:87]
	v_mfma_f32_16x16x32_bf16 v[80:83], v[176:179], v[202:205], v[80:83]
	v_mfma_f32_16x16x32_bf16 v[68:71], v[168:171], v[210:213], v[68:71]
	v_mfma_f32_16x16x32_bf16 v[64:67], v[176:179], v[210:213], v[64:67]
	s_setprio 0
	s_barrier
; #define PG8_STAGE(bufoff, gbase, voff) do { _Pragma("unroll") for (int _i = 0; _i < 2; ++_i) \
;         __builtin_amdgcn_global_load_lds((const unsigned*)((const char*)(gbase) + (voff)[_i]), (PG8_LAS unsigned*)(lds + (bufoff) + ldsw + _i * 8192), 16, 0, 0); } while (0)
; #define PG8_LDA(dst, b, h) do { _Pragma("unroll") for (int m = 0; m < 4; ++m) _Pragma("unroll") for (int k = 0; k < 2; ++k) dst[m][k] = *(const PG8_LAS bf16x8*)(lds + PG8_SA(b, h) + aoff + m * 2048 + k * 1024); } while (0)
; #define PG8_MMA(ai, bj, At, Bt) do { __builtin_amdgcn_s_setprio(1); _Pragma("unroll") for (int m = 0; m < 4; ++m) _Pragma("unroll") for (int n = 0; n < 2; ++n) _Pragma("unroll") for (int k = 0; k < 2; ++k) \
;         acc[ai][bj][m][n] = __builtin_amdgcn_mfma_f32_16x16x32_bf16(Bt[n][k], At[m][k], acc[ai][bj][m][n], 0, 0, 0); __builtin_amdgcn_s_setprio(0); } while (0)
; #define PG8_WAIT_V(n) asm volatile("s_waitcnt vmcnt(" #n ")" ::: "memory")
; #define PG8_WAIT_L(n) asm volatile("s_waitcnt lgkmcnt(" #n ")" ::: "memory")
; #define PG8_BAR __builtin_amdgcn_s_barrier()
; #define PG8_SCHED __builtin_amdgcn_sched_barrier(0)
; template <class Epi, class Sched, bool ALIGN_EPI = false, bool SP2 = false>
; __device__ __forceinline__ void gemm_phase(PG8_LAS unsigned char* lds, const Gemm g, const Sched& S, const Epi& E) {
;     ...
;             PG8_LDA(At, 1, 1); PG8_STAGE(PG8_SB(1, 0), b3, voffB); PG8_STAGE(PG8_SB(1, 1), b3 + hstep, voffB); PG8_STAGE(PG8_SA(1, 0), a3, voffA);
;             PG8_WAIT_V(8); PG8_WAIT_L(0); PG8_BAR; PG8_MMA(1, 0, At, B0); PG8_MMA(1, 1, At, B1); PG8_BAR; PG8_SCHED;
	s_add_i32 s28, s66, s38
	v_lshl_add_u64 v[144:145], v[144:145], 0, s[14:15]
	s_mov_b32 m0, s28
	ds_read_b128 v[180:183], v140 offset:49152
	ds_read_b128 v[184:187], v140 offset:50176
	ds_read_b128 v[190:193], v140 offset:51200
	ds_read_b128 v[194:197], v140 offset:52224
	ds_read_b128 v[198:201], v140 offset:53248
	ds_read_b128 v[202:205], v140 offset:54272
	ds_read_b128 v[206:209], v140 offset:55296
	ds_read_b128 v[210:213], v140 offset:56320
	global_load_lds_dwordx4 v[144:145], off
	s_add_i32 m0, s28, 0x2000
	s_add_u32 s26, s26, 0xb0080
	v_lshl_add_u64 v[144:145], v[214:215], 0, s[14:15]
	s_addc_u32 s27, s27, 0
	s_add_i32 s28, s67, s38
	global_load_lds_dwordx4 v[144:145], off
	v_lshl_add_u64 v[144:145], s[26:27], 0, v[128:129]
	s_mov_b32 m0, s28
	s_nop 0
	global_load_lds_dwordx4 v[144:145], off
	v_lshl_add_u64 v[144:145], s[26:27], 0, v[130:131]
	s_add_i32 m0, s28, 0x2000
	s_nop 0
	global_load_lds_dwordx4 v[144:145], off
	v_lshl_add_u64 v[144:145], v[216:217], 0, s[14:15]
	s_mov_b32 m0, s45
	s_nop 0
	global_load_lds_dwordx4 v[144:145], off
	v_lshl_add_u64 v[144:145], v[218:219], 0, s[14:15]
	s_mov_b32 m0, s47
	s_nop 0
	global_load_lds_dwordx4 v[144:145], off
	s_waitcnt vmcnt(8) lgkmcnt(0)
	s_setprio 1
	s_barrier
	s_waitcnt lgkmcnt(0)
	v_mfma_f32_16x16x32_bf16 v[60:63], v[148:151], v[180:183], v[60:63]
	v_mfma_f32_16x16x32_bf16 v[56:59], v[156:159], v[180:183], v[56:59]
	v_mfma_f32_16x16x32_bf16 v[44:47], v[148:151], v[190:193], v[44:47]
	v_mfma_f32_16x16x32_bf16 v[40:43], v[156:159], v[190:193], v[40:43]
	v_mfma_f32_16x16x32_bf16 v[28:31], v[148:151], v[198:201], v[28:31]
	v_mfma_f32_16x16x32_bf16 v[24:27], v[156:159], v[198:201], v[24:27]
	v_mfma_f32_16x16x32_bf16 v[12:15], v[148:151], v[206:209], v[12:15]
	v_mfma_f32_16x16x32_bf16 v[8:11], v[156:159], v[206:209], v[8:11]
	v_mfma_f32_16x16x32_bf16 v[60:63], v[152:155], v[184:187], v[60:63]
	v_mfma_f32_16x16x32_bf16 v[56:59], v[160:163], v[184:187], v[56:59]
	v_mfma_f32_16x16x32_bf16 v[44:47], v[152:155], v[194:197], v[44:47]
	v_mfma_f32_16x16x32_bf16 v[40:43], v[160:163], v[194:197], v[40:43]
	v_mfma_f32_16x16x32_bf16 v[28:31], v[152:155], v[202:205], v[28:31]
	v_mfma_f32_16x16x32_bf16 v[24:27], v[160:163], v[202:205], v[24:27]
	v_mfma_f32_16x16x32_bf16 v[12:15], v[152:155], v[210:213], v[12:15]
	v_mfma_f32_16x16x32_bf16 v[8:11], v[160:163], v[210:213], v[8:11]
	s_setprio 0
	s_setprio 1
	v_mfma_f32_16x16x32_bf16 v[52:55], v[164:167], v[180:183], v[52:55]
	v_mfma_f32_16x16x32_bf16 v[48:51], v[172:175], v[180:183], v[48:51]
	v_mfma_f32_16x16x32_bf16 v[36:39], v[164:167], v[190:193], v[36:39]
	v_mfma_f32_16x16x32_bf16 v[32:35], v[172:175], v[190:193], v[32:35]
	v_mfma_f32_16x16x32_bf16 v[20:23], v[164:167], v[198:201], v[20:23]
	v_mfma_f32_16x16x32_bf16 v[16:19], v[172:175], v[198:201], v[16:19]
	v_mfma_f32_16x16x32_bf16 v[4:7], v[164:167], v[206:209], v[4:7]
	v_mfma_f32_16x16x32_bf16 v[0:3], v[172:175], v[206:209], v[0:3]
	v_mfma_f32_16x16x32_bf16 v[52:55], v[168:171], v[184:187], v[52:55]
	v_mfma_f32_16x16x32_bf16 v[48:51], v[176:179], v[184:187], v[48:51]
	v_mfma_f32_16x16x32_bf16 v[36:39], v[168:171], v[194:197], v[36:39]
	v_mfma_f32_16x16x32_bf16 v[32:35], v[176:179], v[194:197], v[32:35]
	v_mfma_f32_16x16x32_bf16 v[20:23], v[168:171], v[202:205], v[20:23]
	v_mfma_f32_16x16x32_bf16 v[16:19], v[176:179], v[202:205], v[16:19]
	v_mfma_f32_16x16x32_bf16 v[4:7], v[168:171], v[210:213], v[4:7]
	v_mfma_f32_16x16x32_bf16 v[0:3], v[176:179], v[210:213], v[0:3]
	s_setprio 0
	s_barrier
	s_add_u32 s63, s63, 0x100
	s_addc_u32 s64, s64, 0
	s_add_u32 s24, s24, 0x100
	s_addc_u32 s25, s25, 0
	s_cmp_lt_i32 s65, s44
	s_mov_b32 s26, s65
	s_cbranch_scc1 .LBB0_1098

; template <bool SHIFT> __device__ __forceinline__ void attn_dense_body(const bf16* __restrict__ Qb, const bf16* __restrict__ Kh, const bf16* __restrict__ Vh, bf16* __restrict__ Ob, int seq, char* lds, LAS unsigned char* ldsl, float negB, const float* __restrict__ gq, int qpos0) {
;     ...
;   float l_reg = 0; f32x16 o[2] = {}; bf16x8 qr[7];
;     ...
;   f32x16 pA0, pA1, pB0, pB1; bf16x8 pa0, pa1, pa2, pa3; const int NT = seq / KVBLK;
;   DMA(0, 0); asm volatile("s_waitcnt vmcnt(0)" ::: "memory"); __syncthreads();
;   DMA(1, KVBLK);
;   qkt<SHIFT ? 7 : 6>(pA0, pA1, K_lds, qr, r32, hi); partialSM(pA0);
;   asm volatile("s_waitcnt vmcnt(0)" ::: "memory"); __syncthreads();
.LBB0_1594:
	s_or_b64 exec, exec, s[4:5]
	v_readfirstlane_b32 s60, v109
	s_add_u32 s56, s10, s50
	s_addc_u32 s57, s11, s51
	s_lshl_b32 s60, s60, 11
	s_add_u32 s56, s56, 0x12c00000
	s_addc_u32 s57, s57, 0
	s_add_u32 s58, s10, s52
	s_addc_u32 s59, s11, s53
	s_add_u32 s58, s58, 0x1bc00000
	s_addc_u32 s59, s59, 0
	v_add_u32_e32 v134, 0xc000, v115
	s_add_i32 m0, s60, 0x0
	s_nop 0
	global_load_lds_dwordx4 v124, s[56:57]
	global_load_lds_dwordx4 v126, s[56:57] offset:1024
	s_add_u32 s56, s56, 0x4000
	s_addc_u32 s57, s57, 0
	s_add_i32 m0, s60, 0x4000
	s_nop 0
	global_load_lds_dwordx4 v124, s[56:57]
	global_load_lds_dwordx4 v126, s[56:57] offset:1024
	s_add_u32 s56, s56, 0x4000
	s_addc_u32 s57, s57, 0
	s_add_i32 m0, s60, 0xc000
	s_nop 0
	global_load_lds_dwordx4 v128, s[58:59]
	s_add_u32 s58, s58, 0x2000
	s_addc_u32 s59, s59, 0
	s_add_i32 m0, s60, 0x8000
	s_nop 0
	global_load_lds_dwordx4 v124, s[56:57]
	global_load_lds_dwordx4 v126, s[56:57] offset:1024
	s_add_u32 s56, s56, 0x4000
	s_addc_u32 s57, s57, 0
	s_add_i32 m0, s60, 0x10000
	s_nop 0
	global_load_lds_dwordx4 v128, s[58:59]
	s_add_u32 s58, s58, 0x2000
	s_addc_u32 s59, s59, 0
	v_mov_b64_e32 v[0:1], 0
	v_mov_b64_e32 v[2:3], 0
	v_mov_b64_e32 v[4:5], 0
	v_mov_b64_e32 v[6:7], 0
	v_mov_b64_e32 v[8:9], 0
	v_mov_b64_e32 v[10:11], 0
	v_mov_b64_e32 v[12:13], 0
	v_mov_b64_e32 v[14:15], 0
	v_mov_b64_e32 v[16:17], 0
	v_mov_b64_e32 v[18:19], 0
	v_mov_b64_e32 v[20:21], 0
	v_mov_b64_e32 v[22:23], 0
	v_mov_b64_e32 v[24:25], 0
	v_mov_b64_e32 v[26:27], 0
	v_mov_b64_e32 v[28:29], 0
	v_mov_b64_e32 v[30:31], 0
	v_mov_b32_e32 v133, 0
	v_mov_b32_e32 v135, 0
	s_cmp_ge_u32 s60, 0x2000
	s_cbranch_scc0 .Latt_noprio
	s_setprio 1
.Latt_noprio:
	s_waitcnt vmcnt(6)
	s_barrier
	ds_read_b128 v[156:159], v146 offset:0
	ds_read_b128 v[160:163], v146 offset:8192
	ds_read_b128 v[164:167], v147 offset:0
	ds_read_b128 v[168:171], v147 offset:8192
	ds_read_b128 v[172:175], v148 offset:0
	ds_read_b128 v[176:179], v148 offset:8192
	ds_read_b128 v[180:183], v149 offset:0
	ds_read_b128 v[184:187], v149 offset:8192
	ds_read_b128 v[64:67], v150 offset:0
	ds_read_b128 v[68:71], v150 offset:8192
	ds_read_b128 v[72:75], v151 offset:0
	ds_read_b128 v[76:79], v151 offset:8192
	s_waitcnt lgkmcnt(0)
	v_mfma_f32_32x32x16_bf16 v[32:47], v[156:159], v[86:89], 0
	v_mfma_f32_32x32x16_bf16 v[48:63], v[160:163], v[86:89], 0
	v_mfma_f32_32x32x16_bf16 v[32:47], v[164:167], v[82:85], v[32:47]
	v_mfma_f32_32x32x16_bf16 v[48:63], v[168:171], v[82:85], v[48:63]
	v_mfma_f32_32x32x16_bf16 v[32:47], v[172:175], v[90:93], v[32:47]
	v_mfma_f32_32x32x16_bf16 v[48:63], v[176:179], v[90:93], v[48:63]
	v_mfma_f32_32x32x16_bf16 v[32:47], v[180:183], v[94:97], v[32:47]
	v_mfma_f32_32x32x16_bf16 v[48:63], v[184:187], v[94:97], v[48:63]
	v_mfma_f32_32x32x16_bf16 v[32:47], v[64:67], v[98:101], v[32:47]
	v_mfma_f32_32x32x16_bf16 v[48:63], v[68:71], v[98:101], v[48:63]
	v_mfma_f32_32x32x16_bf16 v[32:47], v[72:75], v[102:105], v[32:47]
	v_mfma_f32_32x32x16_bf16 v[48:63], v[76:79], v[102:105], v[48:63]
	s_waitcnt vmcnt(3) lgkmcnt(0)
	s_barrier
	ds_read_b128 v[156:159], v146 offset:16384
	ds_read_b128 v[160:163], v146 offset:24576
	ds_read_b128 v[164:167], v147 offset:16384
	ds_read_b128 v[168:171], v147 offset:24576
	ds_read_b128 v[172:175], v148 offset:16384
	ds_read_b128 v[176:179], v148 offset:24576
	ds_read_b128 v[180:183], v149 offset:16384
	ds_read_b128 v[184:187], v149 offset:24576
	ds_read_b128 v[64:67], v150 offset:16384
	ds_read_b128 v[68:71], v150 offset:24576
	ds_read_b128 v[72:75], v151 offset:16384
	ds_read_b128 v[76:79], v151 offset:24576
	v_exp_f32_e32 v32, v32
	v_exp_f32_e32 v33, v33
	v_exp_f32_e32 v34, v34
	v_exp_f32_e32 v35, v35
	v_exp_f32_e32 v36, v36
	v_exp_f32_e32 v37, v37
	v_exp_f32_e32 v38, v38
	v_exp_f32_e32 v39, v39
	v_exp_f32_e32 v40, v40
	v_exp_f32_e32 v41, v41
	v_exp_f32_e32 v42, v42
	v_exp_f32_e32 v43, v43
	v_exp_f32_e32 v44, v44
	v_exp_f32_e32 v45, v45
	v_exp_f32_e32 v46, v46
	v_exp_f32_e32 v47, v47
	s_add_i32 m0, s60, 0x0
	s_nop 0
	global_load_lds_dwordx4 v124, s[56:57]
	global_load_lds_dwordx4 v126, s[56:57] offset:1024
	s_add_u32 s56, s56, 0x4000
	s_addc_u32 s57, s57, 0
	s_add_i32 m0, s60, 0x14000
	s_nop 0
	global_load_lds_dwordx4 v128, s[58:59]
	s_add_u32 s58, s58, 0x2000
	s_addc_u32 s59, s59, 0
	s_mov_b32 s33, 10
; #define SBAR() __builtin_amdgcn_sched_barrier(0)
; #define ROT() do { const int t_ = bv; bv = bk; bk = bw; bw = t_; } while (0)
; __device__ __forceinline__ void finishSM(f32x16& p0, f32x16& p1, float& l_reg, bf16x8& pa0, bf16x8& pa1, bf16x8& pa2, bf16x8& pa3) {
; #pragma unroll
;   for (int r = 0; r < 16; ++r) p1[r] = __builtin_amdgcn_exp2f(p1[r]);
;   float ps = 0;
; #pragma unroll
;   for (int r = 0; r < 16; ++r) ps += p0[r];
; #pragma unroll
;   for (int r = 0; r < 16; ++r) ps += p1[r];
;   l_reg += ps;
; template <bool SHIFT> __device__ __forceinline__ void attn_dense_body(const bf16* __restrict__ Qb, const bf16* __restrict__ Kh, const bf16* __restrict__ Vh, bf16* __restrict__ Ob, int seq, char* lds, LAS unsigned char* ldsl, float negB, const float* __restrict__ gq, int qpos0) {
;     ...
;   for (int j = 1; j + 1 < NT; j += 2) {
;     DMA(bw, (j + 1) * KVBLK);
;     SBAR(); qkt<SHIFT ? 7 : 6>(pB0, pB1, (bf16*)((char*)K_lds + bk * SHM_K), qr, r32, hi);
;     finishSM(pA0, pA1, l_reg, pa0, pa1, pa2, pa3); SBAR();
;     pv_d0(o, vb0 + bv * (int)SHM_V, pa0, pa1, pa2, pa3); partialSM(pB0);
;     asm volatile("s_waitcnt vmcnt(0)" ::: "memory"); __syncthreads(); ROT();
.Latt_loop:
	s_waitcnt lgkmcnt(0)
	ds_read_b64_tr_b16 v[222:223], v134 offset:0
	ds_read_b64_tr_b16 v[224:225], v134 offset:2048
	ds_read_b64_tr_b16 v[226:227], v134 offset:4096
	ds_read_b64_tr_b16 v[228:229], v134 offset:6144
	ds_read_b64_tr_b16 v[230:231], v134 offset:8192
	ds_read_b64_tr_b16 v[232:233], v134 offset:10240
	ds_read_b64_tr_b16 v[234:235], v134 offset:12288
	ds_read_b64_tr_b16 v[236:237], v134 offset:14336
	ds_read_b64_tr_b16 v[238:239], v134 offset:512
	ds_read_b64_tr_b16 v[240:241], v134 offset:2560
	ds_read_b64_tr_b16 v[242:243], v134 offset:4608
	ds_read_b64_tr_b16 v[244:245], v134 offset:6656
	ds_read_b64_tr_b16 v[246:247], v134 offset:8704
	ds_read_b64_tr_b16 v[248:249], v134 offset:10752
	ds_read_b64_tr_b16 v[140:141], v134 offset:12800
	ds_read_b64_tr_b16 v[142:143], v134 offset:14848
	v_mfma_f32_32x32x16_bf16 v[190:205], v[156:159], v[86:89], 0
	v_exp_f32_e32 v48, v48
	v_add_f32_e32 v133, v133, v32
	v_exp_f32_e32 v49, v49
	v_add_f32_e32 v135, v135, v33
	v_exp_f32_e32 v50, v50
	v_mfma_f32_32x32x16_bf16 v[206:221], v[160:163], v[86:89], 0
	v_add_f32_e32 v133, v133, v34
	v_exp_f32_e32 v51, v51
	v_add_f32_e32 v135, v135, v35
	v_exp_f32_e32 v52, v52
	v_add_f32_e32 v133, v133, v36
	v_mfma_f32_32x32x16_bf16 v[190:205], v[164:167], v[82:85], v[190:205]
	v_exp_f32_e32 v53, v53
	v_add_f32_e32 v135, v135, v37
	v_exp_f32_e32 v54, v54
	v_add_f32_e32 v133, v133, v38
	v_exp_f32_e32 v55, v55
	v_add_f32_e32 v135, v135, v39
	v_mfma_f32_32x32x16_bf16 v[206:221], v[168:171], v[82:85], v[206:221]
	v_exp_f32_e32 v56, v56
	v_add_f32_e32 v133, v133, v40
	v_exp_f32_e32 v57, v57
	v_add_f32_e32 v135, v135, v41
	v_exp_f32_e32 v58, v58
	v_mfma_f32_32x32x16_bf16 v[190:205], v[172:175], v[90:93], v[190:205]
	v_add_f32_e32 v133, v133, v42
	v_exp_f32_e32 v59, v59
	v_add_f32_e32 v135, v135, v43
	v_exp_f32_e32 v60, v60
	v_add_f32_e32 v133, v133, v44
	v_mfma_f32_32x32x16_bf16 v[206:221], v[176:179], v[90:93], v[206:221]
	v_exp_f32_e32 v61, v61
	v_add_f32_e32 v135, v135, v45
	v_exp_f32_e32 v62, v62
	v_add_f32_e32 v133, v133, v46
	v_exp_f32_e32 v63, v63
	v_add_f32_e32 v135, v135, v47
	v_mfma_f32_32x32x16_bf16 v[190:205], v[180:183], v[94:97], v[190:205]
	v_add_f32_e32 v133, v133, v48
	v_add_f32_e32 v135, v135, v49
	v_add_f32_e32 v133, v133, v50
	v_add_f32_e32 v135, v135, v51
	v_add_f32_e32 v133, v133, v52
	v_mfma_f32_32x32x16_bf16 v[206:221], v[184:187], v[94:97], v[206:221]
	v_add_f32_e32 v135, v135, v53
	v_add_f32_e32 v133, v133, v54
	v_add_f32_e32 v135, v135, v55
	v_add_f32_e32 v133, v133, v56
	v_add_f32_e32 v135, v135, v57
	v_mfma_f32_32x32x16_bf16 v[190:205], v[64:67], v[98:101], v[190:205]
	v_add_f32_e32 v133, v133, v58
	v_add_f32_e32 v135, v135, v59
	v_add_f32_e32 v133, v133, v60
	v_add_f32_e32 v135, v135, v61
	v_add_f32_e32 v133, v133, v62
	v_add_f32_e32 v135, v135, v63
	v_mfma_f32_32x32x16_bf16 v[206:221], v[68:71], v[98:101], v[206:221]
	v_cvt_pk_bf16_f32 v32, v32, v33
	v_cvt_pk_bf16_f32 v33, v34, v35
	v_cvt_pk_bf16_f32 v34, v36, v37
	v_cvt_pk_bf16_f32 v35, v38, v39
	v_cvt_pk_bf16_f32 v36, v40, v41
	v_mfma_f32_32x32x16_bf16 v[190:205], v[72:75], v[102:105], v[190:205]
	v_cvt_pk_bf16_f32 v37, v42, v43
	v_cvt_pk_bf16_f32 v38, v44, v45
	v_cvt_pk_bf16_f32 v39, v46, v47
	v_cvt_pk_bf16_f32 v48, v48, v49
	v_cvt_pk_bf16_f32 v49, v50, v51
	v_mfma_f32_32x32x16_bf16 v[206:221], v[76:79], v[102:105], v[206:221]
	v_cvt_pk_bf16_f32 v50, v52, v53
	v_cvt_pk_bf16_f32 v51, v54, v55
	v_cvt_pk_bf16_f32 v52, v56, v57
	v_cvt_pk_bf16_f32 v53, v58, v59
	v_cvt_pk_bf16_f32 v54, v60, v61
	v_cvt_pk_bf16_f32 v55, v62, v63
	s_waitcnt vmcnt(3) lgkmcnt(0)
	s_barrier
	ds_read_b128 v[156:159], v146 offset:32768
	ds_read_b128 v[160:163], v146 offset:40960
	ds_read_b128 v[164:167], v147 offset:32768
	ds_read_b128 v[168:171], v147 offset:40960
	ds_read_b128 v[172:175], v148 offset:32768
	ds_read_b128 v[176:179], v148 offset:40960
	ds_read_b128 v[180:183], v149 offset:32768
	ds_read_b128 v[184:187], v149 offset:40960
	ds_read_b128 v[64:67], v150 offset:32768
	ds_read_b128 v[68:71], v150 offset:40960
	ds_read_b128 v[72:75], v151 offset:32768
	ds_read_b128 v[76:79], v151 offset:40960
	v_mfma_f32_32x32x16_bf16 v[0:15], v[32:35], v[222:225], v[0:15]
	s_add_i32 m0, s60, 0x4000
	v_exp_f32_e32 v190, v190
	v_exp_f32_e32 v191, v191
	v_mfma_f32_32x32x16_bf16 v[0:15], v[36:39], v[226:229], v[0:15]
	global_load_lds_dwordx4 v124, s[56:57]
	global_load_lds_dwordx4 v126, s[56:57] offset:1024
	v_exp_f32_e32 v192, v192
	v_exp_f32_e32 v193, v193
	v_mfma_f32_32x32x16_bf16 v[0:15], v[48:51], v[230:233], v[0:15]
	s_add_u32 s56, s56, 0x4000
	s_addc_u32 s57, s57, 0
	v_exp_f32_e32 v194, v194
	v_exp_f32_e32 v195, v195
	v_mfma_f32_32x32x16_bf16 v[0:15], v[52:55], v[234:237], v[0:15]
	s_add_i32 m0, s60, 0xc000
	v_exp_f32_e32 v196, v196
	v_exp_f32_e32 v197, v197
	v_mfma_f32_32x32x16_bf16 v[16:31], v[32:35], v[238:241], v[16:31]
	global_load_lds_dwordx4 v128, s[58:59]
	v_exp_f32_e32 v198, v198
	v_exp_f32_e32 v199, v199
	v_mfma_f32_32x32x16_bf16 v[16:31], v[36:39], v[242:245], v[16:31]
	s_add_u32 s58, s58, 0x2000
	s_addc_u32 s59, s59, 0
	v_exp_f32_e32 v200, v200
	v_exp_f32_e32 v201, v201
	v_mfma_f32_32x32x16_bf16 v[16:31], v[48:51], v[246:249], v[16:31]
	v_exp_f32_e32 v202, v202
	v_exp_f32_e32 v203, v203
	v_mfma_f32_32x32x16_bf16 v[16:31], v[52:55], v[140:143], v[16:31]
	v_exp_f32_e32 v204, v204
	v_exp_f32_e32 v205, v205
	s_waitcnt lgkmcnt(0)
; #define SBAR() __builtin_amdgcn_sched_barrier(0)
; #define ROT() do { const int t_ = bv; bv = bk; bk = bw; bw = t_; } while (0)
; template <int D0> __device__ __forceinline__ void pv_one(f32x16& od, int vb, bf16x8 pa0, bf16x8 pa1, bf16x8 pa2, bf16x8 pa3) {
;   const s16x4 l0 = tr_read<v_rd_off(D0, 0, 0)>(vb), h0 = tr_read<v_rd_off(D0, 0, 1)>(vb), l1 = tr_read<v_rd_off(D0, 1, 0)>(vb), h1 = tr_read<v_rd_off(D0, 1, 1)>(vb);
;   const s16x4 l2 = tr_read<v_rd_off(D0, 2, 0)>(vb), h2 = tr_read<v_rd_off(D0, 2, 1)>(vb), l3 = tr_read<v_rd_off(D0, 3, 0)>(vb), h3 = tr_read<v_rd_off(D0, 3, 1)>(vb);
;   asm volatile("s_waitcnt lgkmcnt(0)" ::: "memory"); SBAR();
;     ...
;   od = __builtin_amdgcn_mfma_f32_32x32x16_bf16(pa0, PK(l0, h0), od, 0, 0, 0);
;   od = __builtin_amdgcn_mfma_f32_32x32x16_bf16(pa1, PK(l1, h1), od, 0, 0, 0);
;   od = __builtin_amdgcn_mfma_f32_32x32x16_bf16(pa2, PK(l2, h2), od, 0, 0, 0);
;   od = __builtin_amdgcn_mfma_f32_32x32x16_bf16(pa3, PK(l3, h3), od, 0, 0, 0);
;     ...
; }
; __device__ __forceinline__ void pv_d0(f32x16* o, int vb, bf16x8 pa0, bf16x8 pa1, bf16x8 pa2, bf16x8 pa3) {
;   pv_one<0>(o[0], vb, pa0, pa1, pa2, pa3); pv_one<1>(o[1], vb, pa0, pa1, pa2, pa3);
; template <bool SHIFT> __device__ __forceinline__ void attn_dense_body(const bf16* __restrict__ Qb, const bf16* __restrict__ Kh, const bf16* __restrict__ Vh, bf16* __restrict__ Ob, int seq, char* lds, LAS unsigned char* ldsl, float negB, const float* __restrict__ gq, int qpos0) {
;     ...
;     DMA(bw, (j + 2) * KVBLK);
;     SBAR(); qkt<SHIFT ? 7 : 6>(pA0, pA1, (bf16*)((char*)K_lds + bk * SHM_K), qr, r32, hi);
;     finishSM(pB0, pB1, l_reg, pa0, pa1, pa2, pa3); SBAR();
;     pv_d0(o, vb0 + bv * (int)SHM_V, pa0, pa1, pa2, pa3); partialSM(pA0);
;     asm volatile("s_waitcnt vmcnt(0)" ::: "memory"); __syncthreads(); ROT();
	ds_read_b64_tr_b16 v[222:223], v134 offset:16384
	ds_read_b64_tr_b16 v[224:225], v134 offset:18432
	ds_read_b64_tr_b16 v[226:227], v134 offset:20480
	ds_read_b64_tr_b16 v[228:229], v134 offset:22528
	ds_read_b64_tr_b16 v[230:231], v134 offset:24576
	ds_read_b64_tr_b16 v[232:233], v134 offset:26624
	ds_read_b64_tr_b16 v[234:235], v134 offset:28672
	ds_read_b64_tr_b16 v[236:237], v134 offset:30720
	ds_read_b64_tr_b16 v[238:239], v134 offset:16896
	ds_read_b64_tr_b16 v[240:241], v134 offset:18944
	ds_read_b64_tr_b16 v[242:243], v134 offset:20992
	ds_read_b64_tr_b16 v[244:245], v134 offset:23040
	ds_read_b64_tr_b16 v[246:247], v134 offset:25088
	ds_read_b64_tr_b16 v[248:249], v134 offset:27136
	ds_read_b64_tr_b16 v[140:141], v134 offset:29184
	ds_read_b64_tr_b16 v[142:143], v134 offset:31232
	v_mfma_f32_32x32x16_bf16 v[32:47], v[156:159], v[86:89], 0
	v_exp_f32_e32 v206, v206
	v_add_f32_e32 v133, v133, v190
	v_exp_f32_e32 v207, v207
	v_add_f32_e32 v135, v135, v191
	v_exp_f32_e32 v208, v208
	v_mfma_f32_32x32x16_bf16 v[48:63], v[160:163], v[86:89], 0
	v_add_f32_e32 v133, v133, v192
	v_exp_f32_e32 v209, v209
	v_add_f32_e32 v135, v135, v193
	v_exp_f32_e32 v210, v210
	v_add_f32_e32 v133, v133, v194
	v_mfma_f32_32x32x16_bf16 v[32:47], v[164:167], v[82:85], v[32:47]
	v_exp_f32_e32 v211, v211
	v_add_f32_e32 v135, v135, v195
	v_exp_f32_e32 v212, v212
	v_add_f32_e32 v133, v133, v196
	v_exp_f32_e32 v213, v213
	v_add_f32_e32 v135, v135, v197
	v_mfma_f32_32x32x16_bf16 v[48:63], v[168:171], v[82:85], v[48:63]
	v_exp_f32_e32 v214, v214
	v_add_f32_e32 v133, v133, v198
	v_exp_f32_e32 v215, v215
	v_add_f32_e32 v135, v135, v199
	v_exp_f32_e32 v216, v216
	v_mfma_f32_32x32x16_bf16 v[32:47], v[172:175], v[90:93], v[32:47]
	v_add_f32_e32 v133, v133, v200
	v_exp_f32_e32 v217, v217
	v_add_f32_e32 v135, v135, v201
	v_exp_f32_e32 v218, v218
	v_add_f32_e32 v133, v133, v202
	v_mfma_f32_32x32x16_bf16 v[48:63], v[176:179], v[90:93], v[48:63]
	v_exp_f32_e32 v219, v219
	v_add_f32_e32 v135, v135, v203
	v_exp_f32_e32 v220, v220
	v_add_f32_e32 v133, v133, v204
	v_exp_f32_e32 v221, v221
	v_add_f32_e32 v135, v135, v205
	v_mfma_f32_32x32x16_bf16 v[32:47], v[180:183], v[94:97], v[32:47]
	v_add_f32_e32 v133, v133, v206
	v_add_f32_e32 v135, v135, v207
	v_add_f32_e32 v133, v133, v208
	v_add_f32_e32 v135, v135, v209
	v_add_f32_e32 v133, v133, v210
	v_mfma_f32_32x32x16_bf16 v[48:63], v[184:187], v[94:97], v[48:63]
	v_add_f32_e32 v135, v135, v211
	v_add_f32_e32 v133, v133, v212
	v_add_f32_e32 v135, v135, v213
	v_add_f32_e32 v133, v133, v214
	v_add_f32_e32 v135, v135, v215
	v_mfma_f32_32x32x16_bf16 v[32:47], v[64:67], v[98:101], v[32:47]
	v_add_f32_e32 v133, v133, v216
	v_add_f32_e32 v135, v135, v217
	v_add_f32_e32 v133, v133, v218
	v_add_f32_e32 v135, v135, v219
	v_add_f32_e32 v133, v133, v220
	v_add_f32_e32 v135, v135, v221
	v_mfma_f32_32x32x16_bf16 v[48:63], v[68:71], v[98:101], v[48:63]
	v_cvt_pk_bf16_f32 v190, v190, v191
	v_cvt_pk_bf16_f32 v191, v192, v193
	v_cvt_pk_bf16_f32 v192, v194, v195
	v_cvt_pk_bf16_f32 v193, v196, v197
	v_cvt_pk_bf16_f32 v194, v198, v199
	v_mfma_f32_32x32x16_bf16 v[32:47], v[72:75], v[102:105], v[32:47]
	v_cvt_pk_bf16_f32 v195, v200, v201
	v_cvt_pk_bf16_f32 v196, v202, v203
	v_cvt_pk_bf16_f32 v197, v204, v205
	v_cvt_pk_bf16_f32 v206, v206, v207
	v_cvt_pk_bf16_f32 v207, v208, v209
	v_mfma_f32_32x32x16_bf16 v[48:63], v[76:79], v[102:105], v[48:63]
	v_cvt_pk_bf16_f32 v208, v210, v211
	v_cvt_pk_bf16_f32 v209, v212, v213
	v_cvt_pk_bf16_f32 v210, v214, v215
	v_cvt_pk_bf16_f32 v211, v216, v217
	v_cvt_pk_bf16_f32 v212, v218, v219
	v_cvt_pk_bf16_f32 v213, v220, v221
	s_waitcnt vmcnt(3) lgkmcnt(0)
	s_barrier
	ds_read_b128 v[156:159], v146 offset:0
	ds_read_b128 v[160:163], v146 offset:8192
	ds_read_b128 v[164:167], v147 offset:0
	ds_read_b128 v[168:171], v147 offset:8192
	ds_read_b128 v[172:175], v148 offset:0
	ds_read_b128 v[176:179], v148 offset:8192
	ds_read_b128 v[180:183], v149 offset:0
	ds_read_b128 v[184:187], v149 offset:8192
	ds_read_b128 v[64:67], v150 offset:0
	ds_read_b128 v[68:71], v150 offset:8192
	ds_read_b128 v[72:75], v151 offset:0
	ds_read_b128 v[76:79], v151 offset:8192
	v_mfma_f32_32x32x16_bf16 v[0:15], v[190:193], v[222:225], v[0:15]
	s_add_i32 m0, s60, 0x8000
	v_exp_f32_e32 v32, v32
	v_exp_f32_e32 v33, v33
	v_mfma_f32_32x32x16_bf16 v[0:15], v[194:197], v[226:229], v[0:15]
	global_load_lds_dwordx4 v124, s[56:57]
	global_load_lds_dwordx4 v126, s[56:57] offset:1024
	v_exp_f32_e32 v34, v34
	v_exp_f32_e32 v35, v35
	v_mfma_f32_32x32x16_bf16 v[0:15], v[206:209], v[230:233], v[0:15]
	s_add_u32 s56, s56, 0x4000
	s_addc_u32 s57, s57, 0
	v_exp_f32_e32 v36, v36
	v_exp_f32_e32 v37, v37
	v_mfma_f32_32x32x16_bf16 v[0:15], v[210:213], v[234:237], v[0:15]
	s_add_i32 m0, s60, 0x10000
	v_exp_f32_e32 v38, v38
	v_exp_f32_e32 v39, v39
	v_mfma_f32_32x32x16_bf16 v[16:31], v[190:193], v[238:241], v[16:31]
	global_load_lds_dwordx4 v128, s[58:59]
	v_exp_f32_e32 v40, v40
	v_exp_f32_e32 v41, v41
	v_mfma_f32_32x32x16_bf16 v[16:31], v[194:197], v[242:245], v[16:31]
	s_add_u32 s58, s58, 0x2000
	s_addc_u32 s59, s59, 0
	v_exp_f32_e32 v42, v42
	v_exp_f32_e32 v43, v43
	v_mfma_f32_32x32x16_bf16 v[16:31], v[206:209], v[246:249], v[16:31]
	v_exp_f32_e32 v44, v44
	v_exp_f32_e32 v45, v45
	v_mfma_f32_32x32x16_bf16 v[16:31], v[210:213], v[140:143], v[16:31]
	v_exp_f32_e32 v46, v46
	v_exp_f32_e32 v47, v47
	s_waitcnt lgkmcnt(0)
; __device__ __forceinline__ void partialSM(f32x16& p0) {
; #pragma unroll
;   for (int r = 0; r < 16; ++r) p0[r] = __builtin_amdgcn_exp2f(p0[r]);
; }
; __device__ __forceinline__ void finishSM(f32x16& p0, f32x16& p1, float& l_reg, bf16x8& pa0, bf16x8& pa1, bf16x8& pa2, bf16x8& pa3) {
; #pragma unroll
;   for (int r = 0; r < 16; ++r) p1[r] = __builtin_amdgcn_exp2f(p1[r]);
;   float ps = 0;
; #pragma unroll
;   for (int r = 0; r < 16; ++r) ps += p0[r];
; #pragma unroll
;   for (int r = 0; r < 16; ++r) ps += p1[r];
;   l_reg += ps;
;     ...
;   PK4(p0, 0, pa0); PK4(p0, 8, pa1); PK4(p1, 0, pa2); PK4(p1, 8, pa3);
;     ...
; }
; template <int ND> __device__ __forceinline__ void qkt(f32x16& p0, f32x16& p1, const bf16* Ks, const bf16x8* qr, int r32, int hi) {
;   p0 = f32x16{}; p1 = f32x16{};
; #pragma unroll
;   for (int d0 = 0; d0 < ND; ++d0) { int cb = (d0 * 16 + hi * 8) * 2;
;     bf16x8 b0 = *reinterpret_cast<const bf16x8*>((const char*)Ks + KSWZ(r32, cb));
;     bf16x8 b1 = *reinterpret_cast<const bf16x8*>((const char*)Ks + KSWZ(32 + r32, cb));
;     p0 = __builtin_amdgcn_mfma_f32_32x32x16_bf16(b0, qr[d0], p0, 0, 0, 0);
;     p1 = __builtin_amdgcn_mfma_f32_32x32x16_bf16(b1, qr[d0], p1, 0, 0, 0); }
; }
; __device__ __forceinline__ int v_st(int k, int c) { const int kk = (k & ~0xC) | ((k & 4) << 1) | ((k & 8) >> 1); return ((kk >> 3) * 4 + (c >> 5)) * 512 + ((kk & 7) * 32 + (c & 31)) * 2; }
; __device__ __forceinline__ int v_rd_base(int lane) { return ((lane & 3) << 3) | (((lane >> 2) & 3) << 6) | (((lane >> 4) & 1) << 5) | (((lane >> 5) & 1) << 8); }
; template <int OFF> __device__ __forceinline__ s16x4 tr_read(int vb) {
;   s16x4 r; asm volatile("ds_read_b64_tr_b16 %0, %1 offset:%2" : "=&v"(r) : "v"(vb), "i"(OFF) : "memory"); return r;
; }
; template <int D0> __device__ __forceinline__ void pv_one(f32x16& od, int vb, bf16x8 pa0, bf16x8 pa1, bf16x8 pa2, bf16x8 pa3) {
;   const s16x4 l0 = tr_read<v_rd_off(D0, 0, 0)>(vb), h0 = tr_read<v_rd_off(D0, 0, 1)>(vb), l1 = tr_read<v_rd_off(D0, 1, 0)>(vb), h1 = tr_read<v_rd_off(D0, 1, 1)>(vb);
;   const s16x4 l2 = tr_read<v_rd_off(D0, 2, 0)>(vb), h2 = tr_read<v_rd_off(D0, 2, 1)>(vb), l3 = tr_read<v_rd_off(D0, 3, 0)>(vb), h3 = tr_read<v_rd_off(D0, 3, 1)>(vb);
;   asm volatile("s_waitcnt lgkmcnt(0)" ::: "memory"); SBAR();
;     ...
;   od = __builtin_amdgcn_mfma_f32_32x32x16_bf16(pa0, PK(l0, h0), od, 0, 0, 0);
	ds_read_b64_tr_b16 v[222:223], v134 offset:32768
	ds_read_b64_tr_b16 v[224:225], v134 offset:34816
	ds_read_b64_tr_b16 v[226:227], v134 offset:36864
	ds_read_b64_tr_b16 v[228:229], v134 offset:38912
	ds_read_b64_tr_b16 v[230:231], v134 offset:40960
	ds_read_b64_tr_b16 v[232:233], v134 offset:43008
	ds_read_b64_tr_b16 v[234:235], v134 offset:45056
	ds_read_b64_tr_b16 v[236:237], v134 offset:47104
	ds_read_b64_tr_b16 v[238:239], v134 offset:33280
	ds_read_b64_tr_b16 v[240:241], v134 offset:35328
	ds_read_b64_tr_b16 v[242:243], v134 offset:37376
	ds_read_b64_tr_b16 v[244:245], v134 offset:39424
	ds_read_b64_tr_b16 v[246:247], v134 offset:41472
	ds_read_b64_tr_b16 v[248:249], v134 offset:43520
	ds_read_b64_tr_b16 v[140:141], v134 offset:45568
	ds_read_b64_tr_b16 v[142:143], v134 offset:47616
	v_mfma_f32_32x32x16_bf16 v[190:205], v[156:159], v[86:89], 0
	v_exp_f32_e32 v48, v48
	v_add_f32_e32 v133, v133, v32
	v_exp_f32_e32 v49, v49
	v_add_f32_e32 v135, v135, v33
	v_exp_f32_e32 v50, v50
	v_mfma_f32_32x32x16_bf16 v[206:221], v[160:163], v[86:89], 0
	v_add_f32_e32 v133, v133, v34
	v_exp_f32_e32 v51, v51
	v_add_f32_e32 v135, v135, v35
	v_exp_f32_e32 v52, v52
	v_add_f32_e32 v133, v133, v36
	v_mfma_f32_32x32x16_bf16 v[190:205], v[164:167], v[82:85], v[190:205]
	v_exp_f32_e32 v53, v53
	v_add_f32_e32 v135, v135, v37
	v_exp_f32_e32 v54, v54
	v_add_f32_e32 v133, v133, v38
	v_exp_f32_e32 v55, v55
	v_add_f32_e32 v135, v135, v39
	v_mfma_f32_32x32x16_bf16 v[206:221], v[168:171], v[82:85], v[206:221]
	v_exp_f32_e32 v56, v56
	v_add_f32_e32 v133, v133, v40
	v_exp_f32_e32 v57, v57
	v_add_f32_e32 v135, v135, v41
	v_exp_f32_e32 v58, v58
	v_mfma_f32_32x32x16_bf16 v[190:205], v[172:175], v[90:93], v[190:205]
	v_add_f32_e32 v133, v133, v42
	v_exp_f32_e32 v59, v59
	v_add_f32_e32 v135, v135, v43
	v_exp_f32_e32 v60, v60
	v_add_f32_e32 v133, v133, v44
	v_mfma_f32_32x32x16_bf16 v[206:221], v[176:179], v[90:93], v[206:221]
	v_exp_f32_e32 v61, v61
	v_add_f32_e32 v135, v135, v45
	v_exp_f32_e32 v62, v62
	v_add_f32_e32 v133, v133, v46
	v_exp_f32_e32 v63, v63
	v_add_f32_e32 v135, v135, v47
	v_mfma_f32_32x32x16_bf16 v[190:205], v[180:183], v[94:97], v[190:205]
	v_add_f32_e32 v133, v133, v48
	v_add_f32_e32 v135, v135, v49
	v_add_f32_e32 v133, v133, v50
	v_add_f32_e32 v135, v135, v51
	v_add_f32_e32 v133, v133, v52
	v_mfma_f32_32x32x16_bf16 v[206:221], v[184:187], v[94:97], v[206:221]
	v_add_f32_e32 v135, v135, v53
	v_add_f32_e32 v133, v133, v54
	v_add_f32_e32 v135, v135, v55
	v_add_f32_e32 v133, v133, v56
	v_add_f32_e32 v135, v135, v57
	v_mfma_f32_32x32x16_bf16 v[190:205], v[64:67], v[98:101], v[190:205]
	v_add_f32_e32 v133, v133, v58
	v_add_f32_e32 v135, v135, v59
	v_add_f32_e32 v133, v133, v60
	v_add_f32_e32 v135, v135, v61
	v_add_f32_e32 v133, v133, v62
	v_add_f32_e32 v135, v135, v63
	v_mfma_f32_32x32x16_bf16 v[206:221], v[68:71], v[98:101], v[206:221]
	v_cvt_pk_bf16_f32 v32, v32, v33
	v_cvt_pk_bf16_f32 v33, v34, v35
	v_cvt_pk_bf16_f32 v34, v36, v37
	v_cvt_pk_bf16_f32 v35, v38, v39
	v_cvt_pk_bf16_f32 v36, v40, v41
	v_mfma_f32_32x32x16_bf16 v[190:205], v[72:75], v[102:105], v[190:205]
	v_cvt_pk_bf16_f32 v37, v42, v43
	v_cvt_pk_bf16_f32 v38, v44, v45
	v_cvt_pk_bf16_f32 v39, v46, v47
	v_cvt_pk_bf16_f32 v48, v48, v49
	v_cvt_pk_bf16_f32 v49, v50, v51
	v_mfma_f32_32x32x16_bf16 v[206:221], v[76:79], v[102:105], v[206:221]
	v_cvt_pk_bf16_f32 v50, v52, v53
	v_cvt_pk_bf16_f32 v51, v54, v55
	v_cvt_pk_bf16_f32 v52, v56, v57
	v_cvt_pk_bf16_f32 v53, v58, v59
	v_cvt_pk_bf16_f32 v54, v60, v61
	v_cvt_pk_bf16_f32 v55, v62, v63
	s_waitcnt vmcnt(3) lgkmcnt(0)
	s_barrier
	ds_read_b128 v[156:159], v146 offset:16384
	ds_read_b128 v[160:163], v146 offset:24576
	ds_read_b128 v[164:167], v147 offset:16384
	ds_read_b128 v[168:171], v147 offset:24576
	ds_read_b128 v[172:175], v148 offset:16384
	ds_read_b128 v[176:179], v148 offset:24576
	ds_read_b128 v[180:183], v149 offset:16384
	ds_read_b128 v[184:187], v149 offset:24576
	ds_read_b128 v[64:67], v150 offset:16384
	ds_read_b128 v[68:71], v150 offset:24576
	ds_read_b128 v[72:75], v151 offset:16384
	ds_read_b128 v[76:79], v151 offset:24576
	v_mfma_f32_32x32x16_bf16 v[0:15], v[32:35], v[222:225], v[0:15]
	s_add_i32 m0, s60, 0x0
	v_exp_f32_e32 v190, v190
	v_exp_f32_e32 v191, v191
	v_mfma_f32_32x32x16_bf16 v[0:15], v[36:39], v[226:229], v[0:15]
	global_load_lds_dwordx4 v124, s[56:57]
	global_load_lds_dwordx4 v126, s[56:57] offset:1024
	v_exp_f32_e32 v192, v192
	v_exp_f32_e32 v193, v193
	v_mfma_f32_32x32x16_bf16 v[0:15], v[48:51], v[230:233], v[0:15]
	s_add_u32 s56, s56, 0x4000
	s_addc_u32 s57, s57, 0
	v_exp_f32_e32 v194, v194
	v_exp_f32_e32 v195, v195
	v_mfma_f32_32x32x16_bf16 v[0:15], v[52:55], v[234:237], v[0:15]
	s_add_i32 m0, s60, 0x14000
	v_exp_f32_e32 v196, v196
	v_exp_f32_e32 v197, v197
	v_mfma_f32_32x32x16_bf16 v[16:31], v[32:35], v[238:241], v[16:31]
	global_load_lds_dwordx4 v128, s[58:59]
	v_exp_f32_e32 v198, v198
	v_exp_f32_e32 v199, v199
	v_mfma_f32_32x32x16_bf16 v[16:31], v[36:39], v[242:245], v[16:31]
	s_add_u32 s58, s58, 0x2000
	s_addc_u32 s59, s59, 0
	v_exp_f32_e32 v200, v200
	v_exp_f32_e32 v201, v201
	v_mfma_f32_32x32x16_bf16 v[16:31], v[48:51], v[246:249], v[16:31]
	v_exp_f32_e32 v202, v202
	v_exp_f32_e32 v203, v203
	v_mfma_f32_32x32x16_bf16 v[16:31], v[52:55], v[140:143], v[16:31]
	v_exp_f32_e32 v204, v204
	v_exp_f32_e32 v205, v205
	s_waitcnt lgkmcnt(0)
; __device__ __forceinline__ void partialSM(f32x16& p0) {
; #pragma unroll
;   for (int r = 0; r < 16; ++r) p0[r] = __builtin_amdgcn_exp2f(p0[r]);
; }
; __device__ __forceinline__ void finishSM(f32x16& p0, f32x16& p1, float& l_reg, bf16x8& pa0, bf16x8& pa1, bf16x8& pa2, bf16x8& pa3) {
; #pragma unroll
;   for (int r = 0; r < 16; ++r) p1[r] = __builtin_amdgcn_exp2f(p1[r]);
;   float ps = 0;
; #pragma unroll
;   for (int r = 0; r < 16; ++r) ps += p0[r];
; #pragma unroll
;   for (int r = 0; r < 16; ++r) ps += p1[r];
;   l_reg += ps;
;     ...
;   PK4(p0, 0, pa0); PK4(p0, 8, pa1); PK4(p1, 0, pa2); PK4(p1, 8, pa3);
;     ...
; }
; template <int ND> __device__ __forceinline__ void qkt(f32x16& p0, f32x16& p1, const bf16* Ks, const bf16x8* qr, int r32, int hi) {
;   p0 = f32x16{}; p1 = f32x16{};
; #pragma unroll
;   for (int d0 = 0; d0 < ND; ++d0) { int cb = (d0 * 16 + hi * 8) * 2;
;     bf16x8 b0 = *reinterpret_cast<const bf16x8*>((const char*)Ks + KSWZ(r32, cb));
;     bf16x8 b1 = *reinterpret_cast<const bf16x8*>((const char*)Ks + KSWZ(32 + r32, cb));
;     p0 = __builtin_amdgcn_mfma_f32_32x32x16_bf16(b0, qr[d0], p0, 0, 0, 0);
;     p1 = __builtin_amdgcn_mfma_f32_32x32x16_bf16(b1, qr[d0], p1, 0, 0, 0); }
; }
; __device__ __forceinline__ int v_st(int k, int c) { const int kk = (k & ~0xC) | ((k & 4) << 1) | ((k & 8) >> 1); return ((kk >> 3) * 4 + (c >> 5)) * 512 + ((kk & 7) * 32 + (c & 31)) * 2; }
; __device__ __forceinline__ int v_rd_base(int lane) { return ((lane & 3) << 3) | (((lane >> 2) & 3) << 6) | (((lane >> 4) & 1) << 5) | (((lane >> 5) & 1) << 8); }
; template <int OFF> __device__ __forceinline__ s16x4 tr_read(int vb) {
;   s16x4 r; asm volatile("ds_read_b64_tr_b16 %0, %1 offset:%2" : "=&v"(r) : "v"(vb), "i"(OFF) : "memory"); return r;
; }
; template <int D0> __device__ __forceinline__ void pv_one(f32x16& od, int vb, bf16x8 pa0, bf16x8 pa1, bf16x8 pa2, bf16x8 pa3) {
;   const s16x4 l0 = tr_read<v_rd_off(D0, 0, 0)>(vb), h0 = tr_read<v_rd_off(D0, 0, 1)>(vb), l1 = tr_read<v_rd_off(D0, 1, 0)>(vb), h1 = tr_read<v_rd_off(D0, 1, 1)>(vb);
;   const s16x4 l2 = tr_read<v_rd_off(D0, 2, 0)>(vb), h2 = tr_read<v_rd_off(D0, 2, 1)>(vb), l3 = tr_read<v_rd_off(D0, 3, 0)>(vb), h3 = tr_read<v_rd_off(D0, 3, 1)>(vb);
;   asm volatile("s_waitcnt lgkmcnt(0)" ::: "memory"); SBAR();
;     ...
;   od = __builtin_amdgcn_mfma_f32_32x32x16_bf16(pa0, PK(l0, h0), od, 0, 0, 0);
	ds_read_b64_tr_b16 v[222:223], v134 offset:0
	ds_read_b64_tr_b16 v[224:225], v134 offset:2048
	ds_read_b64_tr_b16 v[226:227], v134 offset:4096
	ds_read_b64_tr_b16 v[228:229], v134 offset:6144
	ds_read_b64_tr_b16 v[230:231], v134 offset:8192
	ds_read_b64_tr_b16 v[232:233], v134 offset:10240
	ds_read_b64_tr_b16 v[234:235], v134 offset:12288
	ds_read_b64_tr_b16 v[236:237], v134 offset:14336
	ds_read_b64_tr_b16 v[238:239], v134 offset:512
	ds_read_b64_tr_b16 v[240:241], v134 offset:2560
	ds_read_b64_tr_b16 v[242:243], v134 offset:4608
	ds_read_b64_tr_b16 v[244:245], v134 offset:6656
	ds_read_b64_tr_b16 v[246:247], v134 offset:8704
	ds_read_b64_tr_b16 v[248:249], v134 offset:10752
	ds_read_b64_tr_b16 v[140:141], v134 offset:12800
	ds_read_b64_tr_b16 v[142:143], v134 offset:14848
	v_mfma_f32_32x32x16_bf16 v[32:47], v[156:159], v[86:89], 0
	v_exp_f32_e32 v206, v206
	v_add_f32_e32 v133, v133, v190
	v_exp_f32_e32 v207, v207
	v_add_f32_e32 v135, v135, v191
	v_exp_f32_e32 v208, v208
	v_mfma_f32_32x32x16_bf16 v[48:63], v[160:163], v[86:89], 0
	v_add_f32_e32 v133, v133, v192
	v_exp_f32_e32 v209, v209
	v_add_f32_e32 v135, v135, v193
	v_exp_f32_e32 v210, v210
	v_add_f32_e32 v133, v133, v194
	v_mfma_f32_32x32x16_bf16 v[32:47], v[164:167], v[82:85], v[32:47]
	v_exp_f32_e32 v211, v211
	v_add_f32_e32 v135, v135, v195
	v_exp_f32_e32 v212, v212
	v_add_f32_e32 v133, v133, v196
	v_exp_f32_e32 v213, v213
	v_add_f32_e32 v135, v135, v197
	v_mfma_f32_32x32x16_bf16 v[48:63], v[168:171], v[82:85], v[48:63]
	v_exp_f32_e32 v214, v214
	v_add_f32_e32 v133, v133, v198
	v_exp_f32_e32 v215, v215
	v_add_f32_e32 v135, v135, v199
	v_exp_f32_e32 v216, v216
	v_mfma_f32_32x32x16_bf16 v[32:47], v[172:175], v[90:93], v[32:47]
	v_add_f32_e32 v133, v133, v200
	v_exp_f32_e32 v217, v217
	v_add_f32_e32 v135, v135, v201
	v_exp_f32_e32 v218, v218
	v_add_f32_e32 v133, v133, v202
	v_mfma_f32_32x32x16_bf16 v[48:63], v[176:179], v[90:93], v[48:63]
	v_exp_f32_e32 v219, v219
	v_add_f32_e32 v135, v135, v203
	v_exp_f32_e32 v220, v220
	v_add_f32_e32 v133, v133, v204
	v_exp_f32_e32 v221, v221
	v_add_f32_e32 v135, v135, v205
	v_mfma_f32_32x32x16_bf16 v[32:47], v[180:183], v[94:97], v[32:47]
	v_add_f32_e32 v133, v133, v206
	v_add_f32_e32 v135, v135, v207
	v_add_f32_e32 v133, v133, v208
	v_add_f32_e32 v135, v135, v209
	v_add_f32_e32 v133, v133, v210
	v_mfma_f32_32x32x16_bf16 v[48:63], v[184:187], v[94:97], v[48:63]
	v_add_f32_e32 v135, v135, v211
	v_add_f32_e32 v133, v133, v212
	v_add_f32_e32 v135, v135, v213
	v_add_f32_e32 v133, v133, v214
	v_add_f32_e32 v135, v135, v215
	v_mfma_f32_32x32x16_bf16 v[32:47], v[64:67], v[98:101], v[32:47]
	v_add_f32_e32 v133, v133, v216
	v_add_f32_e32 v135, v135, v217
	v_add_f32_e32 v133, v133, v218
	v_add_f32_e32 v135, v135, v219
	v_add_f32_e32 v133, v133, v220
	v_add_f32_e32 v135, v135, v221
	v_mfma_f32_32x32x16_bf16 v[48:63], v[68:71], v[98:101], v[48:63]
	v_cvt_pk_bf16_f32 v190, v190, v191
	v_cvt_pk_bf16_f32 v191, v192, v193
	v_cvt_pk_bf16_f32 v192, v194, v195
	v_cvt_pk_bf16_f32 v193, v196, v197
	v_cvt_pk_bf16_f32 v194, v198, v199
	v_mfma_f32_32x32x16_bf16 v[32:47], v[72:75], v[102:105], v[32:47]
	v_cvt_pk_bf16_f32 v195, v200, v201
	v_cvt_pk_bf16_f32 v196, v202, v203
	v_cvt_pk_bf16_f32 v197, v204, v205
	v_cvt_pk_bf16_f32 v206, v206, v207
	v_cvt_pk_bf16_f32 v207, v208, v209
	v_mfma_f32_32x32x16_bf16 v[48:63], v[76:79], v[102:105], v[48:63]
	v_cvt_pk_bf16_f32 v208, v210, v211
	v_cvt_pk_bf16_f32 v209, v212, v213
	v_cvt_pk_bf16_f32 v210, v214, v215
	v_cvt_pk_bf16_f32 v211, v216, v217
	v_cvt_pk_bf16_f32 v212, v218, v219
	v_cvt_pk_bf16_f32 v213, v220, v221
	s_waitcnt vmcnt(3) lgkmcnt(0)
	s_barrier
	ds_read_b128 v[156:159], v146 offset:32768
	ds_read_b128 v[160:163], v146 offset:40960
	ds_read_b128 v[164:167], v147 offset:32768
	ds_read_b128 v[168:171], v147 offset:40960
	ds_read_b128 v[172:175], v148 offset:32768
	ds_read_b128 v[176:179], v148 offset:40960
	ds_read_b128 v[180:183], v149 offset:32768
	ds_read_b128 v[184:187], v149 offset:40960
	ds_read_b128 v[64:67], v150 offset:32768
	ds_read_b128 v[68:71], v150 offset:40960
	ds_read_b128 v[72:75], v151 offset:32768
	ds_read_b128 v[76:79], v151 offset:40960
	v_mfma_f32_32x32x16_bf16 v[0:15], v[190:193], v[222:225], v[0:15]
	s_add_i32 m0, s60, 0x4000
	v_exp_f32_e32 v32, v32
	v_exp_f32_e32 v33, v33
	v_mfma_f32_32x32x16_bf16 v[0:15], v[194:197], v[226:229], v[0:15]
	global_load_lds_dwordx4 v124, s[56:57]
	global_load_lds_dwordx4 v126, s[56:57] offset:1024
	v_exp_f32_e32 v34, v34
	v_exp_f32_e32 v35, v35
	v_mfma_f32_32x32x16_bf16 v[0:15], v[206:209], v[230:233], v[0:15]
	s_add_u32 s56, s56, 0x4000
	s_addc_u32 s57, s57, 0
	v_exp_f32_e32 v36, v36
	v_exp_f32_e32 v37, v37
	v_mfma_f32_32x32x16_bf16 v[0:15], v[210:213], v[234:237], v[0:15]
	s_add_i32 m0, s60, 0xc000
	v_exp_f32_e32 v38, v38
	v_exp_f32_e32 v39, v39
	v_mfma_f32_32x32x16_bf16 v[16:31], v[190:193], v[238:241], v[16:31]
	global_load_lds_dwordx4 v128, s[58:59]
	v_exp_f32_e32 v40, v40
	v_exp_f32_e32 v41, v41
	v_mfma_f32_32x32x16_bf16 v[16:31], v[194:197], v[242:245], v[16:31]
	s_add_u32 s58, s58, 0x2000
	s_addc_u32 s59, s59, 0
	v_exp_f32_e32 v42, v42
	v_exp_f32_e32 v43, v43
	v_mfma_f32_32x32x16_bf16 v[16:31], v[206:209], v[246:249], v[16:31]
	v_exp_f32_e32 v44, v44
	v_exp_f32_e32 v45, v45
	v_mfma_f32_32x32x16_bf16 v[16:31], v[210:213], v[140:143], v[16:31]
	v_exp_f32_e32 v46, v46
	v_exp_f32_e32 v47, v47
	s_waitcnt lgkmcnt(0)
; __device__ __forceinline__ void partialSM(f32x16& p0) {
; #pragma unroll
;   for (int r = 0; r < 16; ++r) p0[r] = __builtin_amdgcn_exp2f(p0[r]);
; }
; __device__ __forceinline__ void finishSM(f32x16& p0, f32x16& p1, float& l_reg, bf16x8& pa0, bf16x8& pa1, bf16x8& pa2, bf16x8& pa3) {
; #pragma unroll
;   for (int r = 0; r < 16; ++r) p1[r] = __builtin_amdgcn_exp2f(p1[r]);
;   float ps = 0;
; #pragma unroll
;   for (int r = 0; r < 16; ++r) ps += p0[r];
; #pragma unroll
;   for (int r = 0; r < 16; ++r) ps += p1[r];
;   l_reg += ps;
;     ...
;   PK4(p0, 0, pa0); PK4(p0, 8, pa1); PK4(p1, 0, pa2); PK4(p1, 8, pa3);
;     ...
; }
; template <int ND> __device__ __forceinline__ void qkt(f32x16& p0, f32x16& p1, const bf16* Ks, const bf16x8* qr, int r32, int hi) {
;   p0 = f32x16{}; p1 = f32x16{};
; #pragma unroll
;   for (int d0 = 0; d0 < ND; ++d0) { int cb = (d0 * 16 + hi * 8) * 2;
;     bf16x8 b0 = *reinterpret_cast<const bf16x8*>((const char*)Ks + KSWZ(r32, cb));
;     bf16x8 b1 = *reinterpret_cast<const bf16x8*>((const char*)Ks + KSWZ(32 + r32, cb));
;     p0 = __builtin_amdgcn_mfma_f32_32x32x16_bf16(b0, qr[d0], p0, 0, 0, 0);
;     p1 = __builtin_amdgcn_mfma_f32_32x32x16_bf16(b1, qr[d0], p1, 0, 0, 0); }
; }
; __device__ __forceinline__ int v_st(int k, int c) { const int kk = (k & ~0xC) | ((k & 4) << 1) | ((k & 8) >> 1); return ((kk >> 3) * 4 + (c >> 5)) * 512 + ((kk & 7) * 32 + (c & 31)) * 2; }
; __device__ __forceinline__ int v_rd_base(int lane) { return ((lane & 3) << 3) | (((lane >> 2) & 3) << 6) | (((lane >> 4) & 1) << 5) | (((lane >> 5) & 1) << 8); }
; template <int OFF> __device__ __forceinline__ s16x4 tr_read(int vb) {
;   s16x4 r; asm volatile("ds_read_b64_tr_b16 %0, %1 offset:%2" : "=&v"(r) : "v"(vb), "i"(OFF) : "memory"); return r;
; }
; template <int D0> __device__ __forceinline__ void pv_one(f32x16& od, int vb, bf16x8 pa0, bf16x8 pa1, bf16x8 pa2, bf16x8 pa3) {
;   const s16x4 l0 = tr_read<v_rd_off(D0, 0, 0)>(vb), h0 = tr_read<v_rd_off(D0, 0, 1)>(vb), l1 = tr_read<v_rd_off(D0, 1, 0)>(vb), h1 = tr_read<v_rd_off(D0, 1, 1)>(vb);
;   const s16x4 l2 = tr_read<v_rd_off(D0, 2, 0)>(vb), h2 = tr_read<v_rd_off(D0, 2, 1)>(vb), l3 = tr_read<v_rd_off(D0, 3, 0)>(vb), h3 = tr_read<v_rd_off(D0, 3, 1)>(vb);
;   asm volatile("s_waitcnt lgkmcnt(0)" ::: "memory"); SBAR();
;     ...
;   od = __builtin_amdgcn_mfma_f32_32x32x16_bf16(pa0, PK(l0, h0), od, 0, 0, 0);
	ds_read_b64_tr_b16 v[222:223], v134 offset:16384
	ds_read_b64_tr_b16 v[224:225], v134 offset:18432
	ds_read_b64_tr_b16 v[226:227], v134 offset:20480
	ds_read_b64_tr_b16 v[228:229], v134 offset:22528
	ds_read_b64_tr_b16 v[230:231], v134 offset:24576
	ds_read_b64_tr_b16 v[232:233], v134 offset:26624
	ds_read_b64_tr_b16 v[234:235], v134 offset:28672
	ds_read_b64_tr_b16 v[236:237], v134 offset:30720
	ds_read_b64_tr_b16 v[238:239], v134 offset:16896
	ds_read_b64_tr_b16 v[240:241], v134 offset:18944
	ds_read_b64_tr_b16 v[242:243], v134 offset:20992
	ds_read_b64_tr_b16 v[244:245], v134 offset:23040
	ds_read_b64_tr_b16 v[246:247], v134 offset:25088
	ds_read_b64_tr_b16 v[248:249], v134 offset:27136
	ds_read_b64_tr_b16 v[140:141], v134 offset:29184
	ds_read_b64_tr_b16 v[142:143], v134 offset:31232
	v_mfma_f32_32x32x16_bf16 v[190:205], v[156:159], v[86:89], 0
	v_exp_f32_e32 v48, v48
	v_add_f32_e32 v133, v133, v32
	v_exp_f32_e32 v49, v49
	v_add_f32_e32 v135, v135, v33
	v_exp_f32_e32 v50, v50
	v_mfma_f32_32x32x16_bf16 v[206:221], v[160:163], v[86:89], 0
	v_add_f32_e32 v133, v133, v34
	v_exp_f32_e32 v51, v51
	v_add_f32_e32 v135, v135, v35
	v_exp_f32_e32 v52, v52
	v_add_f32_e32 v133, v133, v36
	v_mfma_f32_32x32x16_bf16 v[190:205], v[164:167], v[82:85], v[190:205]
	v_exp_f32_e32 v53, v53
	v_add_f32_e32 v135, v135, v37
	v_exp_f32_e32 v54, v54
	v_add_f32_e32 v133, v133, v38
	v_exp_f32_e32 v55, v55
	v_add_f32_e32 v135, v135, v39
	v_mfma_f32_32x32x16_bf16 v[206:221], v[168:171], v[82:85], v[206:221]
	v_exp_f32_e32 v56, v56
	v_add_f32_e32 v133, v133, v40
	v_exp_f32_e32 v57, v57
	v_add_f32_e32 v135, v135, v41
	v_exp_f32_e32 v58, v58
	v_mfma_f32_32x32x16_bf16 v[190:205], v[172:175], v[90:93], v[190:205]
	v_add_f32_e32 v133, v133, v42
	v_exp_f32_e32 v59, v59
	v_add_f32_e32 v135, v135, v43
	v_exp_f32_e32 v60, v60
	v_add_f32_e32 v133, v133, v44
	v_mfma_f32_32x32x16_bf16 v[206:221], v[176:179], v[90:93], v[206:221]
	v_exp_f32_e32 v61, v61
	v_add_f32_e32 v135, v135, v45
	v_exp_f32_e32 v62, v62
	v_add_f32_e32 v133, v133, v46
	v_exp_f32_e32 v63, v63
	v_add_f32_e32 v135, v135, v47
	v_mfma_f32_32x32x16_bf16 v[190:205], v[180:183], v[94:97], v[190:205]
	v_add_f32_e32 v133, v133, v48
	v_add_f32_e32 v135, v135, v49
	v_add_f32_e32 v133, v133, v50
	v_add_f32_e32 v135, v135, v51
	v_add_f32_e32 v133, v133, v52
	v_mfma_f32_32x32x16_bf16 v[206:221], v[184:187], v[94:97], v[206:221]
	v_add_f32_e32 v135, v135, v53
	v_add_f32_e32 v133, v133, v54
	v_add_f32_e32 v135, v135, v55
	v_add_f32_e32 v133, v133, v56
	v_add_f32_e32 v135, v135, v57
	v_mfma_f32_32x32x16_bf16 v[190:205], v[64:67], v[98:101], v[190:205]
	v_add_f32_e32 v133, v133, v58
	v_add_f32_e32 v135, v135, v59
	v_add_f32_e32 v133, v133, v60
	v_add_f32_e32 v135, v135, v61
	v_add_f32_e32 v133, v133, v62
	v_add_f32_e32 v135, v135, v63
	v_mfma_f32_32x32x16_bf16 v[206:221], v[68:71], v[98:101], v[206:221]
	v_cvt_pk_bf16_f32 v32, v32, v33
	v_cvt_pk_bf16_f32 v33, v34, v35
	v_cvt_pk_bf16_f32 v34, v36, v37
	v_cvt_pk_bf16_f32 v35, v38, v39
	v_cvt_pk_bf16_f32 v36, v40, v41
	v_mfma_f32_32x32x16_bf16 v[190:205], v[72:75], v[102:105], v[190:205]
	v_cvt_pk_bf16_f32 v37, v42, v43
	v_cvt_pk_bf16_f32 v38, v44, v45
	v_cvt_pk_bf16_f32 v39, v46, v47
	v_cvt_pk_bf16_f32 v48, v48, v49
	v_cvt_pk_bf16_f32 v49, v50, v51
	v_mfma_f32_32x32x16_bf16 v[206:221], v[76:79], v[102:105], v[206:221]
	v_cvt_pk_bf16_f32 v50, v52, v53
	v_cvt_pk_bf16_f32 v51, v54, v55
	v_cvt_pk_bf16_f32 v52, v56, v57
	v_cvt_pk_bf16_f32 v53, v58, v59
	v_cvt_pk_bf16_f32 v54, v60, v61
	v_cvt_pk_bf16_f32 v55, v62, v63
	s_waitcnt vmcnt(3) lgkmcnt(0)
	s_barrier
	ds_read_b128 v[156:159], v146 offset:0
	ds_read_b128 v[160:163], v146 offset:8192
	ds_read_b128 v[164:167], v147 offset:0
	ds_read_b128 v[168:171], v147 offset:8192
	ds_read_b128 v[172:175], v148 offset:0
	ds_read_b128 v[176:179], v148 offset:8192
	ds_read_b128 v[180:183], v149 offset:0
	ds_read_b128 v[184:187], v149 offset:8192
	ds_read_b128 v[64:67], v150 offset:0
	ds_read_b128 v[68:71], v150 offset:8192
	ds_read_b128 v[72:75], v151 offset:0
	ds_read_b128 v[76:79], v151 offset:8192
	v_mfma_f32_32x32x16_bf16 v[0:15], v[32:35], v[222:225], v[0:15]
	s_add_i32 m0, s60, 0x8000
	v_exp_f32_e32 v190, v190
	v_exp_f32_e32 v191, v191
	v_mfma_f32_32x32x16_bf16 v[0:15], v[36:39], v[226:229], v[0:15]
	global_load_lds_dwordx4 v124, s[56:57]
	global_load_lds_dwordx4 v126, s[56:57] offset:1024
	v_exp_f32_e32 v192, v192
	v_exp_f32_e32 v193, v193
	v_mfma_f32_32x32x16_bf16 v[0:15], v[48:51], v[230:233], v[0:15]
	s_add_u32 s56, s56, 0x4000
	s_addc_u32 s57, s57, 0
	v_exp_f32_e32 v194, v194
	v_exp_f32_e32 v195, v195
	v_mfma_f32_32x32x16_bf16 v[0:15], v[52:55], v[234:237], v[0:15]
	s_add_i32 m0, s60, 0x10000
	v_exp_f32_e32 v196, v196
	v_exp_f32_e32 v197, v197
	v_mfma_f32_32x32x16_bf16 v[16:31], v[32:35], v[238:241], v[16:31]
	global_load_lds_dwordx4 v128, s[58:59]
	v_exp_f32_e32 v198, v198
	v_exp_f32_e32 v199, v199
	v_mfma_f32_32x32x16_bf16 v[16:31], v[36:39], v[242:245], v[16:31]
	s_add_u32 s58, s58, 0x2000
	s_addc_u32 s59, s59, 0
	v_exp_f32_e32 v200, v200
	v_exp_f32_e32 v201, v201
	v_mfma_f32_32x32x16_bf16 v[16:31], v[48:51], v[246:249], v[16:31]
	v_exp_f32_e32 v202, v202
	v_exp_f32_e32 v203, v203
	v_mfma_f32_32x32x16_bf16 v[16:31], v[52:55], v[140:143], v[16:31]
	v_exp_f32_e32 v204, v204
	v_exp_f32_e32 v205, v205
	s_waitcnt lgkmcnt(0)
; __device__ __forceinline__ void partialSM(f32x16& p0) {
; #pragma unroll
;   for (int r = 0; r < 16; ++r) p0[r] = __builtin_amdgcn_exp2f(p0[r]);
; }
; __device__ __forceinline__ void finishSM(f32x16& p0, f32x16& p1, float& l_reg, bf16x8& pa0, bf16x8& pa1, bf16x8& pa2, bf16x8& pa3) {
; #pragma unroll
;   for (int r = 0; r < 16; ++r) p1[r] = __builtin_amdgcn_exp2f(p1[r]);
;   float ps = 0;
; #pragma unroll
;   for (int r = 0; r < 16; ++r) ps += p0[r];
; #pragma unroll
;   for (int r = 0; r < 16; ++r) ps += p1[r];
;   l_reg += ps;
;     ...
;   PK4(p0, 0, pa0); PK4(p0, 8, pa1); PK4(p1, 0, pa2); PK4(p1, 8, pa3);
;     ...
; }
; template <int ND> __device__ __forceinline__ void qkt(f32x16& p0, f32x16& p1, const bf16* Ks, const bf16x8* qr, int r32, int hi) {
;   p0 = f32x16{}; p1 = f32x16{};
; #pragma unroll
;   for (int d0 = 0; d0 < ND; ++d0) { int cb = (d0 * 16 + hi * 8) * 2;
;     bf16x8 b0 = *reinterpret_cast<const bf16x8*>((const char*)Ks + KSWZ(r32, cb));
;     bf16x8 b1 = *reinterpret_cast<const bf16x8*>((const char*)Ks + KSWZ(32 + r32, cb));
;     p0 = __builtin_amdgcn_mfma_f32_32x32x16_bf16(b0, qr[d0], p0, 0, 0, 0);
;     p1 = __builtin_amdgcn_mfma_f32_32x32x16_bf16(b1, qr[d0], p1, 0, 0, 0); }
; }
; __device__ __forceinline__ int v_st(int k, int c) { const int kk = (k & ~0xC) | ((k & 4) << 1) | ((k & 8) >> 1); return ((kk >> 3) * 4 + (c >> 5)) * 512 + ((kk & 7) * 32 + (c & 31)) * 2; }
; __device__ __forceinline__ int v_rd_base(int lane) { return ((lane & 3) << 3) | (((lane >> 2) & 3) << 6) | (((lane >> 4) & 1) << 5) | (((lane >> 5) & 1) << 8); }
; template <int OFF> __device__ __forceinline__ s16x4 tr_read(int vb) {
;   s16x4 r; asm volatile("ds_read_b64_tr_b16 %0, %1 offset:%2" : "=&v"(r) : "v"(vb), "i"(OFF) : "memory"); return r;
; }
; template <int D0> __device__ __forceinline__ void pv_one(f32x16& od, int vb, bf16x8 pa0, bf16x8 pa1, bf16x8 pa2, bf16x8 pa3) {
;   const s16x4 l0 = tr_read<v_rd_off(D0, 0, 0)>(vb), h0 = tr_read<v_rd_off(D0, 0, 1)>(vb), l1 = tr_read<v_rd_off(D0, 1, 0)>(vb), h1 = tr_read<v_rd_off(D0, 1, 1)>(vb);
;   const s16x4 l2 = tr_read<v_rd_off(D0, 2, 0)>(vb), h2 = tr_read<v_rd_off(D0, 2, 1)>(vb), l3 = tr_read<v_rd_off(D0, 3, 0)>(vb), h3 = tr_read<v_rd_off(D0, 3, 1)>(vb);
;   asm volatile("s_waitcnt lgkmcnt(0)" ::: "memory"); SBAR();
;     ...
;   od = __builtin_amdgcn_mfma_f32_32x32x16_bf16(pa0, PK(l0, h0), od, 0, 0, 0);
	ds_read_b64_tr_b16 v[222:223], v134 offset:32768
	ds_read_b64_tr_b16 v[224:225], v134 offset:34816
	ds_read_b64_tr_b16 v[226:227], v134 offset:36864
	ds_read_b64_tr_b16 v[228:229], v134 offset:38912
	ds_read_b64_tr_b16 v[230:231], v134 offset:40960
	ds_read_b64_tr_b16 v[232:233], v134 offset:43008
	ds_read_b64_tr_b16 v[234:235], v134 offset:45056
	ds_read_b64_tr_b16 v[236:237], v134 offset:47104
	ds_read_b64_tr_b16 v[238:239], v134 offset:33280
	ds_read_b64_tr_b16 v[240:241], v134 offset:35328
	ds_read_b64_tr_b16 v[242:243], v134 offset:37376
	ds_read_b64_tr_b16 v[244:245], v134 offset:39424
	ds_read_b64_tr_b16 v[246:247], v134 offset:41472
	ds_read_b64_tr_b16 v[248:249], v134 offset:43520
	ds_read_b64_tr_b16 v[140:141], v134 offset:45568
	ds_read_b64_tr_b16 v[142:143], v134 offset:47616
	v_mfma_f32_32x32x16_bf16 v[32:47], v[156:159], v[86:89], 0
	v_exp_f32_e32 v206, v206
	v_add_f32_e32 v133, v133, v190
	v_exp_f32_e32 v207, v207
	v_add_f32_e32 v135, v135, v191
	v_exp_f32_e32 v208, v208
	v_mfma_f32_32x32x16_bf16 v[48:63], v[160:163], v[86:89], 0
	v_add_f32_e32 v133, v133, v192
	v_exp_f32_e32 v209, v209
	v_add_f32_e32 v135, v135, v193
	v_exp_f32_e32 v210, v210
	v_add_f32_e32 v133, v133, v194
	v_mfma_f32_32x32x16_bf16 v[32:47], v[164:167], v[82:85], v[32:47]
	v_exp_f32_e32 v211, v211
	v_add_f32_e32 v135, v135, v195
	v_exp_f32_e32 v212, v212
	v_add_f32_e32 v133, v133, v196
	v_exp_f32_e32 v213, v213
	v_add_f32_e32 v135, v135, v197
	v_mfma_f32_32x32x16_bf16 v[48:63], v[168:171], v[82:85], v[48:63]
	v_exp_f32_e32 v214, v214
	v_add_f32_e32 v133, v133, v198
	v_exp_f32_e32 v215, v215
	v_add_f32_e32 v135, v135, v199
	v_exp_f32_e32 v216, v216
	v_mfma_f32_32x32x16_bf16 v[32:47], v[172:175], v[90:93], v[32:47]
	v_add_f32_e32 v133, v133, v200
	v_exp_f32_e32 v217, v217
	v_add_f32_e32 v135, v135, v201
	v_exp_f32_e32 v218, v218
	v_add_f32_e32 v133, v133, v202
	v_mfma_f32_32x32x16_bf16 v[48:63], v[176:179], v[90:93], v[48:63]
	v_exp_f32_e32 v219, v219
	v_add_f32_e32 v135, v135, v203
	v_exp_f32_e32 v220, v220
	v_add_f32_e32 v133, v133, v204
	v_exp_f32_e32 v221, v221
	v_add_f32_e32 v135, v135, v205
	v_mfma_f32_32x32x16_bf16 v[32:47], v[180:183], v[94:97], v[32:47]
	v_add_f32_e32 v133, v133, v206
	v_add_f32_e32 v135, v135, v207
	v_add_f32_e32 v133, v133, v208
	v_add_f32_e32 v135, v135, v209
	v_add_f32_e32 v133, v133, v210
	v_mfma_f32_32x32x16_bf16 v[48:63], v[184:187], v[94:97], v[48:63]
	v_add_f32_e32 v135, v135, v211
	v_add_f32_e32 v133, v133, v212
	v_add_f32_e32 v135, v135, v213
	v_add_f32_e32 v133, v133, v214
	v_add_f32_e32 v135, v135, v215
	v_mfma_f32_32x32x16_bf16 v[32:47], v[64:67], v[98:101], v[32:47]
	v_add_f32_e32 v133, v133, v216
	v_add_f32_e32 v135, v135, v217
	v_add_f32_e32 v133, v133, v218
	v_add_f32_e32 v135, v135, v219
	v_add_f32_e32 v133, v133, v220
	v_add_f32_e32 v135, v135, v221
	v_mfma_f32_32x32x16_bf16 v[48:63], v[68:71], v[98:101], v[48:63]
	v_cvt_pk_bf16_f32 v190, v190, v191
	v_cvt_pk_bf16_f32 v191, v192, v193
	v_cvt_pk_bf16_f32 v192, v194, v195
	v_cvt_pk_bf16_f32 v193, v196, v197
	v_cvt_pk_bf16_f32 v194, v198, v199
	v_mfma_f32_32x32x16_bf16 v[32:47], v[72:75], v[102:105], v[32:47]
	v_cvt_pk_bf16_f32 v195, v200, v201
	v_cvt_pk_bf16_f32 v196, v202, v203
	v_cvt_pk_bf16_f32 v197, v204, v205
	v_cvt_pk_bf16_f32 v206, v206, v207
	v_cvt_pk_bf16_f32 v207, v208, v209
	v_mfma_f32_32x32x16_bf16 v[48:63], v[76:79], v[102:105], v[48:63]
	v_cvt_pk_bf16_f32 v208, v210, v211
	v_cvt_pk_bf16_f32 v209, v212, v213
	v_cvt_pk_bf16_f32 v210, v214, v215
	v_cvt_pk_bf16_f32 v211, v216, v217
	v_cvt_pk_bf16_f32 v212, v218, v219
	v_cvt_pk_bf16_f32 v213, v220, v221
	s_waitcnt vmcnt(3) lgkmcnt(0)
	s_barrier
	ds_read_b128 v[156:159], v146 offset:16384
	ds_read_b128 v[160:163], v146 offset:24576
	ds_read_b128 v[164:167], v147 offset:16384
	ds_read_b128 v[168:171], v147 offset:24576
	ds_read_b128 v[172:175], v148 offset:16384
	ds_read_b128 v[176:179], v148 offset:24576
	ds_read_b128 v[180:183], v149 offset:16384
	ds_read_b128 v[184:187], v149 offset:24576
	ds_read_b128 v[64:67], v150 offset:16384
	ds_read_b128 v[68:71], v150 offset:24576
	ds_read_b128 v[72:75], v151 offset:16384
	ds_read_b128 v[76:79], v151 offset:24576
	v_mfma_f32_32x32x16_bf16 v[0:15], v[190:193], v[222:225], v[0:15]
	s_add_i32 m0, s60, 0x0
	v_exp_f32_e32 v32, v32
	v_exp_f32_e32 v33, v33
	v_mfma_f32_32x32x16_bf16 v[0:15], v[194:197], v[226:229], v[0:15]
	global_load_lds_dwordx4 v124, s[56:57]
	global_load_lds_dwordx4 v126, s[56:57] offset:1024
	v_exp_f32_e32 v34, v34
	v_exp_f32_e32 v35, v35
	v_mfma_f32_32x32x16_bf16 v[0:15], v[206:209], v[230:233], v[0:15]
	s_add_u32 s56, s56, 0x4000
	s_addc_u32 s57, s57, 0
	v_exp_f32_e32 v36, v36
	v_exp_f32_e32 v37, v37
	v_mfma_f32_32x32x16_bf16 v[0:15], v[210:213], v[234:237], v[0:15]
	s_add_i32 m0, s60, 0x14000
	v_exp_f32_e32 v38, v38
	v_exp_f32_e32 v39, v39
	v_mfma_f32_32x32x16_bf16 v[16:31], v[190:193], v[238:241], v[16:31]
	global_load_lds_dwordx4 v128, s[58:59]
	v_exp_f32_e32 v40, v40
	v_exp_f32_e32 v41, v41
	v_mfma_f32_32x32x16_bf16 v[16:31], v[194:197], v[242:245], v[16:31]
	s_add_u32 s58, s58, 0x2000
	s_addc_u32 s59, s59, 0
	v_exp_f32_e32 v42, v42
	v_exp_f32_e32 v43, v43
	v_mfma_f32_32x32x16_bf16 v[16:31], v[206:209], v[246:249], v[16:31]
	v_exp_f32_e32 v44, v44
	v_exp_f32_e32 v45, v45
	v_mfma_f32_32x32x16_bf16 v[16:31], v[210:213], v[140:143], v[16:31]
	v_exp_f32_e32 v46, v46
	v_exp_f32_e32 v47, v47
	s_sub_u32 s33, s33, 1
	s_cmp_lg_u32 s33, 0
	s_cbranch_scc1 .Latt_loop
; __device__ __forceinline__ void partialSM(f32x16& p0) {
; #pragma unroll
;   for (int r = 0; r < 16; ++r) p0[r] = __builtin_amdgcn_exp2f(p0[r]);
; }
; __device__ __forceinline__ void finishSM(f32x16& p0, f32x16& p1, float& l_reg, bf16x8& pa0, bf16x8& pa1, bf16x8& pa2, bf16x8& pa3) {
; #pragma unroll
;   for (int r = 0; r < 16; ++r) p1[r] = __builtin_amdgcn_exp2f(p1[r]);
;   float ps = 0;
; #pragma unroll
;   for (int r = 0; r < 16; ++r) ps += p0[r];
; #pragma unroll
;   for (int r = 0; r < 16; ++r) ps += p1[r];
;   l_reg += ps;
;     ...
;   PK4(p0, 0, pa0); PK4(p0, 8, pa1); PK4(p1, 0, pa2); PK4(p1, 8, pa3);
;     ...
; }
; template <int ND> __device__ __forceinline__ void qkt(f32x16& p0, f32x16& p1, const bf16* Ks, const bf16x8* qr, int r32, int hi) {
;   p0 = f32x16{}; p1 = f32x16{};
; #pragma unroll
;   for (int d0 = 0; d0 < ND; ++d0) { int cb = (d0 * 16 + hi * 8) * 2;
;     bf16x8 b0 = *reinterpret_cast<const bf16x8*>((const char*)Ks + KSWZ(r32, cb));
;     bf16x8 b1 = *reinterpret_cast<const bf16x8*>((const char*)Ks + KSWZ(32 + r32, cb));
;     p0 = __builtin_amdgcn_mfma_f32_32x32x16_bf16(b0, qr[d0], p0, 0, 0, 0);
;     p1 = __builtin_amdgcn_mfma_f32_32x32x16_bf16(b1, qr[d0], p1, 0, 0, 0); }
; }
; __device__ __forceinline__ int v_st(int k, int c) { const int kk = (k & ~0xC) | ((k & 4) << 1) | ((k & 8) >> 1); return ((kk >> 3) * 4 + (c >> 5)) * 512 + ((kk & 7) * 32 + (c & 31)) * 2; }
; __device__ __forceinline__ int v_rd_base(int lane) { return ((lane & 3) << 3) | (((lane >> 2) & 3) << 6) | (((lane >> 4) & 1) << 5) | (((lane >> 5) & 1) << 8); }
; template <int OFF> __device__ __forceinline__ s16x4 tr_read(int vb) {
;   s16x4 r; asm volatile("ds_read_b64_tr_b16 %0, %1 offset:%2" : "=&v"(r) : "v"(vb), "i"(OFF) : "memory"); return r;
; }
; template <int D0> __device__ __forceinline__ void pv_one(f32x16& od, int vb, bf16x8 pa0, bf16x8 pa1, bf16x8 pa2, bf16x8 pa3) {
;   const s16x4 l0 = tr_read<v_rd_off(D0, 0, 0)>(vb), h0 = tr_read<v_rd_off(D0, 0, 1)>(vb), l1 = tr_read<v_rd_off(D0, 1, 0)>(vb), h1 = tr_read<v_rd_off(D0, 1, 1)>(vb);
;   const s16x4 l2 = tr_read<v_rd_off(D0, 2, 0)>(vb), h2 = tr_read<v_rd_off(D0, 2, 1)>(vb), l3 = tr_read<v_rd_off(D0, 3, 0)>(vb), h3 = tr_read<v_rd_off(D0, 3, 1)>(vb);
;   asm volatile("s_waitcnt lgkmcnt(0)" ::: "memory"); SBAR();
;     ...
;   od = __builtin_amdgcn_mfma_f32_32x32x16_bf16(pa0, PK(l0, h0), od, 0, 0, 0);
	s_waitcnt lgkmcnt(0)
	ds_read_b64_tr_b16 v[222:223], v134 offset:0
	ds_read_b64_tr_b16 v[224:225], v134 offset:2048
	ds_read_b64_tr_b16 v[226:227], v134 offset:4096
	ds_read_b64_tr_b16 v[228:229], v134 offset:6144
	ds_read_b64_tr_b16 v[230:231], v134 offset:8192
	ds_read_b64_tr_b16 v[232:233], v134 offset:10240
	ds_read_b64_tr_b16 v[234:235], v134 offset:12288
	ds_read_b64_tr_b16 v[236:237], v134 offset:14336
	ds_read_b64_tr_b16 v[238:239], v134 offset:512
	ds_read_b64_tr_b16 v[240:241], v134 offset:2560
	ds_read_b64_tr_b16 v[242:243], v134 offset:4608
	ds_read_b64_tr_b16 v[244:245], v134 offset:6656
	ds_read_b64_tr_b16 v[246:247], v134 offset:8704
	ds_read_b64_tr_b16 v[248:249], v134 offset:10752
	ds_read_b64_tr_b16 v[140:141], v134 offset:12800
	ds_read_b64_tr_b16 v[142:143], v134 offset:14848
	v_mfma_f32_32x32x16_bf16 v[190:205], v[156:159], v[86:89], 0
	v_exp_f32_e32 v48, v48
	v_add_f32_e32 v133, v133, v32
	v_exp_f32_e32 v49, v49
	v_add_f32_e32 v135, v135, v33
	v_exp_f32_e32 v50, v50
	v_mfma_f32_32x32x16_bf16 v[206:221], v[160:163], v[86:89], 0
	v_add_f32_e32 v133, v133, v34
	v_exp_f32_e32 v51, v51
	v_add_f32_e32 v135, v135, v35
	v_exp_f32_e32 v52, v52
	v_add_f32_e32 v133, v133, v36
	v_mfma_f32_32x32x16_bf16 v[190:205], v[164:167], v[82:85], v[190:205]
	v_exp_f32_e32 v53, v53
	v_add_f32_e32 v135, v135, v37
	v_exp_f32_e32 v54, v54
	v_add_f32_e32 v133, v133, v38
	v_exp_f32_e32 v55, v55
	v_add_f32_e32 v135, v135, v39
	v_mfma_f32_32x32x16_bf16 v[206:221], v[168:171], v[82:85], v[206:221]
	v_exp_f32_e32 v56, v56
	v_add_f32_e32 v133, v133, v40
	v_exp_f32_e32 v57, v57
	v_add_f32_e32 v135, v135, v41
	v_exp_f32_e32 v58, v58
	v_mfma_f32_32x32x16_bf16 v[190:205], v[172:175], v[90:93], v[190:205]
	v_add_f32_e32 v133, v133, v42
	v_exp_f32_e32 v59, v59
	v_add_f32_e32 v135, v135, v43
	v_exp_f32_e32 v60, v60
	v_add_f32_e32 v133, v133, v44
	v_mfma_f32_32x32x16_bf16 v[206:221], v[176:179], v[90:93], v[206:221]
	v_exp_f32_e32 v61, v61
	v_add_f32_e32 v135, v135, v45
	v_exp_f32_e32 v62, v62
	v_add_f32_e32 v133, v133, v46
	v_exp_f32_e32 v63, v63
	v_add_f32_e32 v135, v135, v47
	v_mfma_f32_32x32x16_bf16 v[190:205], v[180:183], v[94:97], v[190:205]
	v_add_f32_e32 v133, v133, v48
	v_add_f32_e32 v135, v135, v49
	v_add_f32_e32 v133, v133, v50
	v_add_f32_e32 v135, v135, v51
	v_add_f32_e32 v133, v133, v52
	v_mfma_f32_32x32x16_bf16 v[206:221], v[184:187], v[94:97], v[206:221]
	v_add_f32_e32 v135, v135, v53
	v_add_f32_e32 v133, v133, v54
	v_add_f32_e32 v135, v135, v55
	v_add_f32_e32 v133, v133, v56
	v_add_f32_e32 v135, v135, v57
	v_mfma_f32_32x32x16_bf16 v[190:205], v[64:67], v[98:101], v[190:205]
	v_add_f32_e32 v133, v133, v58
	v_add_f32_e32 v135, v135, v59
	v_add_f32_e32 v133, v133, v60
	v_add_f32_e32 v135, v135, v61
	v_add_f32_e32 v133, v133, v62
	v_add_f32_e32 v135, v135, v63
	v_mfma_f32_32x32x16_bf16 v[206:221], v[68:71], v[98:101], v[206:221]
	v_cvt_pk_bf16_f32 v32, v32, v33
	v_cvt_pk_bf16_f32 v33, v34, v35
	v_cvt_pk_bf16_f32 v34, v36, v37
	v_cvt_pk_bf16_f32 v35, v38, v39
	v_cvt_pk_bf16_f32 v36, v40, v41
	v_mfma_f32_32x32x16_bf16 v[190:205], v[72:75], v[102:105], v[190:205]
	v_cvt_pk_bf16_f32 v37, v42, v43
	v_cvt_pk_bf16_f32 v38, v44, v45
	v_cvt_pk_bf16_f32 v39, v46, v47
	v_cvt_pk_bf16_f32 v48, v48, v49
	v_cvt_pk_bf16_f32 v49, v50, v51
	v_mfma_f32_32x32x16_bf16 v[206:221], v[76:79], v[102:105], v[206:221]
	v_cvt_pk_bf16_f32 v50, v52, v53
	v_cvt_pk_bf16_f32 v51, v54, v55
	v_cvt_pk_bf16_f32 v52, v56, v57
	v_cvt_pk_bf16_f32 v53, v58, v59
	v_cvt_pk_bf16_f32 v54, v60, v61
	v_cvt_pk_bf16_f32 v55, v62, v63
	s_waitcnt vmcnt(3) lgkmcnt(0)
	s_barrier
	ds_read_b128 v[156:159], v146 offset:32768
	ds_read_b128 v[160:163], v146 offset:40960
	ds_read_b128 v[164:167], v147 offset:32768
	ds_read_b128 v[168:171], v147 offset:40960
	ds_read_b128 v[172:175], v148 offset:32768
	ds_read_b128 v[176:179], v148 offset:40960
	ds_read_b128 v[180:183], v149 offset:32768
	ds_read_b128 v[184:187], v149 offset:40960
	ds_read_b128 v[64:67], v150 offset:32768
	ds_read_b128 v[68:71], v150 offset:40960
	ds_read_b128 v[72:75], v151 offset:32768
	ds_read_b128 v[76:79], v151 offset:40960
	v_mfma_f32_32x32x16_bf16 v[0:15], v[32:35], v[222:225], v[0:15]
	s_add_i32 m0, s60, 0x4000
	v_exp_f32_e32 v190, v190
	v_exp_f32_e32 v191, v191
	v_mfma_f32_32x32x16_bf16 v[0:15], v[36:39], v[226:229], v[0:15]
	global_load_lds_dwordx4 v124, s[56:57]
	global_load_lds_dwordx4 v126, s[56:57] offset:1024
	v_exp_f32_e32 v192, v192
	v_exp_f32_e32 v193, v193
	v_mfma_f32_32x32x16_bf16 v[0:15], v[48:51], v[230:233], v[0:15]
	s_add_u32 s56, s56, 0x4000
	s_addc_u32 s57, s57, 0
	v_exp_f32_e32 v194, v194
	v_exp_f32_e32 v195, v195
	v_mfma_f32_32x32x16_bf16 v[0:15], v[52:55], v[234:237], v[0:15]
	s_add_i32 m0, s60, 0xc000
	v_exp_f32_e32 v196, v196
	v_exp_f32_e32 v197, v197
	v_mfma_f32_32x32x16_bf16 v[16:31], v[32:35], v[238:241], v[16:31]
	global_load_lds_dwordx4 v128, s[58:59]
	v_exp_f32_e32 v198, v198
	v_exp_f32_e32 v199, v199
	v_mfma_f32_32x32x16_bf16 v[16:31], v[36:39], v[242:245], v[16:31]
	s_add_u32 s58, s58, 0x2000
	s_addc_u32 s59, s59, 0
	v_exp_f32_e32 v200, v200
	v_exp_f32_e32 v201, v201
	v_mfma_f32_32x32x16_bf16 v[16:31], v[48:51], v[246:249], v[16:31]
	v_exp_f32_e32 v202, v202
	v_exp_f32_e32 v203, v203
	v_mfma_f32_32x32x16_bf16 v[16:31], v[52:55], v[140:143], v[16:31]
	v_exp_f32_e32 v204, v204
	v_exp_f32_e32 v205, v205
	s_waitcnt lgkmcnt(0)
; __device__ __forceinline__ void partialSM(f32x16& p0) {
; #pragma unroll
;   for (int r = 0; r < 16; ++r) p0[r] = __builtin_amdgcn_exp2f(p0[r]);
; }
; __device__ __forceinline__ void finishSM(f32x16& p0, f32x16& p1, float& l_reg, bf16x8& pa0, bf16x8& pa1, bf16x8& pa2, bf16x8& pa3) {
; #pragma unroll
;   for (int r = 0; r < 16; ++r) p1[r] = __builtin_amdgcn_exp2f(p1[r]);
;   float ps = 0;
; #pragma unroll
;   for (int r = 0; r < 16; ++r) ps += p0[r];
; #pragma unroll
;   for (int r = 0; r < 16; ++r) ps += p1[r];
;   l_reg += ps;
;     ...
;   PK4(p0, 0, pa0); PK4(p0, 8, pa1); PK4(p1, 0, pa2); PK4(p1, 8, pa3);
;     ...
; }
; template <int ND> __device__ __forceinline__ void qkt(f32x16& p0, f32x16& p1, const bf16* Ks, const bf16x8* qr, int r32, int hi) {
;   p0 = f32x16{}; p1 = f32x16{};
; #pragma unroll
;   for (int d0 = 0; d0 < ND; ++d0) { int cb = (d0 * 16 + hi * 8) * 2;
;     bf16x8 b0 = *reinterpret_cast<const bf16x8*>((const char*)Ks + KSWZ(r32, cb));
;     bf16x8 b1 = *reinterpret_cast<const bf16x8*>((const char*)Ks + KSWZ(32 + r32, cb));
;     p0 = __builtin_amdgcn_mfma_f32_32x32x16_bf16(b0, qr[d0], p0, 0, 0, 0);
;     p1 = __builtin_amdgcn_mfma_f32_32x32x16_bf16(b1, qr[d0], p1, 0, 0, 0); }
; }
; __device__ __forceinline__ int v_st(int k, int c) { const int kk = (k & ~0xC) | ((k & 4) << 1) | ((k & 8) >> 1); return ((kk >> 3) * 4 + (c >> 5)) * 512 + ((kk & 7) * 32 + (c & 31)) * 2; }
; __device__ __forceinline__ int v_rd_base(int lane) { return ((lane & 3) << 3) | (((lane >> 2) & 3) << 6) | (((lane >> 4) & 1) << 5) | (((lane >> 5) & 1) << 8); }
; template <int OFF> __device__ __forceinline__ s16x4 tr_read(int vb) {
;   s16x4 r; asm volatile("ds_read_b64_tr_b16 %0, %1 offset:%2" : "=&v"(r) : "v"(vb), "i"(OFF) : "memory"); return r;
; }
; template <int D0> __device__ __forceinline__ void pv_one(f32x16& od, int vb, bf16x8 pa0, bf16x8 pa1, bf16x8 pa2, bf16x8 pa3) {
;   const s16x4 l0 = tr_read<v_rd_off(D0, 0, 0)>(vb), h0 = tr_read<v_rd_off(D0, 0, 1)>(vb), l1 = tr_read<v_rd_off(D0, 1, 0)>(vb), h1 = tr_read<v_rd_off(D0, 1, 1)>(vb);
;   const s16x4 l2 = tr_read<v_rd_off(D0, 2, 0)>(vb), h2 = tr_read<v_rd_off(D0, 2, 1)>(vb), l3 = tr_read<v_rd_off(D0, 3, 0)>(vb), h3 = tr_read<v_rd_off(D0, 3, 1)>(vb);
;   asm volatile("s_waitcnt lgkmcnt(0)" ::: "memory"); SBAR();
;     ...
;   od = __builtin_amdgcn_mfma_f32_32x32x16_bf16(pa0, PK(l0, h0), od, 0, 0, 0);
	ds_read_b64_tr_b16 v[222:223], v134 offset:16384
	ds_read_b64_tr_b16 v[224:225], v134 offset:18432
	ds_read_b64_tr_b16 v[226:227], v134 offset:20480
	ds_read_b64_tr_b16 v[228:229], v134 offset:22528
	ds_read_b64_tr_b16 v[230:231], v134 offset:24576
	ds_read_b64_tr_b16 v[232:233], v134 offset:26624
	ds_read_b64_tr_b16 v[234:235], v134 offset:28672
	ds_read_b64_tr_b16 v[236:237], v134 offset:30720
	ds_read_b64_tr_b16 v[238:239], v134 offset:16896
	ds_read_b64_tr_b16 v[240:241], v134 offset:18944
	ds_read_b64_tr_b16 v[242:243], v134 offset:20992
	ds_read_b64_tr_b16 v[244:245], v134 offset:23040
	ds_read_b64_tr_b16 v[246:247], v134 offset:25088
	ds_read_b64_tr_b16 v[248:249], v134 offset:27136
	ds_read_b64_tr_b16 v[140:141], v134 offset:29184
	ds_read_b64_tr_b16 v[142:143], v134 offset:31232
	v_mfma_f32_32x32x16_bf16 v[32:47], v[156:159], v[86:89], 0
	v_exp_f32_e32 v206, v206
	v_add_f32_e32 v133, v133, v190
	v_exp_f32_e32 v207, v207
	v_add_f32_e32 v135, v135, v191
	v_exp_f32_e32 v208, v208
	v_mfma_f32_32x32x16_bf16 v[48:63], v[160:163], v[86:89], 0
	v_add_f32_e32 v133, v133, v192
	v_exp_f32_e32 v209, v209
	v_add_f32_e32 v135, v135, v193
	v_exp_f32_e32 v210, v210
	v_add_f32_e32 v133, v133, v194
	v_mfma_f32_32x32x16_bf16 v[32:47], v[164:167], v[82:85], v[32:47]
	v_exp_f32_e32 v211, v211
	v_add_f32_e32 v135, v135, v195
	v_exp_f32_e32 v212, v212
	v_add_f32_e32 v133, v133, v196
	v_exp_f32_e32 v213, v213
	v_add_f32_e32 v135, v135, v197
	v_mfma_f32_32x32x16_bf16 v[48:63], v[168:171], v[82:85], v[48:63]
	v_exp_f32_e32 v214, v214
	v_add_f32_e32 v133, v133, v198
	v_exp_f32_e32 v215, v215
	v_add_f32_e32 v135, v135, v199
	v_exp_f32_e32 v216, v216
	v_mfma_f32_32x32x16_bf16 v[32:47], v[172:175], v[90:93], v[32:47]
	v_add_f32_e32 v133, v133, v200
	v_exp_f32_e32 v217, v217
	v_add_f32_e32 v135, v135, v201
	v_exp_f32_e32 v218, v218
	v_add_f32_e32 v133, v133, v202
	v_mfma_f32_32x32x16_bf16 v[48:63], v[176:179], v[90:93], v[48:63]
	v_exp_f32_e32 v219, v219
	v_add_f32_e32 v135, v135, v203
	v_exp_f32_e32 v220, v220
	v_add_f32_e32 v133, v133, v204
	v_exp_f32_e32 v221, v221
	v_add_f32_e32 v135, v135, v205
	v_mfma_f32_32x32x16_bf16 v[32:47], v[180:183], v[94:97], v[32:47]
	v_add_f32_e32 v133, v133, v206
	v_add_f32_e32 v135, v135, v207
	v_add_f32_e32 v133, v133, v208
	v_add_f32_e32 v135, v135, v209
	v_add_f32_e32 v133, v133, v210
	v_mfma_f32_32x32x16_bf16 v[48:63], v[184:187], v[94:97], v[48:63]
	v_add_f32_e32 v135, v135, v211
	v_add_f32_e32 v133, v133, v212
	v_add_f32_e32 v135, v135, v213
	v_add_f32_e32 v133, v133, v214
	v_add_f32_e32 v135, v135, v215
	v_mfma_f32_32x32x16_bf16 v[32:47], v[64:67], v[98:101], v[32:47]
	v_add_f32_e32 v133, v133, v216
	v_add_f32_e32 v135, v135, v217
	v_add_f32_e32 v133, v133, v218
	v_add_f32_e32 v135, v135, v219
	v_add_f32_e32 v133, v133, v220
	v_add_f32_e32 v135, v135, v221
	v_mfma_f32_32x32x16_bf16 v[48:63], v[68:71], v[98:101], v[48:63]
	v_cvt_pk_bf16_f32 v190, v190, v191
	v_cvt_pk_bf16_f32 v191, v192, v193
	v_cvt_pk_bf16_f32 v192, v194, v195
	v_cvt_pk_bf16_f32 v193, v196, v197
	v_cvt_pk_bf16_f32 v194, v198, v199
	v_mfma_f32_32x32x16_bf16 v[32:47], v[72:75], v[102:105], v[32:47]
	v_cvt_pk_bf16_f32 v195, v200, v201
	v_cvt_pk_bf16_f32 v196, v202, v203
	v_cvt_pk_bf16_f32 v197, v204, v205
	v_cvt_pk_bf16_f32 v206, v206, v207
	v_cvt_pk_bf16_f32 v207, v208, v209
	v_mfma_f32_32x32x16_bf16 v[48:63], v[76:79], v[102:105], v[48:63]
	v_cvt_pk_bf16_f32 v208, v210, v211
	v_cvt_pk_bf16_f32 v209, v212, v213
	v_cvt_pk_bf16_f32 v210, v214, v215
	v_cvt_pk_bf16_f32 v211, v216, v217
	v_cvt_pk_bf16_f32 v212, v218, v219
	v_cvt_pk_bf16_f32 v213, v220, v221
	s_waitcnt vmcnt(3) lgkmcnt(0)
	s_barrier
	ds_read_b128 v[156:159], v146 offset:0
	ds_read_b128 v[160:163], v146 offset:8192
	ds_read_b128 v[164:167], v147 offset:0
	ds_read_b128 v[168:171], v147 offset:8192
	ds_read_b128 v[172:175], v148 offset:0
	ds_read_b128 v[176:179], v148 offset:8192
	ds_read_b128 v[180:183], v149 offset:0
	ds_read_b128 v[184:187], v149 offset:8192
	ds_read_b128 v[64:67], v150 offset:0
	ds_read_b128 v[68:71], v150 offset:8192
	ds_read_b128 v[72:75], v151 offset:0
	ds_read_b128 v[76:79], v151 offset:8192
	v_mfma_f32_32x32x16_bf16 v[0:15], v[190:193], v[222:225], v[0:15]
	s_add_i32 m0, s60, 0x8000
	v_exp_f32_e32 v32, v32
	v_exp_f32_e32 v33, v33
	v_mfma_f32_32x32x16_bf16 v[0:15], v[194:197], v[226:229], v[0:15]
	global_load_lds_dwordx4 v124, s[56:57]
	global_load_lds_dwordx4 v126, s[56:57] offset:1024
	v_exp_f32_e32 v34, v34
	v_exp_f32_e32 v35, v35
	v_mfma_f32_32x32x16_bf16 v[0:15], v[206:209], v[230:233], v[0:15]
	s_add_u32 s56, s56, 0x4000
	s_addc_u32 s57, s57, 0
	v_exp_f32_e32 v36, v36
	v_exp_f32_e32 v37, v37
	v_mfma_f32_32x32x16_bf16 v[0:15], v[210:213], v[234:237], v[0:15]
	s_add_i32 m0, s60, 0x10000
	v_exp_f32_e32 v38, v38
	v_exp_f32_e32 v39, v39
	v_mfma_f32_32x32x16_bf16 v[16:31], v[190:193], v[238:241], v[16:31]
	global_load_lds_dwordx4 v128, s[58:59]
	v_exp_f32_e32 v40, v40
	v_exp_f32_e32 v41, v41
	v_mfma_f32_32x32x16_bf16 v[16:31], v[194:197], v[242:245], v[16:31]
	s_add_u32 s58, s58, 0x2000
	s_addc_u32 s59, s59, 0
	v_exp_f32_e32 v42, v42
	v_exp_f32_e32 v43, v43
	v_mfma_f32_32x32x16_bf16 v[16:31], v[206:209], v[246:249], v[16:31]
	v_exp_f32_e32 v44, v44
	v_exp_f32_e32 v45, v45
	v_mfma_f32_32x32x16_bf16 v[16:31], v[210:213], v[140:143], v[16:31]
	v_exp_f32_e32 v46, v46
	v_exp_f32_e32 v47, v47
	s_waitcnt lgkmcnt(0)
; __device__ __forceinline__ void partialSM(f32x16& p0) {
; #pragma unroll
;   for (int r = 0; r < 16; ++r) p0[r] = __builtin_amdgcn_exp2f(p0[r]);
; }
; __device__ __forceinline__ void finishSM(f32x16& p0, f32x16& p1, float& l_reg, bf16x8& pa0, bf16x8& pa1, bf16x8& pa2, bf16x8& pa3) {
; #pragma unroll
;   for (int r = 0; r < 16; ++r) p1[r] = __builtin_amdgcn_exp2f(p1[r]);
;   float ps = 0;
; #pragma unroll
;   for (int r = 0; r < 16; ++r) ps += p0[r];
; #pragma unroll
;   for (int r = 0; r < 16; ++r) ps += p1[r];
;   l_reg += ps;
;     ...
;   PK4(p0, 0, pa0); PK4(p0, 8, pa1); PK4(p1, 0, pa2); PK4(p1, 8, pa3);
;     ...
; }
; template <int ND> __device__ __forceinline__ void qkt(f32x16& p0, f32x16& p1, const bf16* Ks, const bf16x8* qr, int r32, int hi) {
;   p0 = f32x16{}; p1 = f32x16{};
; #pragma unroll
;   for (int d0 = 0; d0 < ND; ++d0) { int cb = (d0 * 16 + hi * 8) * 2;
;     bf16x8 b0 = *reinterpret_cast<const bf16x8*>((const char*)Ks + KSWZ(r32, cb));
;     bf16x8 b1 = *reinterpret_cast<const bf16x8*>((const char*)Ks + KSWZ(32 + r32, cb));
;     p0 = __builtin_amdgcn_mfma_f32_32x32x16_bf16(b0, qr[d0], p0, 0, 0, 0);
;     p1 = __builtin_amdgcn_mfma_f32_32x32x16_bf16(b1, qr[d0], p1, 0, 0, 0); }
; }
; __device__ __forceinline__ int v_st(int k, int c) { const int kk = (k & ~0xC) | ((k & 4) << 1) | ((k & 8) >> 1); return ((kk >> 3) * 4 + (c >> 5)) * 512 + ((kk & 7) * 32 + (c & 31)) * 2; }
; __device__ __forceinline__ int v_rd_base(int lane) { return ((lane & 3) << 3) | (((lane >> 2) & 3) << 6) | (((lane >> 4) & 1) << 5) | (((lane >> 5) & 1) << 8); }
; template <int OFF> __device__ __forceinline__ s16x4 tr_read(int vb) {
;   s16x4 r; asm volatile("ds_read_b64_tr_b16 %0, %1 offset:%2" : "=&v"(r) : "v"(vb), "i"(OFF) : "memory"); return r;
; }
; template <int D0> __device__ __forceinline__ void pv_one(f32x16& od, int vb, bf16x8 pa0, bf16x8 pa1, bf16x8 pa2, bf16x8 pa3) {
;   const s16x4 l0 = tr_read<v_rd_off(D0, 0, 0)>(vb), h0 = tr_read<v_rd_off(D0, 0, 1)>(vb), l1 = tr_read<v_rd_off(D0, 1, 0)>(vb), h1 = tr_read<v_rd_off(D0, 1, 1)>(vb);
;   const s16x4 l2 = tr_read<v_rd_off(D0, 2, 0)>(vb), h2 = tr_read<v_rd_off(D0, 2, 1)>(vb), l3 = tr_read<v_rd_off(D0, 3, 0)>(vb), h3 = tr_read<v_rd_off(D0, 3, 1)>(vb);
;   asm volatile("s_waitcnt lgkmcnt(0)" ::: "memory"); SBAR();
;     ...
;   od = __builtin_amdgcn_mfma_f32_32x32x16_bf16(pa0, PK(l0, h0), od, 0, 0, 0);
	ds_read_b64_tr_b16 v[222:223], v134 offset:32768
	ds_read_b64_tr_b16 v[224:225], v134 offset:34816
	ds_read_b64_tr_b16 v[226:227], v134 offset:36864
	ds_read_b64_tr_b16 v[228:229], v134 offset:38912
	ds_read_b64_tr_b16 v[230:231], v134 offset:40960
	ds_read_b64_tr_b16 v[232:233], v134 offset:43008
	ds_read_b64_tr_b16 v[234:235], v134 offset:45056
	ds_read_b64_tr_b16 v[236:237], v134 offset:47104
	ds_read_b64_tr_b16 v[238:239], v134 offset:33280
	ds_read_b64_tr_b16 v[240:241], v134 offset:35328
	ds_read_b64_tr_b16 v[242:243], v134 offset:37376
	ds_read_b64_tr_b16 v[244:245], v134 offset:39424
	ds_read_b64_tr_b16 v[246:247], v134 offset:41472
	ds_read_b64_tr_b16 v[248:249], v134 offset:43520
	ds_read_b64_tr_b16 v[140:141], v134 offset:45568
	ds_read_b64_tr_b16 v[142:143], v134 offset:47616
	v_mfma_f32_32x32x16_bf16 v[190:205], v[156:159], v[86:89], 0
	v_exp_f32_e32 v48, v48
	v_add_f32_e32 v133, v133, v32
	v_exp_f32_e32 v49, v49
	v_add_f32_e32 v135, v135, v33
	v_exp_f32_e32 v50, v50
	v_mfma_f32_32x32x16_bf16 v[206:221], v[160:163], v[86:89], 0
	v_add_f32_e32 v133, v133, v34
	v_exp_f32_e32 v51, v51
	v_add_f32_e32 v135, v135, v35
	v_exp_f32_e32 v52, v52
	v_add_f32_e32 v133, v133, v36
	v_mfma_f32_32x32x16_bf16 v[190:205], v[164:167], v[82:85], v[190:205]
	v_exp_f32_e32 v53, v53
	v_add_f32_e32 v135, v135, v37
	v_exp_f32_e32 v54, v54
	v_add_f32_e32 v133, v133, v38
	v_exp_f32_e32 v55, v55
	v_add_f32_e32 v135, v135, v39
	v_mfma_f32_32x32x16_bf16 v[206:221], v[168:171], v[82:85], v[206:221]
	v_exp_f32_e32 v56, v56
	v_add_f32_e32 v133, v133, v40
	v_exp_f32_e32 v57, v57
	v_add_f32_e32 v135, v135, v41
	v_exp_f32_e32 v58, v58
	v_mfma_f32_32x32x16_bf16 v[190:205], v[172:175], v[90:93], v[190:205]
	v_add_f32_e32 v133, v133, v42
	v_exp_f32_e32 v59, v59
	v_add_f32_e32 v135, v135, v43
	v_exp_f32_e32 v60, v60
	v_add_f32_e32 v133, v133, v44
	v_mfma_f32_32x32x16_bf16 v[206:221], v[176:179], v[90:93], v[206:221]
	v_exp_f32_e32 v61, v61
	v_add_f32_e32 v135, v135, v45
	v_exp_f32_e32 v62, v62
	v_add_f32_e32 v133, v133, v46
	v_exp_f32_e32 v63, v63
	v_add_f32_e32 v135, v135, v47
	v_mfma_f32_32x32x16_bf16 v[190:205], v[180:183], v[94:97], v[190:205]
	v_add_f32_e32 v133, v133, v48
	v_add_f32_e32 v135, v135, v49
	v_add_f32_e32 v133, v133, v50
	v_add_f32_e32 v135, v135, v51
	v_add_f32_e32 v133, v133, v52
	v_mfma_f32_32x32x16_bf16 v[206:221], v[184:187], v[94:97], v[206:221]
	v_add_f32_e32 v135, v135, v53
	v_add_f32_e32 v133, v133, v54
	v_add_f32_e32 v135, v135, v55
	v_add_f32_e32 v133, v133, v56
	v_add_f32_e32 v135, v135, v57
	v_mfma_f32_32x32x16_bf16 v[190:205], v[64:67], v[98:101], v[190:205]
	v_add_f32_e32 v133, v133, v58
	v_add_f32_e32 v135, v135, v59
	v_add_f32_e32 v133, v133, v60
	v_add_f32_e32 v135, v135, v61
	v_add_f32_e32 v133, v133, v62
	v_add_f32_e32 v135, v135, v63
	v_mfma_f32_32x32x16_bf16 v[206:221], v[68:71], v[98:101], v[206:221]
	v_cvt_pk_bf16_f32 v32, v32, v33
	v_cvt_pk_bf16_f32 v33, v34, v35
	v_cvt_pk_bf16_f32 v34, v36, v37
	v_cvt_pk_bf16_f32 v35, v38, v39
	v_cvt_pk_bf16_f32 v36, v40, v41
	v_mfma_f32_32x32x16_bf16 v[190:205], v[72:75], v[102:105], v[190:205]
	v_cvt_pk_bf16_f32 v37, v42, v43
	v_cvt_pk_bf16_f32 v38, v44, v45
	v_cvt_pk_bf16_f32 v39, v46, v47
	v_cvt_pk_bf16_f32 v48, v48, v49
	v_cvt_pk_bf16_f32 v49, v50, v51
	v_mfma_f32_32x32x16_bf16 v[206:221], v[76:79], v[102:105], v[206:221]
	v_cvt_pk_bf16_f32 v50, v52, v53
	v_cvt_pk_bf16_f32 v51, v54, v55
	v_cvt_pk_bf16_f32 v52, v56, v57
	v_cvt_pk_bf16_f32 v53, v58, v59
	v_cvt_pk_bf16_f32 v54, v60, v61
	v_cvt_pk_bf16_f32 v55, v62, v63
	s_waitcnt vmcnt(3) lgkmcnt(0)
	s_barrier
	ds_read_b128 v[156:159], v146 offset:16384
	ds_read_b128 v[160:163], v146 offset:24576
	ds_read_b128 v[164:167], v147 offset:16384
	ds_read_b128 v[168:171], v147 offset:24576
	ds_read_b128 v[172:175], v148 offset:16384
	ds_read_b128 v[176:179], v148 offset:24576
	ds_read_b128 v[180:183], v149 offset:16384
	ds_read_b128 v[184:187], v149 offset:24576
	ds_read_b128 v[64:67], v150 offset:16384
	ds_read_b128 v[68:71], v150 offset:24576
	ds_read_b128 v[72:75], v151 offset:16384
	ds_read_b128 v[76:79], v151 offset:24576
	v_mfma_f32_32x32x16_bf16 v[0:15], v[32:35], v[222:225], v[0:15]
	s_add_i32 m0, s60, 0x0
	v_exp_f32_e32 v190, v190
	v_exp_f32_e32 v191, v191
	v_mfma_f32_32x32x16_bf16 v[0:15], v[36:39], v[226:229], v[0:15]
	global_load_lds_dwordx4 v124, s[56:57]
	global_load_lds_dwordx4 v126, s[56:57] offset:1024
	v_exp_f32_e32 v192, v192
	v_exp_f32_e32 v193, v193
	v_mfma_f32_32x32x16_bf16 v[0:15], v[48:51], v[230:233], v[0:15]
	s_add_u32 s56, s56, 0x4000
	s_addc_u32 s57, s57, 0
	v_exp_f32_e32 v194, v194
	v_exp_f32_e32 v195, v195
	v_mfma_f32_32x32x16_bf16 v[0:15], v[52:55], v[234:237], v[0:15]
	s_add_i32 m0, s60, 0x14000
	v_exp_f32_e32 v196, v196
	v_exp_f32_e32 v197, v197
	v_mfma_f32_32x32x16_bf16 v[16:31], v[32:35], v[238:241], v[16:31]
	global_load_lds_dwordx4 v128, s[58:59]
	v_exp_f32_e32 v198, v198
	v_exp_f32_e32 v199, v199
	v_mfma_f32_32x32x16_bf16 v[16:31], v[36:39], v[242:245], v[16:31]
	s_add_u32 s58, s58, 0x2000
	s_addc_u32 s59, s59, 0
	v_exp_f32_e32 v200, v200
	v_exp_f32_e32 v201, v201
	v_mfma_f32_32x32x16_bf16 v[16:31], v[48:51], v[246:249], v[16:31]
	v_exp_f32_e32 v202, v202
	v_exp_f32_e32 v203, v203
	v_mfma_f32_32x32x16_bf16 v[16:31], v[52:55], v[140:143], v[16:31]
	v_exp_f32_e32 v204, v204
	v_exp_f32_e32 v205, v205
	s_waitcnt lgkmcnt(0)
; __device__ __forceinline__ void partialSM(f32x16& p0) {
; #pragma unroll
;   for (int r = 0; r < 16; ++r) p0[r] = __builtin_amdgcn_exp2f(p0[r]);
; }
; __device__ __forceinline__ void finishSM(f32x16& p0, f32x16& p1, float& l_reg, bf16x8& pa0, bf16x8& pa1, bf16x8& pa2, bf16x8& pa3) {
; #pragma unroll
;   for (int r = 0; r < 16; ++r) p1[r] = __builtin_amdgcn_exp2f(p1[r]);
;   float ps = 0;
; #pragma unroll
;   for (int r = 0; r < 16; ++r) ps += p0[r];
; #pragma unroll
;   for (int r = 0; r < 16; ++r) ps += p1[r];
;   l_reg += ps;
;     ...
;   PK4(p0, 0, pa0); PK4(p0, 8, pa1); PK4(p1, 0, pa2); PK4(p1, 8, pa3);
;     ...
; }
; template <int ND> __device__ __forceinline__ void qkt(f32x16& p0, f32x16& p1, const bf16* Ks, const bf16x8* qr, int r32, int hi) {
;   p0 = f32x16{}; p1 = f32x16{};
; #pragma unroll
;   for (int d0 = 0; d0 < ND; ++d0) { int cb = (d0 * 16 + hi * 8) * 2;
;     bf16x8 b0 = *reinterpret_cast<const bf16x8*>((const char*)Ks + KSWZ(r32, cb));
;     bf16x8 b1 = *reinterpret_cast<const bf16x8*>((const char*)Ks + KSWZ(32 + r32, cb));
;     p0 = __builtin_amdgcn_mfma_f32_32x32x16_bf16(b0, qr[d0], p0, 0, 0, 0);
;     p1 = __builtin_amdgcn_mfma_f32_32x32x16_bf16(b1, qr[d0], p1, 0, 0, 0); }
; }
; __device__ __forceinline__ int v_st(int k, int c) { const int kk = (k & ~0xC) | ((k & 4) << 1) | ((k & 8) >> 1); return ((kk >> 3) * 4 + (c >> 5)) * 512 + ((kk & 7) * 32 + (c & 31)) * 2; }
; __device__ __forceinline__ int v_rd_base(int lane) { return ((lane & 3) << 3) | (((lane >> 2) & 3) << 6) | (((lane >> 4) & 1) << 5) | (((lane >> 5) & 1) << 8); }
; template <int OFF> __device__ __forceinline__ s16x4 tr_read(int vb) {
;   s16x4 r; asm volatile("ds_read_b64_tr_b16 %0, %1 offset:%2" : "=&v"(r) : "v"(vb), "i"(OFF) : "memory"); return r;
; }
; template <int D0> __device__ __forceinline__ void pv_one(f32x16& od, int vb, bf16x8 pa0, bf16x8 pa1, bf16x8 pa2, bf16x8 pa3) {
;   const s16x4 l0 = tr_read<v_rd_off(D0, 0, 0)>(vb), h0 = tr_read<v_rd_off(D0, 0, 1)>(vb), l1 = tr_read<v_rd_off(D0, 1, 0)>(vb), h1 = tr_read<v_rd_off(D0, 1, 1)>(vb);
;   const s16x4 l2 = tr_read<v_rd_off(D0, 2, 0)>(vb), h2 = tr_read<v_rd_off(D0, 2, 1)>(vb), l3 = tr_read<v_rd_off(D0, 3, 0)>(vb), h3 = tr_read<v_rd_off(D0, 3, 1)>(vb);
;   asm volatile("s_waitcnt lgkmcnt(0)" ::: "memory"); SBAR();
;     ...
;   od = __builtin_amdgcn_mfma_f32_32x32x16_bf16(pa0, PK(l0, h0), od, 0, 0, 0);
	ds_read_b64_tr_b16 v[222:223], v134 offset:0
	ds_read_b64_tr_b16 v[224:225], v134 offset:2048
	ds_read_b64_tr_b16 v[226:227], v134 offset:4096
	ds_read_b64_tr_b16 v[228:229], v134 offset:6144
	ds_read_b64_tr_b16 v[230:231], v134 offset:8192
	ds_read_b64_tr_b16 v[232:233], v134 offset:10240
	ds_read_b64_tr_b16 v[234:235], v134 offset:12288
	ds_read_b64_tr_b16 v[236:237], v134 offset:14336
	ds_read_b64_tr_b16 v[238:239], v134 offset:512
	ds_read_b64_tr_b16 v[240:241], v134 offset:2560
	ds_read_b64_tr_b16 v[242:243], v134 offset:4608
	ds_read_b64_tr_b16 v[244:245], v134 offset:6656
	ds_read_b64_tr_b16 v[246:247], v134 offset:8704
	ds_read_b64_tr_b16 v[248:249], v134 offset:10752
	ds_read_b64_tr_b16 v[140:141], v134 offset:12800
	ds_read_b64_tr_b16 v[142:143], v134 offset:14848
	v_mfma_f32_32x32x16_bf16 v[32:47], v[156:159], v[86:89], 0
	v_exp_f32_e32 v206, v206
	v_add_f32_e32 v133, v133, v190
	v_exp_f32_e32 v207, v207
	v_add_f32_e32 v135, v135, v191
	v_exp_f32_e32 v208, v208
	v_mfma_f32_32x32x16_bf16 v[48:63], v[160:163], v[86:89], 0
	v_add_f32_e32 v133, v133, v192
	v_exp_f32_e32 v209, v209
	v_add_f32_e32 v135, v135, v193
	v_exp_f32_e32 v210, v210
	v_add_f32_e32 v133, v133, v194
	v_mfma_f32_32x32x16_bf16 v[32:47], v[164:167], v[82:85], v[32:47]
	v_exp_f32_e32 v211, v211
	v_add_f32_e32 v135, v135, v195
	v_exp_f32_e32 v212, v212
	v_add_f32_e32 v133, v133, v196
	v_exp_f32_e32 v213, v213
	v_add_f32_e32 v135, v135, v197
	v_mfma_f32_32x32x16_bf16 v[48:63], v[168:171], v[82:85], v[48:63]
	v_exp_f32_e32 v214, v214
	v_add_f32_e32 v133, v133, v198
	v_exp_f32_e32 v215, v215
	v_add_f32_e32 v135, v135, v199
	v_exp_f32_e32 v216, v216
	v_mfma_f32_32x32x16_bf16 v[32:47], v[172:175], v[90:93], v[32:47]
	v_add_f32_e32 v133, v133, v200
	v_exp_f32_e32 v217, v217
	v_add_f32_e32 v135, v135, v201
	v_exp_f32_e32 v218, v218
	v_add_f32_e32 v133, v133, v202
	v_mfma_f32_32x32x16_bf16 v[48:63], v[176:179], v[90:93], v[48:63]
	v_exp_f32_e32 v219, v219
	v_add_f32_e32 v135, v135, v203
	v_exp_f32_e32 v220, v220
	v_add_f32_e32 v133, v133, v204
	v_exp_f32_e32 v221, v221
	v_add_f32_e32 v135, v135, v205
	v_mfma_f32_32x32x16_bf16 v[32:47], v[180:183], v[94:97], v[32:47]
	v_add_f32_e32 v133, v133, v206
	v_add_f32_e32 v135, v135, v207
	v_add_f32_e32 v133, v133, v208
	v_add_f32_e32 v135, v135, v209
	v_add_f32_e32 v133, v133, v210
	v_mfma_f32_32x32x16_bf16 v[48:63], v[184:187], v[94:97], v[48:63]
	v_add_f32_e32 v135, v135, v211
	v_add_f32_e32 v133, v133, v212
	v_add_f32_e32 v135, v135, v213
	v_add_f32_e32 v133, v133, v214
	v_add_f32_e32 v135, v135, v215
	v_mfma_f32_32x32x16_bf16 v[32:47], v[64:67], v[98:101], v[32:47]
	v_add_f32_e32 v133, v133, v216
	v_add_f32_e32 v135, v135, v217
	v_add_f32_e32 v133, v133, v218
	v_add_f32_e32 v135, v135, v219
	v_add_f32_e32 v133, v133, v220
	v_add_f32_e32 v135, v135, v221
	v_mfma_f32_32x32x16_bf16 v[48:63], v[68:71], v[98:101], v[48:63]
	v_cvt_pk_bf16_f32 v190, v190, v191
	v_cvt_pk_bf16_f32 v191, v192, v193
	v_cvt_pk_bf16_f32 v192, v194, v195
	v_cvt_pk_bf16_f32 v193, v196, v197
	v_cvt_pk_bf16_f32 v194, v198, v199
	v_mfma_f32_32x32x16_bf16 v[32:47], v[72:75], v[102:105], v[32:47]
	v_cvt_pk_bf16_f32 v195, v200, v201
	v_cvt_pk_bf16_f32 v196, v202, v203
	v_cvt_pk_bf16_f32 v197, v204, v205
	v_cvt_pk_bf16_f32 v206, v206, v207
	v_cvt_pk_bf16_f32 v207, v208, v209
	v_mfma_f32_32x32x16_bf16 v[48:63], v[76:79], v[102:105], v[48:63]
	v_cvt_pk_bf16_f32 v208, v210, v211
	v_cvt_pk_bf16_f32 v209, v212, v213
	v_cvt_pk_bf16_f32 v210, v214, v215
	v_cvt_pk_bf16_f32 v211, v216, v217
	v_cvt_pk_bf16_f32 v212, v218, v219
	v_cvt_pk_bf16_f32 v213, v220, v221
	s_waitcnt vmcnt(3) lgkmcnt(0)
	s_barrier
	ds_read_b128 v[156:159], v146 offset:32768
	ds_read_b128 v[160:163], v146 offset:40960
	ds_read_b128 v[164:167], v147 offset:32768
	ds_read_b128 v[168:171], v147 offset:40960
	ds_read_b128 v[172:175], v148 offset:32768
	ds_read_b128 v[176:179], v148 offset:40960
	ds_read_b128 v[180:183], v149 offset:32768
	ds_read_b128 v[184:187], v149 offset:40960
	ds_read_b128 v[64:67], v150 offset:32768
	ds_read_b128 v[68:71], v150 offset:40960
	ds_read_b128 v[72:75], v151 offset:32768
	ds_read_b128 v[76:79], v151 offset:40960
	v_mfma_f32_32x32x16_bf16 v[0:15], v[190:193], v[222:225], v[0:15]
	s_add_i32 m0, s60, 0x4000
	v_exp_f32_e32 v32, v32
	v_exp_f32_e32 v33, v33
	v_mfma_f32_32x32x16_bf16 v[0:15], v[194:197], v[226:229], v[0:15]
	global_load_lds_dwordx4 v124, s[56:57]
	global_load_lds_dwordx4 v126, s[56:57] offset:1024
	v_exp_f32_e32 v34, v34
	v_exp_f32_e32 v35, v35
	v_mfma_f32_32x32x16_bf16 v[0:15], v[206:209], v[230:233], v[0:15]
	s_add_u32 s56, s56, 0x4000
	s_addc_u32 s57, s57, 0
	v_exp_f32_e32 v36, v36
	v_exp_f32_e32 v37, v37
	v_mfma_f32_32x32x16_bf16 v[0:15], v[210:213], v[234:237], v[0:15]
	s_add_i32 m0, s60, 0xc000
	v_exp_f32_e32 v38, v38
	v_exp_f32_e32 v39, v39
	v_mfma_f32_32x32x16_bf16 v[16:31], v[190:193], v[238:241], v[16:31]
	global_load_lds_dwordx4 v128, s[58:59]
	v_exp_f32_e32 v40, v40
	v_exp_f32_e32 v41, v41
	v_mfma_f32_32x32x16_bf16 v[16:31], v[194:197], v[242:245], v[16:31]
	s_add_u32 s58, s58, 0x2000
	s_addc_u32 s59, s59, 0
	v_exp_f32_e32 v42, v42
	v_exp_f32_e32 v43, v43
	v_mfma_f32_32x32x16_bf16 v[16:31], v[206:209], v[246:249], v[16:31]
	v_exp_f32_e32 v44, v44
	v_exp_f32_e32 v45, v45
	v_mfma_f32_32x32x16_bf16 v[16:31], v[210:213], v[140:143], v[16:31]
	v_exp_f32_e32 v46, v46
	v_exp_f32_e32 v47, v47
	s_waitcnt lgkmcnt(0)
; __device__ __forceinline__ void partialSM(f32x16& p0) {
; #pragma unroll
;   for (int r = 0; r < 16; ++r) p0[r] = __builtin_amdgcn_exp2f(p0[r]);
; }
; __device__ __forceinline__ void finishSM(f32x16& p0, f32x16& p1, float& l_reg, bf16x8& pa0, bf16x8& pa1, bf16x8& pa2, bf16x8& pa3) {
; #pragma unroll
;   for (int r = 0; r < 16; ++r) p1[r] = __builtin_amdgcn_exp2f(p1[r]);
;   float ps = 0;
; #pragma unroll
;   for (int r = 0; r < 16; ++r) ps += p0[r];
; #pragma unroll
;   for (int r = 0; r < 16; ++r) ps += p1[r];
;   l_reg += ps;
;     ...
;   PK4(p0, 0, pa0); PK4(p0, 8, pa1); PK4(p1, 0, pa2); PK4(p1, 8, pa3);
;     ...
; }
; template <int ND> __device__ __forceinline__ void qkt(f32x16& p0, f32x16& p1, const bf16* Ks, const bf16x8* qr, int r32, int hi) {
;   p0 = f32x16{}; p1 = f32x16{};
; #pragma unroll
;   for (int d0 = 0; d0 < ND; ++d0) { int cb = (d0 * 16 + hi * 8) * 2;
;     bf16x8 b0 = *reinterpret_cast<const bf16x8*>((const char*)Ks + KSWZ(r32, cb));
;     bf16x8 b1 = *reinterpret_cast<const bf16x8*>((const char*)Ks + KSWZ(32 + r32, cb));
;     p0 = __builtin_amdgcn_mfma_f32_32x32x16_bf16(b0, qr[d0], p0, 0, 0, 0);
;     p1 = __builtin_amdgcn_mfma_f32_32x32x16_bf16(b1, qr[d0], p1, 0, 0, 0); }
; }
; __device__ __forceinline__ int v_st(int k, int c) { const int kk = (k & ~0xC) | ((k & 4) << 1) | ((k & 8) >> 1); return ((kk >> 3) * 4 + (c >> 5)) * 512 + ((kk & 7) * 32 + (c & 31)) * 2; }
; __device__ __forceinline__ int v_rd_base(int lane) { return ((lane & 3) << 3) | (((lane >> 2) & 3) << 6) | (((lane >> 4) & 1) << 5) | (((lane >> 5) & 1) << 8); }
; template <int OFF> __device__ __forceinline__ s16x4 tr_read(int vb) {
;   s16x4 r; asm volatile("ds_read_b64_tr_b16 %0, %1 offset:%2" : "=&v"(r) : "v"(vb), "i"(OFF) : "memory"); return r;
; }
; template <int D0> __device__ __forceinline__ void pv_one(f32x16& od, int vb, bf16x8 pa0, bf16x8 pa1, bf16x8 pa2, bf16x8 pa3) {
;   const s16x4 l0 = tr_read<v_rd_off(D0, 0, 0)>(vb), h0 = tr_read<v_rd_off(D0, 0, 1)>(vb), l1 = tr_read<v_rd_off(D0, 1, 0)>(vb), h1 = tr_read<v_rd_off(D0, 1, 1)>(vb);
;   const s16x4 l2 = tr_read<v_rd_off(D0, 2, 0)>(vb), h2 = tr_read<v_rd_off(D0, 2, 1)>(vb), l3 = tr_read<v_rd_off(D0, 3, 0)>(vb), h3 = tr_read<v_rd_off(D0, 3, 1)>(vb);
;   asm volatile("s_waitcnt lgkmcnt(0)" ::: "memory"); SBAR();
;     ...
;   od = __builtin_amdgcn_mfma_f32_32x32x16_bf16(pa0, PK(l0, h0), od, 0, 0, 0);
	ds_read_b64_tr_b16 v[222:223], v134 offset:16384
	ds_read_b64_tr_b16 v[224:225], v134 offset:18432
	ds_read_b64_tr_b16 v[226:227], v134 offset:20480
	ds_read_b64_tr_b16 v[228:229], v134 offset:22528
	ds_read_b64_tr_b16 v[230:231], v134 offset:24576
	ds_read_b64_tr_b16 v[232:233], v134 offset:26624
	ds_read_b64_tr_b16 v[234:235], v134 offset:28672
	ds_read_b64_tr_b16 v[236:237], v134 offset:30720
	ds_read_b64_tr_b16 v[238:239], v134 offset:16896
	ds_read_b64_tr_b16 v[240:241], v134 offset:18944
	ds_read_b64_tr_b16 v[242:243], v134 offset:20992
	ds_read_b64_tr_b16 v[244:245], v134 offset:23040
	ds_read_b64_tr_b16 v[246:247], v134 offset:25088
	ds_read_b64_tr_b16 v[248:249], v134 offset:27136
	ds_read_b64_tr_b16 v[140:141], v134 offset:29184
	ds_read_b64_tr_b16 v[142:143], v134 offset:31232
	v_mfma_f32_32x32x16_bf16 v[190:205], v[156:159], v[86:89], 0
	v_exp_f32_e32 v48, v48
	v_add_f32_e32 v133, v133, v32
	v_exp_f32_e32 v49, v49
	v_add_f32_e32 v135, v135, v33
	v_exp_f32_e32 v50, v50
	v_mfma_f32_32x32x16_bf16 v[206:221], v[160:163], v[86:89], 0
	v_add_f32_e32 v133, v133, v34
	v_exp_f32_e32 v51, v51
	v_add_f32_e32 v135, v135, v35
	v_exp_f32_e32 v52, v52
	v_add_f32_e32 v133, v133, v36
	v_mfma_f32_32x32x16_bf16 v[190:205], v[164:167], v[82:85], v[190:205]
	v_exp_f32_e32 v53, v53
	v_add_f32_e32 v135, v135, v37
	v_exp_f32_e32 v54, v54
	v_add_f32_e32 v133, v133, v38
	v_exp_f32_e32 v55, v55
	v_add_f32_e32 v135, v135, v39
	v_mfma_f32_32x32x16_bf16 v[206:221], v[168:171], v[82:85], v[206:221]
	v_exp_f32_e32 v56, v56
	v_add_f32_e32 v133, v133, v40
	v_exp_f32_e32 v57, v57
	v_add_f32_e32 v135, v135, v41
	v_exp_f32_e32 v58, v58
	v_mfma_f32_32x32x16_bf16 v[190:205], v[172:175], v[90:93], v[190:205]
	v_add_f32_e32 v133, v133, v42
	v_exp_f32_e32 v59, v59
	v_add_f32_e32 v135, v135, v43
	v_exp_f32_e32 v60, v60
	v_add_f32_e32 v133, v133, v44
	v_mfma_f32_32x32x16_bf16 v[206:221], v[176:179], v[90:93], v[206:221]
	v_exp_f32_e32 v61, v61
	v_add_f32_e32 v135, v135, v45
	v_exp_f32_e32 v62, v62
	v_add_f32_e32 v133, v133, v46
	v_exp_f32_e32 v63, v63
	v_add_f32_e32 v135, v135, v47
	v_mfma_f32_32x32x16_bf16 v[190:205], v[180:183], v[94:97], v[190:205]
	v_add_f32_e32 v133, v133, v48
	v_add_f32_e32 v135, v135, v49
	v_add_f32_e32 v133, v133, v50
	v_add_f32_e32 v135, v135, v51
	v_add_f32_e32 v133, v133, v52
	v_mfma_f32_32x32x16_bf16 v[206:221], v[184:187], v[94:97], v[206:221]
	v_add_f32_e32 v135, v135, v53
	v_add_f32_e32 v133, v133, v54
	v_add_f32_e32 v135, v135, v55
	v_add_f32_e32 v133, v133, v56
	v_add_f32_e32 v135, v135, v57
	v_mfma_f32_32x32x16_bf16 v[190:205], v[64:67], v[98:101], v[190:205]
	v_add_f32_e32 v133, v133, v58
	v_add_f32_e32 v135, v135, v59
	v_add_f32_e32 v133, v133, v60
	v_add_f32_e32 v135, v135, v61
	v_add_f32_e32 v133, v133, v62
	v_add_f32_e32 v135, v135, v63
	v_mfma_f32_32x32x16_bf16 v[206:221], v[68:71], v[98:101], v[206:221]
	v_cvt_pk_bf16_f32 v32, v32, v33
	v_cvt_pk_bf16_f32 v33, v34, v35
	v_cvt_pk_bf16_f32 v34, v36, v37
	v_cvt_pk_bf16_f32 v35, v38, v39
	v_cvt_pk_bf16_f32 v36, v40, v41
	v_mfma_f32_32x32x16_bf16 v[190:205], v[72:75], v[102:105], v[190:205]
	v_cvt_pk_bf16_f32 v37, v42, v43
	v_cvt_pk_bf16_f32 v38, v44, v45
	v_cvt_pk_bf16_f32 v39, v46, v47
	v_cvt_pk_bf16_f32 v48, v48, v49
	v_cvt_pk_bf16_f32 v49, v50, v51
	v_mfma_f32_32x32x16_bf16 v[206:221], v[76:79], v[102:105], v[206:221]
	v_cvt_pk_bf16_f32 v50, v52, v53
	v_cvt_pk_bf16_f32 v51, v54, v55
	v_cvt_pk_bf16_f32 v52, v56, v57
	v_cvt_pk_bf16_f32 v53, v58, v59
	v_cvt_pk_bf16_f32 v54, v60, v61
	v_cvt_pk_bf16_f32 v55, v62, v63
	s_waitcnt vmcnt(3) lgkmcnt(0)
	s_barrier
	ds_read_b128 v[156:159], v146 offset:0
	ds_read_b128 v[160:163], v146 offset:8192
	ds_read_b128 v[164:167], v147 offset:0
	ds_read_b128 v[168:171], v147 offset:8192
	ds_read_b128 v[172:175], v148 offset:0
	ds_read_b128 v[176:179], v148 offset:8192
	ds_read_b128 v[180:183], v149 offset:0
	ds_read_b128 v[184:187], v149 offset:8192
	ds_read_b128 v[64:67], v150 offset:0
	ds_read_b128 v[68:71], v150 offset:8192
	ds_read_b128 v[72:75], v151 offset:0
	ds_read_b128 v[76:79], v151 offset:8192
	v_mfma_f32_32x32x16_bf16 v[0:15], v[32:35], v[222:225], v[0:15]
	s_add_i32 m0, s60, 0x10000
	v_exp_f32_e32 v190, v190
	v_exp_f32_e32 v191, v191
	v_mfma_f32_32x32x16_bf16 v[0:15], v[36:39], v[226:229], v[0:15]
	global_load_lds_dwordx4 v128, s[58:59]
	v_exp_f32_e32 v192, v192
	v_exp_f32_e32 v193, v193
	v_mfma_f32_32x32x16_bf16 v[0:15], v[48:51], v[230:233], v[0:15]
	s_add_u32 s58, s58, 0x2000
	s_addc_u32 s59, s59, 0
	v_exp_f32_e32 v194, v194
	v_exp_f32_e32 v195, v195
	v_mfma_f32_32x32x16_bf16 v[0:15], v[52:55], v[234:237], v[0:15]
	v_exp_f32_e32 v196, v196
	v_exp_f32_e32 v197, v197
	v_mfma_f32_32x32x16_bf16 v[16:31], v[32:35], v[238:241], v[16:31]
	v_exp_f32_e32 v198, v198
	v_exp_f32_e32 v199, v199
	v_mfma_f32_32x32x16_bf16 v[16:31], v[36:39], v[242:245], v[16:31]
	v_exp_f32_e32 v200, v200
	v_exp_f32_e32 v201, v201
	v_mfma_f32_32x32x16_bf16 v[16:31], v[48:51], v[246:249], v[16:31]
	v_exp_f32_e32 v202, v202
	v_exp_f32_e32 v203, v203
	v_mfma_f32_32x32x16_bf16 v[16:31], v[52:55], v[140:143], v[16:31]
	v_exp_f32_e32 v204, v204
	v_exp_f32_e32 v205, v205
	s_waitcnt lgkmcnt(0)
; __device__ __forceinline__ void partialSM(f32x16& p0) {
; #pragma unroll
;   for (int r = 0; r < 16; ++r) p0[r] = __builtin_amdgcn_exp2f(p0[r]);
; }
; __device__ __forceinline__ void finishSM(f32x16& p0, f32x16& p1, float& l_reg, bf16x8& pa0, bf16x8& pa1, bf16x8& pa2, bf16x8& pa3) {
; #pragma unroll
;   for (int r = 0; r < 16; ++r) p1[r] = __builtin_amdgcn_exp2f(p1[r]);
;   float ps = 0;
; #pragma unroll
;   for (int r = 0; r < 16; ++r) ps += p0[r];
; #pragma unroll
;   for (int r = 0; r < 16; ++r) ps += p1[r];
;   l_reg += ps;
;     ...
;   PK4(p0, 0, pa0); PK4(p0, 8, pa1); PK4(p1, 0, pa2); PK4(p1, 8, pa3);
;     ...
; }
; template <int ND> __device__ __forceinline__ void qkt(f32x16& p0, f32x16& p1, const bf16* Ks, const bf16x8* qr, int r32, int hi) {
;   p0 = f32x16{}; p1 = f32x16{};
; #pragma unroll
;   for (int d0 = 0; d0 < ND; ++d0) { int cb = (d0 * 16 + hi * 8) * 2;
;     bf16x8 b0 = *reinterpret_cast<const bf16x8*>((const char*)Ks + KSWZ(r32, cb));
;     bf16x8 b1 = *reinterpret_cast<const bf16x8*>((const char*)Ks + KSWZ(32 + r32, cb));
;     p0 = __builtin_amdgcn_mfma_f32_32x32x16_bf16(b0, qr[d0], p0, 0, 0, 0);
;     p1 = __builtin_amdgcn_mfma_f32_32x32x16_bf16(b1, qr[d0], p1, 0, 0, 0); }
; }
; __device__ __forceinline__ int v_st(int k, int c) { const int kk = (k & ~0xC) | ((k & 4) << 1) | ((k & 8) >> 1); return ((kk >> 3) * 4 + (c >> 5)) * 512 + ((kk & 7) * 32 + (c & 31)) * 2; }
; __device__ __forceinline__ int v_rd_base(int lane) { return ((lane & 3) << 3) | (((lane >> 2) & 3) << 6) | (((lane >> 4) & 1) << 5) | (((lane >> 5) & 1) << 8); }
; template <int OFF> __device__ __forceinline__ s16x4 tr_read(int vb) {
;   s16x4 r; asm volatile("ds_read_b64_tr_b16 %0, %1 offset:%2" : "=&v"(r) : "v"(vb), "i"(OFF) : "memory"); return r;
; }
; template <int D0> __device__ __forceinline__ void pv_one(f32x16& od, int vb, bf16x8 pa0, bf16x8 pa1, bf16x8 pa2, bf16x8 pa3) {
;   const s16x4 l0 = tr_read<v_rd_off(D0, 0, 0)>(vb), h0 = tr_read<v_rd_off(D0, 0, 1)>(vb), l1 = tr_read<v_rd_off(D0, 1, 0)>(vb), h1 = tr_read<v_rd_off(D0, 1, 1)>(vb);
;   const s16x4 l2 = tr_read<v_rd_off(D0, 2, 0)>(vb), h2 = tr_read<v_rd_off(D0, 2, 1)>(vb), l3 = tr_read<v_rd_off(D0, 3, 0)>(vb), h3 = tr_read<v_rd_off(D0, 3, 1)>(vb);
;   asm volatile("s_waitcnt lgkmcnt(0)" ::: "memory"); SBAR();
;     ...
;   od = __builtin_amdgcn_mfma_f32_32x32x16_bf16(pa0, PK(l0, h0), od, 0, 0, 0);
	ds_read_b64_tr_b16 v[222:223], v134 offset:32768
	ds_read_b64_tr_b16 v[224:225], v134 offset:34816
	ds_read_b64_tr_b16 v[226:227], v134 offset:36864
	ds_read_b64_tr_b16 v[228:229], v134 offset:38912
	ds_read_b64_tr_b16 v[230:231], v134 offset:40960
	ds_read_b64_tr_b16 v[232:233], v134 offset:43008
	ds_read_b64_tr_b16 v[234:235], v134 offset:45056
	ds_read_b64_tr_b16 v[236:237], v134 offset:47104
	ds_read_b64_tr_b16 v[238:239], v134 offset:33280
	ds_read_b64_tr_b16 v[240:241], v134 offset:35328
	ds_read_b64_tr_b16 v[242:243], v134 offset:37376
	ds_read_b64_tr_b16 v[244:245], v134 offset:39424
	ds_read_b64_tr_b16 v[246:247], v134 offset:41472
	ds_read_b64_tr_b16 v[248:249], v134 offset:43520
	ds_read_b64_tr_b16 v[140:141], v134 offset:45568
	ds_read_b64_tr_b16 v[142:143], v134 offset:47616
	v_mfma_f32_32x32x16_bf16 v[32:47], v[156:159], v[86:89], 0
	v_exp_f32_e32 v206, v206
	v_add_f32_e32 v133, v133, v190
	v_exp_f32_e32 v207, v207
	v_add_f32_e32 v135, v135, v191
	v_exp_f32_e32 v208, v208
	v_mfma_f32_32x32x16_bf16 v[48:63], v[160:163], v[86:89], 0
	v_add_f32_e32 v133, v133, v192
	v_exp_f32_e32 v209, v209
	v_add_f32_e32 v135, v135, v193
	v_exp_f32_e32 v210, v210
	v_add_f32_e32 v133, v133, v194
	v_mfma_f32_32x32x16_bf16 v[32:47], v[164:167], v[82:85], v[32:47]
	v_exp_f32_e32 v211, v211
	v_add_f32_e32 v135, v135, v195
	v_exp_f32_e32 v212, v212
	v_add_f32_e32 v133, v133, v196
	v_exp_f32_e32 v213, v213
	v_add_f32_e32 v135, v135, v197
	v_mfma_f32_32x32x16_bf16 v[48:63], v[168:171], v[82:85], v[48:63]
	v_exp_f32_e32 v214, v214
	v_add_f32_e32 v133, v133, v198
	v_exp_f32_e32 v215, v215
	v_add_f32_e32 v135, v135, v199
	v_exp_f32_e32 v216, v216
	v_mfma_f32_32x32x16_bf16 v[32:47], v[172:175], v[90:93], v[32:47]
	v_add_f32_e32 v133, v133, v200
	v_exp_f32_e32 v217, v217
	v_add_f32_e32 v135, v135, v201
	v_exp_f32_e32 v218, v218
	v_add_f32_e32 v133, v133, v202
	v_mfma_f32_32x32x16_bf16 v[48:63], v[176:179], v[90:93], v[48:63]
	v_exp_f32_e32 v219, v219
	v_add_f32_e32 v135, v135, v203
	v_exp_f32_e32 v220, v220
	v_add_f32_e32 v133, v133, v204
	v_exp_f32_e32 v221, v221
	v_add_f32_e32 v135, v135, v205
	v_mfma_f32_32x32x16_bf16 v[32:47], v[180:183], v[94:97], v[32:47]
	v_add_f32_e32 v133, v133, v206
	v_add_f32_e32 v135, v135, v207
	v_add_f32_e32 v133, v133, v208
	v_add_f32_e32 v135, v135, v209
	v_add_f32_e32 v133, v133, v210
	v_mfma_f32_32x32x16_bf16 v[48:63], v[184:187], v[94:97], v[48:63]
	v_add_f32_e32 v135, v135, v211
	v_add_f32_e32 v133, v133, v212
	v_add_f32_e32 v135, v135, v213
	v_add_f32_e32 v133, v133, v214
	v_add_f32_e32 v135, v135, v215
	v_mfma_f32_32x32x16_bf16 v[32:47], v[64:67], v[98:101], v[32:47]
	v_add_f32_e32 v133, v133, v216
	v_add_f32_e32 v135, v135, v217
	v_add_f32_e32 v133, v133, v218
	v_add_f32_e32 v135, v135, v219
	v_add_f32_e32 v133, v133, v220
	v_add_f32_e32 v135, v135, v221
	v_mfma_f32_32x32x16_bf16 v[48:63], v[68:71], v[98:101], v[48:63]
	v_cvt_pk_bf16_f32 v190, v190, v191
	v_cvt_pk_bf16_f32 v191, v192, v193
	v_cvt_pk_bf16_f32 v192, v194, v195
	v_cvt_pk_bf16_f32 v193, v196, v197
	v_cvt_pk_bf16_f32 v194, v198, v199
	v_mfma_f32_32x32x16_bf16 v[32:47], v[72:75], v[102:105], v[32:47]
	v_cvt_pk_bf16_f32 v195, v200, v201
	v_cvt_pk_bf16_f32 v196, v202, v203
	v_cvt_pk_bf16_f32 v197, v204, v205
	v_cvt_pk_bf16_f32 v206, v206, v207
	v_cvt_pk_bf16_f32 v207, v208, v209
	v_mfma_f32_32x32x16_bf16 v[48:63], v[76:79], v[102:105], v[48:63]
	v_cvt_pk_bf16_f32 v208, v210, v211
	v_cvt_pk_bf16_f32 v209, v212, v213
	v_cvt_pk_bf16_f32 v210, v214, v215
	v_cvt_pk_bf16_f32 v211, v216, v217
	v_cvt_pk_bf16_f32 v212, v218, v219
	v_cvt_pk_bf16_f32 v213, v220, v221
	s_waitcnt vmcnt(1) lgkmcnt(0)
	s_barrier
	ds_read_b128 v[156:159], v146 offset:16384
	ds_read_b128 v[160:163], v146 offset:24576
	ds_read_b128 v[164:167], v147 offset:16384
	ds_read_b128 v[168:171], v147 offset:24576
	ds_read_b128 v[172:175], v148 offset:16384
	ds_read_b128 v[176:179], v148 offset:24576
	ds_read_b128 v[180:183], v149 offset:16384
	ds_read_b128 v[184:187], v149 offset:24576
	ds_read_b128 v[64:67], v150 offset:16384
	ds_read_b128 v[68:71], v150 offset:24576
	ds_read_b128 v[72:75], v151 offset:16384
	ds_read_b128 v[76:79], v151 offset:24576
	v_mfma_f32_32x32x16_bf16 v[0:15], v[190:193], v[222:225], v[0:15]
	v_exp_f32_e32 v32, v32
	v_exp_f32_e32 v33, v33
	v_mfma_f32_32x32x16_bf16 v[0:15], v[194:197], v[226:229], v[0:15]
	v_exp_f32_e32 v34, v34
	v_exp_f32_e32 v35, v35
	v_mfma_f32_32x32x16_bf16 v[0:15], v[206:209], v[230:233], v[0:15]
	v_exp_f32_e32 v36, v36
	v_exp_f32_e32 v37, v37
	v_mfma_f32_32x32x16_bf16 v[0:15], v[210:213], v[234:237], v[0:15]
	v_exp_f32_e32 v38, v38
	v_exp_f32_e32 v39, v39
	v_mfma_f32_32x32x16_bf16 v[16:31], v[190:193], v[238:241], v[16:31]
	v_exp_f32_e32 v40, v40
	v_exp_f32_e32 v41, v41
	v_mfma_f32_32x32x16_bf16 v[16:31], v[194:197], v[242:245], v[16:31]
	v_exp_f32_e32 v42, v42
	v_exp_f32_e32 v43, v43
	v_mfma_f32_32x32x16_bf16 v[16:31], v[206:209], v[246:249], v[16:31]
	v_exp_f32_e32 v44, v44
	v_exp_f32_e32 v45, v45
	v_mfma_f32_32x32x16_bf16 v[16:31], v[210:213], v[140:143], v[16:31]
	v_exp_f32_e32 v46, v46
	v_exp_f32_e32 v47, v47
	s_waitcnt lgkmcnt(0)
; __device__ __forceinline__ void partialSM(f32x16& p0) {
; #pragma unroll
;   for (int r = 0; r < 16; ++r) p0[r] = __builtin_amdgcn_exp2f(p0[r]);
; }
; __device__ __forceinline__ void finishSM(f32x16& p0, f32x16& p1, float& l_reg, bf16x8& pa0, bf16x8& pa1, bf16x8& pa2, bf16x8& pa3) {
; #pragma unroll
;   for (int r = 0; r < 16; ++r) p1[r] = __builtin_amdgcn_exp2f(p1[r]);
;   float ps = 0;
; #pragma unroll
;   for (int r = 0; r < 16; ++r) ps += p0[r];
; #pragma unroll
;   for (int r = 0; r < 16; ++r) ps += p1[r];
;   l_reg += ps;
;     ...
;   PK4(p0, 0, pa0); PK4(p0, 8, pa1); PK4(p1, 0, pa2); PK4(p1, 8, pa3);
;     ...
; }
; template <int ND> __device__ __forceinline__ void qkt(f32x16& p0, f32x16& p1, const bf16* Ks, const bf16x8* qr, int r32, int hi) {
;   p0 = f32x16{}; p1 = f32x16{};
; #pragma unroll
;   for (int d0 = 0; d0 < ND; ++d0) { int cb = (d0 * 16 + hi * 8) * 2;
;     bf16x8 b0 = *reinterpret_cast<const bf16x8*>((const char*)Ks + KSWZ(r32, cb));
;     bf16x8 b1 = *reinterpret_cast<const bf16x8*>((const char*)Ks + KSWZ(32 + r32, cb));
;     p0 = __builtin_amdgcn_mfma_f32_32x32x16_bf16(b0, qr[d0], p0, 0, 0, 0);
;     p1 = __builtin_amdgcn_mfma_f32_32x32x16_bf16(b1, qr[d0], p1, 0, 0, 0); }
; }
; __device__ __forceinline__ int v_st(int k, int c) { const int kk = (k & ~0xC) | ((k & 4) << 1) | ((k & 8) >> 1); return ((kk >> 3) * 4 + (c >> 5)) * 512 + ((kk & 7) * 32 + (c & 31)) * 2; }
; __device__ __forceinline__ int v_rd_base(int lane) { return ((lane & 3) << 3) | (((lane >> 2) & 3) << 6) | (((lane >> 4) & 1) << 5) | (((lane >> 5) & 1) << 8); }
; template <int OFF> __device__ __forceinline__ s16x4 tr_read(int vb) {
;   s16x4 r; asm volatile("ds_read_b64_tr_b16 %0, %1 offset:%2" : "=&v"(r) : "v"(vb), "i"(OFF) : "memory"); return r;
; }
; template <int D0> __device__ __forceinline__ void pv_one(f32x16& od, int vb, bf16x8 pa0, bf16x8 pa1, bf16x8 pa2, bf16x8 pa3) {
;   const s16x4 l0 = tr_read<v_rd_off(D0, 0, 0)>(vb), h0 = tr_read<v_rd_off(D0, 0, 1)>(vb), l1 = tr_read<v_rd_off(D0, 1, 0)>(vb), h1 = tr_read<v_rd_off(D0, 1, 1)>(vb);
;   const s16x4 l2 = tr_read<v_rd_off(D0, 2, 0)>(vb), h2 = tr_read<v_rd_off(D0, 2, 1)>(vb), l3 = tr_read<v_rd_off(D0, 3, 0)>(vb), h3 = tr_read<v_rd_off(D0, 3, 1)>(vb);
;   asm volatile("s_waitcnt lgkmcnt(0)" ::: "memory"); SBAR();
;     ...
;   od = __builtin_amdgcn_mfma_f32_32x32x16_bf16(pa0, PK(l0, h0), od, 0, 0, 0);
	ds_read_b64_tr_b16 v[222:223], v134 offset:0
	ds_read_b64_tr_b16 v[224:225], v134 offset:2048
	ds_read_b64_tr_b16 v[226:227], v134 offset:4096
	ds_read_b64_tr_b16 v[228:229], v134 offset:6144
	ds_read_b64_tr_b16 v[230:231], v134 offset:8192
	ds_read_b64_tr_b16 v[232:233], v134 offset:10240
	ds_read_b64_tr_b16 v[234:235], v134 offset:12288
	ds_read_b64_tr_b16 v[236:237], v134 offset:14336
	ds_read_b64_tr_b16 v[238:239], v134 offset:512
	ds_read_b64_tr_b16 v[240:241], v134 offset:2560
	ds_read_b64_tr_b16 v[242:243], v134 offset:4608
	ds_read_b64_tr_b16 v[244:245], v134 offset:6656
	ds_read_b64_tr_b16 v[246:247], v134 offset:8704
	ds_read_b64_tr_b16 v[248:249], v134 offset:10752
	ds_read_b64_tr_b16 v[140:141], v134 offset:12800
	ds_read_b64_tr_b16 v[142:143], v134 offset:14848
	v_mfma_f32_32x32x16_bf16 v[190:205], v[156:159], v[86:89], 0
	v_exp_f32_e32 v48, v48
	v_add_f32_e32 v133, v133, v32
	v_exp_f32_e32 v49, v49
	v_add_f32_e32 v135, v135, v33
	v_exp_f32_e32 v50, v50
	v_mfma_f32_32x32x16_bf16 v[206:221], v[160:163], v[86:89], 0
	v_add_f32_e32 v133, v133, v34
	v_exp_f32_e32 v51, v51
	v_add_f32_e32 v135, v135, v35
	v_exp_f32_e32 v52, v52
	v_add_f32_e32 v133, v133, v36
	v_mfma_f32_32x32x16_bf16 v[190:205], v[164:167], v[82:85], v[190:205]
	v_exp_f32_e32 v53, v53
	v_add_f32_e32 v135, v135, v37
	v_exp_f32_e32 v54, v54
	v_add_f32_e32 v133, v133, v38
	v_exp_f32_e32 v55, v55
	v_add_f32_e32 v135, v135, v39
	v_mfma_f32_32x32x16_bf16 v[206:221], v[168:171], v[82:85], v[206:221]
	v_exp_f32_e32 v56, v56
	v_add_f32_e32 v133, v133, v40
	v_exp_f32_e32 v57, v57
	v_add_f32_e32 v135, v135, v41
	v_exp_f32_e32 v58, v58
	v_mfma_f32_32x32x16_bf16 v[190:205], v[172:175], v[90:93], v[190:205]
	v_add_f32_e32 v133, v133, v42
	v_exp_f32_e32 v59, v59
	v_add_f32_e32 v135, v135, v43
	v_exp_f32_e32 v60, v60
	v_add_f32_e32 v133, v133, v44
	v_mfma_f32_32x32x16_bf16 v[206:221], v[176:179], v[90:93], v[206:221]
	v_exp_f32_e32 v61, v61
	v_add_f32_e32 v135, v135, v45
	v_exp_f32_e32 v62, v62
	v_add_f32_e32 v133, v133, v46
	v_exp_f32_e32 v63, v63
	v_add_f32_e32 v135, v135, v47
	v_mfma_f32_32x32x16_bf16 v[190:205], v[180:183], v[94:97], v[190:205]
	v_add_f32_e32 v133, v133, v48
	v_add_f32_e32 v135, v135, v49
	v_add_f32_e32 v133, v133, v50
	v_add_f32_e32 v135, v135, v51
	v_add_f32_e32 v133, v133, v52
	v_mfma_f32_32x32x16_bf16 v[206:221], v[184:187], v[94:97], v[206:221]
	v_add_f32_e32 v135, v135, v53
	v_add_f32_e32 v133, v133, v54
	v_add_f32_e32 v135, v135, v55
	v_add_f32_e32 v133, v133, v56
	v_add_f32_e32 v135, v135, v57
	v_mfma_f32_32x32x16_bf16 v[190:205], v[64:67], v[98:101], v[190:205]
	v_add_f32_e32 v133, v133, v58
	v_add_f32_e32 v135, v135, v59
	v_add_f32_e32 v133, v133, v60
	v_add_f32_e32 v135, v135, v61
	v_add_f32_e32 v133, v133, v62
	v_add_f32_e32 v135, v135, v63
	v_mfma_f32_32x32x16_bf16 v[206:221], v[68:71], v[98:101], v[206:221]
	v_cvt_pk_bf16_f32 v32, v32, v33
	v_cvt_pk_bf16_f32 v33, v34, v35
	v_cvt_pk_bf16_f32 v34, v36, v37
	v_cvt_pk_bf16_f32 v35, v38, v39
	v_cvt_pk_bf16_f32 v36, v40, v41
	v_mfma_f32_32x32x16_bf16 v[190:205], v[72:75], v[102:105], v[190:205]
	v_cvt_pk_bf16_f32 v37, v42, v43
	v_cvt_pk_bf16_f32 v38, v44, v45
	v_cvt_pk_bf16_f32 v39, v46, v47
	v_cvt_pk_bf16_f32 v48, v48, v49
	v_cvt_pk_bf16_f32 v49, v50, v51
	v_mfma_f32_32x32x16_bf16 v[206:221], v[76:79], v[102:105], v[206:221]
	v_cvt_pk_bf16_f32 v50, v52, v53
	v_cvt_pk_bf16_f32 v51, v54, v55
	v_cvt_pk_bf16_f32 v52, v56, v57
	v_cvt_pk_bf16_f32 v53, v58, v59
	v_cvt_pk_bf16_f32 v54, v60, v61
	v_cvt_pk_bf16_f32 v55, v62, v63
	s_waitcnt vmcnt(0) lgkmcnt(0)
	s_barrier
	s_nop 7
	s_nop 3
	v_mfma_f32_32x32x16_bf16 v[0:15], v[32:35], v[222:225], v[0:15]
	v_exp_f32_e32 v190, v190
	v_exp_f32_e32 v191, v191
	v_mfma_f32_32x32x16_bf16 v[0:15], v[36:39], v[226:229], v[0:15]
	v_exp_f32_e32 v192, v192
	v_exp_f32_e32 v193, v193
	v_mfma_f32_32x32x16_bf16 v[0:15], v[48:51], v[230:233], v[0:15]
	v_exp_f32_e32 v194, v194
	v_exp_f32_e32 v195, v195
	v_mfma_f32_32x32x16_bf16 v[0:15], v[52:55], v[234:237], v[0:15]
	v_exp_f32_e32 v196, v196
	v_exp_f32_e32 v197, v197
	v_mfma_f32_32x32x16_bf16 v[16:31], v[32:35], v[238:241], v[16:31]
	v_exp_f32_e32 v198, v198
	v_exp_f32_e32 v199, v199
	v_mfma_f32_32x32x16_bf16 v[16:31], v[36:39], v[242:245], v[16:31]
	v_exp_f32_e32 v200, v200
	v_exp_f32_e32 v201, v201
	v_mfma_f32_32x32x16_bf16 v[16:31], v[48:51], v[246:249], v[16:31]
	v_exp_f32_e32 v202, v202
	v_exp_f32_e32 v203, v203
	v_mfma_f32_32x32x16_bf16 v[16:31], v[52:55], v[140:143], v[16:31]
	v_exp_f32_e32 v204, v204
	v_exp_f32_e32 v205, v205
	s_waitcnt lgkmcnt(0)
; __device__ __forceinline__ void finishSM(f32x16& p0, f32x16& p1, float& l_reg, bf16x8& pa0, bf16x8& pa1, bf16x8& pa2, bf16x8& pa3) {
; #pragma unroll
;   for (int r = 0; r < 16; ++r) p1[r] = __builtin_amdgcn_exp2f(p1[r]);
;   float ps = 0;
; #pragma unroll
;   for (int r = 0; r < 16; ++r) ps += p0[r];
; #pragma unroll
;   for (int r = 0; r < 16; ++r) ps += p1[r];
;   l_reg += ps;
;     ...
;   PK4(p0, 0, pa0); PK4(p0, 8, pa1); PK4(p1, 0, pa2); PK4(p1, 8, pa3);
;     ...
; }
; template <int ND> __device__ __forceinline__ void qkt(f32x16& p0, f32x16& p1, const bf16* Ks, const bf16x8* qr, int r32, int hi) {
;   p0 = f32x16{}; p1 = f32x16{};
; #pragma unroll
;   for (int d0 = 0; d0 < ND; ++d0) { int cb = (d0 * 16 + hi * 8) * 2;
;     bf16x8 b0 = *reinterpret_cast<const bf16x8*>((const char*)Ks + KSWZ(r32, cb));
;     bf16x8 b1 = *reinterpret_cast<const bf16x8*>((const char*)Ks + KSWZ(32 + r32, cb));
;     p0 = __builtin_amdgcn_mfma_f32_32x32x16_bf16(b0, qr[d0], p0, 0, 0, 0);
;     p1 = __builtin_amdgcn_mfma_f32_32x32x16_bf16(b1, qr[d0], p1, 0, 0, 0); }
; }
; __device__ __forceinline__ int v_st(int k, int c) { const int kk = (k & ~0xC) | ((k & 4) << 1) | ((k & 8) >> 1); return ((kk >> 3) * 4 + (c >> 5)) * 512 + ((kk & 7) * 32 + (c & 31)) * 2; }
; __device__ __forceinline__ int v_rd_base(int lane) { return ((lane & 3) << 3) | (((lane >> 2) & 3) << 6) | (((lane >> 4) & 1) << 5) | (((lane >> 5) & 1) << 8); }
; template <int OFF> __device__ __forceinline__ s16x4 tr_read(int vb) {
;   s16x4 r; asm volatile("ds_read_b64_tr_b16 %0, %1 offset:%2" : "=&v"(r) : "v"(vb), "i"(OFF) : "memory"); return r;
; }
; template <bool SHIFT> __device__ __forceinline__ void attn_dense_body(const bf16* __restrict__ Qb, const bf16* __restrict__ Kh, const bf16* __restrict__ Vh, bf16* __restrict__ Ob, int seq, char* lds, LAS unsigned char* ldsl, float negB, const float* __restrict__ gq, int qpos0) {
;     ...
;   finishSM(pB0, pB1, l_reg, pa0, pa1, pa2, pa3); SBAR();
;   pv_d0(o, vb0 + bv * (int)SHM_V, pa0, pa1, pa2, pa3);
;     ...
;   { auto rr = __builtin_amdgcn_permlane32_swap(__float_as_uint(l_reg), __float_as_uint(l_reg), false, false); l_reg = __uint_as_float(rr[0]) + __uint_as_float(rr[1]); }
;   if (hi == 0) li_l[r32] = l_reg; asm volatile("s_waitcnt lgkmcnt(0)" ::: "memory");
;   float rli[16];
; #pragma unroll
;   for (int r = 0; r < 16; ++r) rli[r] = __builtin_amdgcn_rcpf(li_l[crow(r, hi)]);
	ds_read_b64_tr_b16 v[222:223], v134 offset:16384
	ds_read_b64_tr_b16 v[224:225], v134 offset:18432
	ds_read_b64_tr_b16 v[226:227], v134 offset:20480
	ds_read_b64_tr_b16 v[228:229], v134 offset:22528
	ds_read_b64_tr_b16 v[230:231], v134 offset:24576
	ds_read_b64_tr_b16 v[232:233], v134 offset:26624
	ds_read_b64_tr_b16 v[234:235], v134 offset:28672
	ds_read_b64_tr_b16 v[236:237], v134 offset:30720
	ds_read_b64_tr_b16 v[238:239], v134 offset:16896
	ds_read_b64_tr_b16 v[240:241], v134 offset:18944
	ds_read_b64_tr_b16 v[242:243], v134 offset:20992
	ds_read_b64_tr_b16 v[244:245], v134 offset:23040
	ds_read_b64_tr_b16 v[246:247], v134 offset:25088
	ds_read_b64_tr_b16 v[248:249], v134 offset:27136
	ds_read_b64_tr_b16 v[140:141], v134 offset:29184
	ds_read_b64_tr_b16 v[142:143], v134 offset:31232
	s_nop 3
	v_exp_f32_e32 v206, v206
	v_add_f32_e32 v133, v133, v190
	v_exp_f32_e32 v207, v207
	v_add_f32_e32 v135, v135, v191
	v_exp_f32_e32 v208, v208
	v_add_f32_e32 v133, v133, v192
	v_exp_f32_e32 v209, v209
	v_add_f32_e32 v135, v135, v193
	v_exp_f32_e32 v210, v210
	v_add_f32_e32 v133, v133, v194
	v_exp_f32_e32 v211, v211
	v_add_f32_e32 v135, v135, v195
	v_exp_f32_e32 v212, v212
	v_add_f32_e32 v133, v133, v196
	v_exp_f32_e32 v213, v213
	v_add_f32_e32 v135, v135, v197
	v_exp_f32_e32 v214, v214
	v_add_f32_e32 v133, v133, v198
	v_exp_f32_e32 v215, v215
	v_add_f32_e32 v135, v135, v199
	v_exp_f32_e32 v216, v216
	v_add_f32_e32 v133, v133, v200
	v_exp_f32_e32 v217, v217
	v_add_f32_e32 v135, v135, v201
	v_exp_f32_e32 v218, v218
	v_add_f32_e32 v133, v133, v202
	v_exp_f32_e32 v219, v219
	v_add_f32_e32 v135, v135, v203
	v_exp_f32_e32 v220, v220
	v_add_f32_e32 v133, v133, v204
	v_exp_f32_e32 v221, v221
	v_add_f32_e32 v135, v135, v205
	v_add_f32_e32 v133, v133, v206
	v_add_f32_e32 v135, v135, v207
	v_add_f32_e32 v133, v133, v208
	v_add_f32_e32 v135, v135, v209
	v_add_f32_e32 v133, v133, v210
	v_add_f32_e32 v135, v135, v211
	v_add_f32_e32 v133, v133, v212
	v_add_f32_e32 v135, v135, v213
	v_add_f32_e32 v133, v133, v214
	v_add_f32_e32 v135, v135, v215
	v_add_f32_e32 v133, v133, v216
	v_add_f32_e32 v135, v135, v217
	v_add_f32_e32 v133, v133, v218
	v_add_f32_e32 v135, v135, v219
	v_add_f32_e32 v133, v133, v220
	v_add_f32_e32 v135, v135, v221
	v_cvt_pk_bf16_f32 v190, v190, v191
	v_cvt_pk_bf16_f32 v191, v192, v193
	v_cvt_pk_bf16_f32 v192, v194, v195
	v_cvt_pk_bf16_f32 v193, v196, v197
	v_cvt_pk_bf16_f32 v194, v198, v199
	v_cvt_pk_bf16_f32 v195, v200, v201
	v_cvt_pk_bf16_f32 v196, v202, v203
	v_cvt_pk_bf16_f32 v197, v204, v205
	v_cvt_pk_bf16_f32 v206, v206, v207
	v_cvt_pk_bf16_f32 v207, v208, v209
	v_cvt_pk_bf16_f32 v208, v210, v211
	v_cvt_pk_bf16_f32 v209, v212, v213
	v_cvt_pk_bf16_f32 v210, v214, v215
	v_cvt_pk_bf16_f32 v211, v216, v217
	v_cvt_pk_bf16_f32 v212, v218, v219
	v_cvt_pk_bf16_f32 v213, v220, v221
	s_waitcnt lgkmcnt(0)
	s_nop 7
	s_nop 3
	v_mfma_f32_32x32x16_bf16 v[0:15], v[190:193], v[222:225], v[0:15]
	v_mfma_f32_32x32x16_bf16 v[0:15], v[194:197], v[226:229], v[0:15]
	v_mfma_f32_32x32x16_bf16 v[0:15], v[206:209], v[230:233], v[0:15]
	v_mfma_f32_32x32x16_bf16 v[0:15], v[210:213], v[234:237], v[0:15]
	v_mfma_f32_32x32x16_bf16 v[16:31], v[190:193], v[238:241], v[16:31]
	v_mfma_f32_32x32x16_bf16 v[16:31], v[194:197], v[242:245], v[16:31]
	v_mfma_f32_32x32x16_bf16 v[16:31], v[206:209], v[246:249], v[16:31]
	v_mfma_f32_32x32x16_bf16 v[16:31], v[210:213], v[140:143], v[16:31]
	s_setprio 0
	v_add_f32_e32 v32, v133, v135
	s_nop 0
	v_mov_b32_e32 v33, v32
	s_nop 1
	v_permlane32_swap_b32_e32 v32, v33
	s_and_saveexec_b64 s[4:5], s[6:7]
	v_add_f32_e32 v32, v32, v33
	ds_write_b32 v153, v32
	s_or_b64 exec, exec, s[4:5]
	s_waitcnt lgkmcnt(0)
	v_add_u32_e32 v40, v113, v117
	ds_read_b128 v[32:35], v40
	ds_read_b128 v[36:39], v40 offset:32
	s_waitcnt lgkmcnt(1)
	v_rcp_f32_e32 v41, v32
	v_rcp_f32_e32 v42, v33
	v_rcp_f32_e32 v43, v34
	v_rcp_f32_e32 v44, v35
	ds_read_b128 v[32:35], v40 offset:64
	s_waitcnt lgkmcnt(1)
	v_rcp_f32_e32 v45, v36
	v_rcp_f32_e32 v46, v37
	v_rcp_f32_e32 v47, v38
	v_rcp_f32_e32 v48, v39
	ds_read_b128 v[36:39], v40 offset:96
	s_waitcnt lgkmcnt(1)
; __device__ __forceinline__ int crow(int r, int hi) { return (r & 3) + 8 * (r >> 2) + 4 * hi; }
; __device__ __forceinline__ unsigned cvtpk(float lo, float hi) { unsigned r; asm volatile("v_cvt_pk_bf16_f32 %0, %1, %2" : "=v"(r) : "v"(lo), "v"(hi)); return r; }
; template <bool SHIFT> __device__ __forceinline__ void attn_dense_body(const bf16* __restrict__ Qb, const bf16* __restrict__ Kh, const bf16* __restrict__ Vh, bf16* __restrict__ Ob, int seq, char* lds, LAS unsigned char* ldsl, float negB, const float* __restrict__ gq, int qpos0) {
;     ...
;   for (int r = 0; r < 16; ++r) rli[r] = __builtin_amdgcn_rcpf(li_l[crow(r, hi)]);
;   bf16* Ow = Ob + (long)(wid * QBLK) * LDO;
; #pragma unroll
;   for (int r = 0; r < 16; ++r) { int orow = crow(r, hi);
; #pragma unroll
;     for (int d0 = 0; d0 < 2; ++d0) Ow[(long)orow * LDO + d0 * 32 + r32] = (bf16)(cvtpk(o[d0][r] * rli[r], 0.f) & 0xffffu); }
;   __syncthreads();
	v_rcp_f32_e32 v40, v32
	v_rcp_f32_e32 v49, v33
	v_lshlrev_b32_e32 v32, 1, v116
	v_mov_b32_e32 v33, v81
	v_rcp_f32_e32 v50, v34
	v_rcp_f32_e32 v51, v35
	v_lshl_add_u64 v[32:33], s[38:39], 0, v[32:33]
	v_lshlrev_b32_e32 v34, 1, v108
	v_mov_b32_e32 v35, v81
	v_lshl_add_u64 v[32:33], v[32:33], 0, v[34:35]
	v_mul_f32_e32 v0, v0, v41
	v_lshl_add_u64 v[32:33], v[32:33], 0, v[118:119]
	v_cvt_pk_bf16_f32 v0, v0, v81
	global_store_short v[32:33], v0, off
	v_mul_f32_e32 v0, v16, v41
	v_cvt_pk_bf16_f32 v0, v0, v81
	global_store_short v[32:33], v0, off offset:64
	v_mul_f32_e32 v0, v1, v42
	v_cvt_pk_bf16_f32 v0, v0, v81
	global_store_short v[32:33], v0, off offset:2048
	v_mul_f32_e32 v0, v17, v42
	v_cvt_pk_bf16_f32 v0, v0, v81
	global_store_short v[32:33], v0, off offset:2112
	v_mul_f32_e32 v0, v2, v43
	v_cvt_pk_bf16_f32 v2, v0, v81
	v_add_co_u32_e32 v0, vcc, s47, v32
	s_waitcnt lgkmcnt(0)
	v_rcp_f32_e32 v36, v36
	v_addc_co_u32_e32 v1, vcc, 0, v33, vcc
	global_store_short v[0:1], v2, off
	v_mul_f32_e32 v2, v18, v43
	v_cvt_pk_bf16_f32 v2, v2, v81
	global_store_short v[0:1], v2, off offset:64
	v_mul_f32_e32 v2, v3, v44
	v_cvt_pk_bf16_f32 v2, v2, v81
	global_store_short v[0:1], v2, off offset:2048
	v_mul_f32_e32 v2, v19, v44
	v_cvt_pk_bf16_f32 v2, v2, v81
	global_store_short v[0:1], v2, off offset:2112
	v_mul_f32_e32 v0, v4, v45
	v_cvt_pk_bf16_f32 v4, v0, v81
	v_add_co_u32_e32 v0, vcc, s41, v32
	v_rcp_f32_e32 v37, v37
	s_nop 0
	v_addc_co_u32_e32 v1, vcc, 0, v33, vcc
	v_add_co_u32_e32 v2, vcc, s48, v32
	v_rcp_f32_e32 v38, v38
	s_nop 0
	v_addc_co_u32_e32 v3, vcc, 0, v33, vcc
	global_store_short v[2:3], v4, off offset:-4096
	v_mul_f32_e32 v4, v20, v45
	v_cvt_pk_bf16_f32 v4, v4, v81
	global_store_short v[0:1], v4, off offset:64
	v_mul_f32_e32 v4, v5, v46
	v_cvt_pk_bf16_f32 v4, v4, v81
	global_store_short v[0:1], v4, off offset:2048
	v_mul_f32_e32 v4, v21, v46
	v_cvt_pk_bf16_f32 v4, v4, v81
	global_store_short v[0:1], v4, off offset:2112
	v_mul_f32_e32 v0, v6, v47
	v_cvt_pk_bf16_f32 v0, v0, v81
	global_store_short v[2:3], v0, off
	v_mul_f32_e32 v0, v22, v47
	v_cvt_pk_bf16_f32 v0, v0, v81
	global_store_short v[2:3], v0, off offset:64
	v_mul_f32_e32 v0, v7, v48
	v_cvt_pk_bf16_f32 v0, v0, v81
	global_store_short v[2:3], v0, off offset:2048
	v_mul_f32_e32 v0, v23, v48
	v_cvt_pk_bf16_f32 v0, v0, v81
	global_store_short v[2:3], v0, off offset:2112
	v_mul_f32_e32 v0, v8, v40
	v_cvt_pk_bf16_f32 v4, v0, v81
	v_add_co_u32_e32 v0, vcc, s49, v32
	v_rcp_f32_e32 v39, v39
	s_nop 0
	v_addc_co_u32_e32 v1, vcc, 0, v33, vcc
	v_add_co_u32_e32 v2, vcc, s54, v32
	s_nop 1
	v_addc_co_u32_e32 v3, vcc, 0, v33, vcc
	global_store_short v[2:3], v4, off offset:-4096
	v_mul_f32_e32 v4, v24, v40
	v_cvt_pk_bf16_f32 v4, v4, v81
	global_store_short v[0:1], v4, off offset:64
	v_mul_f32_e32 v4, v9, v49
	v_cvt_pk_bf16_f32 v4, v4, v81
	global_store_short v[0:1], v4, off offset:2048
	v_mul_f32_e32 v4, v25, v49
	v_cvt_pk_bf16_f32 v4, v4, v81
	global_store_short v[0:1], v4, off offset:2112
	v_mul_f32_e32 v0, v10, v50
	v_cvt_pk_bf16_f32 v0, v0, v81
	global_store_short v[2:3], v0, off
	v_mul_f32_e32 v0, v26, v50
	v_cvt_pk_bf16_f32 v0, v0, v81
	global_store_short v[2:3], v0, off offset:64
	v_mul_f32_e32 v0, v11, v51
	v_cvt_pk_bf16_f32 v0, v0, v81
	global_store_short v[2:3], v0, off offset:2048
	v_mul_f32_e32 v0, v27, v51
	v_cvt_pk_bf16_f32 v0, v0, v81
	global_store_short v[2:3], v0, off offset:2112
	v_mul_f32_e32 v0, v12, v36
	v_cvt_pk_bf16_f32 v4, v0, v81
	v_add_co_u32_e32 v0, vcc, s45, v32
	s_nop 1
	v_addc_co_u32_e32 v1, vcc, 0, v33, vcc
	v_add_co_u32_e32 v2, vcc, s55, v32
	s_nop 1
	v_addc_co_u32_e32 v3, vcc, 0, v33, vcc
	global_store_short v[2:3], v4, off offset:-4096
	v_mul_f32_e32 v4, v28, v36
	v_cvt_pk_bf16_f32 v4, v4, v81
	global_store_short v[0:1], v4, off offset:64
	v_mul_f32_e32 v4, v13, v37
	v_cvt_pk_bf16_f32 v4, v4, v81
	global_store_short v[0:1], v4, off offset:2048
	v_mul_f32_e32 v4, v29, v37
	v_cvt_pk_bf16_f32 v4, v4, v81
	global_store_short v[0:1], v4, off offset:2112
	v_mul_f32_e32 v0, v14, v38
	v_cvt_pk_bf16_f32 v0, v0, v81
	global_store_short v[2:3], v0, off
	v_mul_f32_e32 v0, v30, v38
	v_cvt_pk_bf16_f32 v0, v0, v81
	global_store_short v[2:3], v0, off offset:64
	v_mul_f32_e32 v0, v15, v39
	v_cvt_pk_bf16_f32 v0, v0, v81
	global_store_short v[2:3], v0, off offset:2048
	v_mul_f32_e32 v0, v31, v39
	v_cvt_pk_bf16_f32 v0, v0, v81
	global_store_short v[2:3], v0, off offset:2112
	s_barrier
	s_branch .LBB0_1590
